# v089 + LoRA weights stored in MFMA-fragment order (contiguous B-fragment loads) + P10 expert scale loads hoisted; placement matched to v089
# speedup vs baseline: 1.0140x; 1.0035x over previous
; __device__ __forceinline__ bf16 f2bf(float f) { return (bf16)(pg8::cvt_pk_bf16(f, 0.f) & 0xffffu); }
; __global__ void __launch_bounds__(NT, 2) mk_fwd(Args args) {
;     ...
;             const float* w2 = args.in[13]; const float* a2 = args.in[15]; const float* g2 = args.in[16]; const float* keys = args.in[25];
;             for (int i = gtid; i < 1024 * 64; i += NGT) { const int n = i >> 6, k = i & 63; W2T[i] = f2bf(w2[k * 1024 + n]); A2T[i] = f2bf(a2[k * 1024 + n]); }
.LBB0_62:
	v_and_b32_e32 v12, 0xf807, v7
	v_and_b32_e32 v13, 56, v7
	v_lshl_or_b32 v12, v13, 5, v12
	v_lshrrev_b32_e32 v13, 3, v7
	v_and_b32_e32 v13, 0xf8, v13
	v_or_b32_e32 v12, v12, v13
	v_sub_u32_e32 v12, v12, v7
	v_lshlrev_b32_e32 v12, 1, v12
	v_ashrrev_i32_e32 v13, 31, v12
	v_lshl_add_u64 v[14:15], v[0:1], 0, v[12:13]
	v_ashrrev_i32_e32 v8, 6, v7
	v_and_b32_e32 v9, 0xfc00, v3
	v_add_u32_e32 v8, v9, v8
	v_ashrrev_i32_e32 v9, 31, v8
	v_lshlrev_b64 v[8:9], 2, v[8:9]
	v_lshl_add_u64 v[10:11], s[62:63], 0, v[8:9]
	v_lshl_add_u64 v[8:9], s[66:67], 0, v[8:9]
	global_load_dword v10, v[10:11], off
	s_nop 0
	global_load_dword v11, v[8:9], off
	v_add_co_u32_e32 v8, vcc, 0x20000, v0
	v_add_u32_e32 v7, s20, v7
	s_nop 0
	v_addc_co_u32_e32 v9, vcc, 0, v1, vcc
	v_lshl_add_u64 v[16:17], v[8:9], 0, v[12:13]
	v_cmp_lt_i32_e32 vcc, s17, v7
	v_add_u32_e32 v3, s3, v3
	s_or_b64 s[30:31], vcc, s[30:31]
	s_waitcnt vmcnt(1)
	v_cvt_pk_bf16_f32 v10, v10, v6
	s_waitcnt vmcnt(0)
	v_cvt_pk_bf16_f32 v11, v11, v6
	global_store_short v[14:15], v10, off
	global_store_short v[16:17], v11, off
	v_lshl_add_u64 v[0:1], v[0:1], 0, s[28:29]
	s_andn2_b64 exec, exec, s[30:31]
	s_cbranch_execnz .LBB0_62

; __device__ __forceinline__ bf16 f2bf(float f) { return (bf16)(pg8::cvt_pk_bf16(f, 0.f) & 0xffffu); }
; __global__ void __launch_bounds__(NT, 2) mk_fwd(Args args) {
;     ...
;             for (int i = gtid; i < 1024 * 160; i += NGT) { const int n = i / 160, k = i % 160; G2T[i] = f2bf(g2[k * 1024 + n]); }
.LBB0_65:
	v_mul_hi_i32 v3, v2, s17
	v_lshrrev_b32_e32 v6, 31, v3
	v_ashrrev_i32_e32 v3, 6, v3
	v_add_u32_e32 v3, v3, v6
	v_mul_u32_u24_e32 v12, 0xa0, v3
	v_sub_u32_e32 v12, v2, v12
	v_lshrrev_b32_e32 v13, 5, v3
	v_mul_u32_u24_e32 v13, 0x1400, v13
	v_lshrrev_b32_e32 v14, 4, v12
	v_lshl_add_u32 v13, v14, 9, v13
	v_bfe_u32 v14, v12, 3, 1
	v_lshl_add_u32 v13, v14, 8, v13
	v_and_b32_e32 v14, 31, v3
	v_lshl_add_u32 v13, v14, 3, v13
	v_and_b32_e32 v14, 7, v12
	v_add_lshl_u32 v13, v13, v14, 1
	v_mad_u64_u32 v[6:7], s[38:39], v3, s33, v[0:1]
	v_ashrrev_i32_e32 v7, 31, v6
	v_lshl_add_u64 v[6:7], v[6:7], 2, s[4:5]
	v_ashrrev_i32_e32 v3, 31, v2
	global_load_dword v8, v[6:7], off
	v_lshl_add_u64 v[6:7], v[2:3], 1, s[28:29]
	v_add_u32_e32 v2, s20, v2
	v_cmp_lt_i32_e32 vcc, s34, v2
	v_add_u32_e32 v0, s3, v0
	s_or_b64 s[30:31], vcc, s[30:31]
	s_waitcnt vmcnt(0)
	v_cvt_pk_bf16_f32 v3, v8, v1
	global_store_short v13, v3, s[28:29]
	s_andn2_b64 exec, exec, s[30:31]
	s_cbranch_execnz .LBB0_65

; __global__ void __launch_bounds__(NT, 2) mk_fwd(Args args) {
;     ...
;                 const int c0 = wave * 128;
;                 const float* w0p = args.in[12]; const float* a0p = args.in[14]; const float* kkw = args.in[17]; const float* kaw = args.in[18];
;     ...
; #pragma unroll 1
;                 for (int mt = 0; mt < 2; ++mt) {
;                     __syncthreads();
; #pragma unroll 6
;                     for (int op = tid; op < 3 * 32 * 128; op += NT) {
;                         const int which = op >> 12, tl = (op >> 7) & 31, c8 = (op & 127) * 8; const int t = t0 + mt * 32 + tl; const bool first = (t & (SEQ - 1)) == 0;
;                         const bf16* cp = P + (size_t)t * NINP + 2048 + which * 1024 + c8;
;                         const u32x4 cu = *(const u32x4*)cp; u32x4 pr = (u32x4){0u, 0u, 0u, 0u}; if (!first) pr = *(const u32x4*)(cp - NINP);
;                         const f32x4 m0 = *(const f32x4*)(mu + which * 1024 + c8), m1 = *(const f32x4*)(mu + which * 1024 + c8 + 4);
;                         u32x4 o;
;                         { float a = bf_lo(cu.x), b = bf_hi(cu.x); a += (bf_lo(pr.x) - a) * m0.x; b += (bf_hi(pr.x) - b) * m0.y; o.x = pk2(a, b); }
;                         { float a = bf_lo(cu.y), b = bf_hi(cu.y); a += (bf_lo(pr.y) - a) * m0.z; b += (bf_hi(pr.y) - b) * m0.w; o.y = pk2(a, b); }
;                         { float a = bf_lo(cu.z), b = bf_hi(cu.z); a += (bf_lo(pr.z) - a) * m1.x; b += (bf_hi(pr.z) - b) * m1.y; o.z = pk2(a, b); }
;                         { float a = bf_lo(cu.w), b = bf_hi(cu.w); a += (bf_lo(pr.w) - a) * m1.z; b += (bf_hi(pr.w) - b) * m1.w; o.w = pk2(a, b); }
;                         if (which == 0) *(u32x4*)(RR + (size_t)t * 1024 + c8) = o;
;                         else if (which == 2) *(u32x4*)(VV + (size_t)t * 1024 + c8) = o;
;                         else *(u32x4*)(Ks + tl * 1032 + c8) = o;
;                     }
;                     __syncthreads();
;                     f32x16 acc[4];
;                     RW_ZERO(); RW_MM(W2T, 64, 0, 4);
; #pragma unroll
;                     for (int nt = 0; nt < 4; ++nt) { const int col = c0 + nt * 32 + (lane & 31); const float w0v = w0p[col];
; #pragma unroll
;                         for (int r = 0; r < 16; ++r) { const int t = t0 + mt * 32 + (r & 3) + 8 * (r >> 2) + 4 * (lane >> 5);
;                             const float sg = sigmoid1(w0v + acc[nt][r]);
.LBB0_300:
	s_cmp_lt_i32 s94, 4
	s_cselect_b64 s[6:7], -1, 0
	s_add_u32 s96, s92, 0x19a00000
	s_addc_u32 s97, s93, 0
	s_add_u32 s30, s92, 0x1ba00000
	s_addc_u32 s31, s93, 0
	s_add_u32 s34, s92, 0x1da00000
	s_addc_u32 s35, s93, 0
	s_add_u32 s24, s92, 0x1fa00000
	s_addc_u32 s25, s93, 0
	s_add_u32 s26, s90, 0x4000000
	s_addc_u32 s27, s91, 0
	s_add_u32 s28, s90, 0x6000000
	s_addc_u32 s29, s91, 0
	s_and_b64 s[40:41], s[6:7], s[0:1]
	s_cmpk_lt_i32 s2, 0x100
	s_cselect_b64 s[38:39], -1, 0
	s_and_b64 s[0:1], s[40:41], s[38:39]
	s_andn2_b64 vcc, exec, s[0:1]
	s_cbranch_vccnz .LBB0_389
	v_writelane_b32 v249, s68, 31
	s_lshl_b32 s3, s85, 7
	v_and_b32_e32 v129, 31, v168
	v_writelane_b32 v249, s69, 32
	v_or_b32_e32 v64, s3, v129
	v_lshrrev_b32_e32 v133, 3, v168
	v_lshrrev_b32_e32 v0, 1, v168
	v_ashrrev_i32_e32 v65, 31, v64
	v_readlane_b32 s4, v249, 8
	v_and_b32_e32 v5, 16, v0
	v_and_b32_e32 v131, 4, v133
	v_lshlrev_b64 v[0:1], 2, v[64:65]
	v_readlane_b32 s6, v249, 10
	v_readlane_b32 s7, v249, 11
	v_readlane_b32 s8, v249, 12
	v_readlane_b32 s9, v249, 13
	v_or_b32_e32 v72, 0x60, v64
	v_lshl_add_u64 v[74:75], s[60:61], 0, v[0:1]
	v_lshl_add_u64 v[76:77], s[90:91], 0, v[0:1]
	v_lshl_add_u64 v[78:79], s[64:65], 0, v[0:1]
	v_lshl_add_u64 v[80:81], s[6:7], 0, v[0:1]
	v_lshl_add_u64 v[82:83], s[8:9], 0, v[0:1]
	v_mul_u32_u24_e32 v1, 0x408, v131
	v_ashrrev_i32_e32 v73, 31, v72
	v_lshlrev_b32_e32 v0, 1, v64
	v_lshlrev_b32_e32 v1, 1, v1
	v_or_b32_e32 v70, 64, v64
	v_add3_u32 v171, 0, v0, v1
	v_lshlrev_b64 v[0:1], 7, v[72:73]
	v_ashrrev_i32_e32 v71, 31, v70
	v_or_b32_e32 v0, v0, v5
	v_or_b32_e32 v68, 32, v64
	v_lshl_add_u64 v[100:101], s[92:93], 0, v[0:1]
	v_lshlrev_b64 v[0:1], 7, v[70:71]
	v_ashrrev_i32_e32 v69, 31, v68
	v_or_b32_e32 v0, v0, v5
	v_lshl_add_u64 v[102:103], s[92:93], 0, v[0:1]
	v_lshlrev_b64 v[0:1], 7, v[68:69]
	s_mov_b64 s[0:1], 0x80
	v_or_b32_e32 v0, v0, v5
	v_lshl_add_u64 v[84:85], v[76:77], 0, s[0:1]
	s_mov_b64 s[0:1], 0x100
	v_lshl_add_u64 v[104:105], s[92:93], 0, v[0:1]
	v_lshlrev_b64 v[0:1], 7, v[64:65]
	v_lshl_add_u64 v[86:87], v[76:77], 0, s[0:1]
	s_mov_b64 s[0:1], 0x180
	v_or_b32_e32 v0, v0, v5
	s_movk_i32 s6, 0x140
	v_lshl_add_u64 v[88:89], v[76:77], 0, s[0:1]
	v_lshl_add_u64 v[106:107], s[92:93], 0, v[0:1]
	v_mad_i64_i32 v[0:1], s[0:1], v72, s6, 0
	v_or_b32_e32 v0, v0, v5
	v_lshl_add_u64 v[108:109], s[92:93], 0, v[0:1]
	v_mad_i64_i32 v[0:1], s[0:1], v70, s6, 0
	v_or_b32_e32 v0, v0, v5
	v_lshl_add_u64 v[110:111], s[92:93], 0, v[0:1]
	v_mad_i64_i32 v[0:1], s[0:1], v68, s6, 0
	v_and_b32_e32 v2, 7, v168
	v_or_b32_e32 v0, v0, v5
	v_mul_u32_u24_e32 v3, 36, v2
	v_lshl_add_u64 v[112:113], s[92:93], 0, v[0:1]
	v_mad_i64_i32 v[0:1], s[0:1], v64, s6, 0
	v_mul_u32_u24_e32 v4, 0x250, v133
	v_add_u32_e32 v170, 0, v5
	v_lshlrev_b32_e32 v96, 1, v3
	v_mov_b32_e32 v97, 0
	v_or_b32_e32 v0, v0, v5
	s_movk_i32 s46, 0x250
	v_lshrrev_b32_e32 v135, 2, v168
	v_lshl_add_u64 v[66:67], v[64:65], 1, s[26:27]
	v_or_b32_e32 v172, 1, v131
	v_add_u32_e32 v173, 0x810, v171
	v_or_b32_e32 v174, 2, v131
	v_add_u32_e32 v175, 0x1020, v171
	v_or_b32_e32 v176, 3, v131
	v_add_u32_e32 v177, 0x1830, v171
	v_or_b32_e32 v178, 8, v131
	v_add_u32_e32 v179, 0x4080, v171
	v_or_b32_e32 v180, 9, v131
	v_add_u32_e32 v181, 0x4890, v171
	v_or_b32_e32 v182, 10, v131
	v_add_u32_e32 v183, 0x50a0, v171
	v_or_b32_e32 v184, 11, v131
	v_add_u32_e32 v185, 0x58b0, v171
	v_or_b32_e32 v186, 16, v131
	v_add_u32_e32 v187, 0x8100, v171
	v_or_b32_e32 v188, 17, v131
	v_add_u32_e32 v189, 0x8910, v171
	v_or_b32_e32 v190, 18, v131
	v_add_u32_e32 v191, 0x9120, v171
	v_or_b32_e32 v192, 19, v131
	v_add_u32_e32 v193, 0x9930, v171
	v_or_b32_e32 v194, 24, v131
	v_add_u32_e32 v195, 0xc180, v171
	v_or_b32_e32 v196, 25, v131
	v_add_u32_e32 v197, 0xc990, v171
	v_or_b32_e32 v198, 26, v131
	v_add_u32_e32 v199, 0xd1a0, v171
	v_or_b32_e32 v200, 27, v131
	v_add_u32_e32 v201, 0xd9b0, v171
	v_lshl_add_u64 v[90:91], v[68:69], 1, s[26:27]
	v_lshl_add_u64 v[92:93], v[70:71], 1, s[26:27]
	v_lshl_add_u64 v[94:95], v[72:73], 1, s[26:27]
	v_lshl_add_u64 v[98:99], s[92:93], 0, v[96:97]
	v_mad_u32_u24 v202, v2, 36, 10
	v_add3_u32 v203, v4, v96, 0
	v_lshrrev_b32_e32 v204, 7, v168
	v_lshlrev_b32_e32 v205, 3, v168
	v_add_u32_e32 v206, 0x80, v170
	v_add_u32_e32 v207, 0x100, v170
	v_lshl_add_u64 v[114:115], s[92:93], 0, v[0:1]
	s_movk_i32 s47, 0x7ff
	s_movk_i32 s60, 0x7f
	s_movk_i32 s61, 0x2c00
	s_mov_b64 s[6:7], 0x1000
	s_movk_i32 s62, 0xfff
	s_movk_i32 s63, 0x2dff
	s_mov_b32 s64, 0x280000
	s_mov_b32 s65, 0x2a0000
	s_mov_b32 s66, 0x2c0000
	v_mbcnt_hi_u32_b32 v208, -1, v169
	s_mov_b32 s67, s2
	v_readlane_b32 s5, v249, 9
	v_readlane_b32 s10, v249, 14
	v_readlane_b32 s11, v249, 15
	v_readlane_b32 s12, v249, 16
	v_readlane_b32 s13, v249, 17
	v_readlane_b32 s14, v249, 18
	v_readlane_b32 s15, v249, 19
	v_readlane_b32 s16, v249, 20
	v_readlane_b32 s17, v249, 21
	v_readlane_b32 s18, v249, 22
	v_readlane_b32 s19, v249, 23
	global_load_dword v230, v[74:75], off
	global_load_dword v231, v[74:75], off offset:128
	global_load_dword v232, v[74:75], off offset:256
	global_load_dword v233, v[74:75], off offset:384
	global_load_dword v234, v[78:79], off
	global_load_dword v235, v[78:79], off offset:128
	global_load_dword v236, v[78:79], off offset:256
	global_load_dword v237, v[78:79], off offset:384
	global_load_dword v238, v[80:81], off
	global_load_dword v239, v[80:81], off offset:128
	global_load_dword v240, v[80:81], off offset:256
	global_load_dword v241, v[80:81], off offset:384
	global_load_dword v242, v[82:83], off
	global_load_dword v243, v[82:83], off offset:128
	global_load_dword v244, v[82:83], off offset:256
	global_load_dword v245, v[82:83], off offset:384
	s_waitcnt vmcnt(0)
	v_lshlrev_b32_e32 v0, 4, v128
	v_mov_b32_e32 v1, s85
	v_lshl_add_u32 v0, v1, 14, v0
	v_mov_b32_e32 v1, 0
	v_mov_b32_e32 v3, 0
	v_lshl_add_u64 v[106:107], s[92:93], 0, v[0:1]
	v_mov_b32_e32 v2, 0x1000
	v_lshl_add_u64 v[104:105], v[106:107], 0, v[2:3]
	v_mov_b32_e32 v2, 0x2000
	v_lshl_add_u64 v[102:103], v[106:107], 0, v[2:3]
	v_mov_b32_e32 v2, 0x3000
	v_lshl_add_u64 v[100:101], v[106:107], 0, v[2:3]
	v_lshlrev_b32_e32 v0, 4, v128
	v_mov_b32_e32 v2, s85
	v_mul_u32_u24_e32 v2, 0xa000, v2
	v_add_u32_e32 v0, v0, v2
	v_lshl_add_u64 v[114:115], s[92:93], 0, v[0:1]
	v_mov_b32_e32 v2, 0x2800
	v_lshl_add_u64 v[112:113], v[114:115], 0, v[2:3]
	v_mov_b32_e32 v2, 0x5000
	v_lshl_add_u64 v[110:111], v[114:115], 0, v[2:3]
	v_mov_b32_e32 v2, 0x7800
	v_lshl_add_u64 v[108:109], v[114:115], 0, v[2:3]

; __device__ __forceinline__ float sigmoid1(float x) { return __builtin_amdgcn_rcpf(1.0f + __expf(-x)); }
; __global__ void __launch_bounds__(NT, 2) mk_fwd(Args args) {
;     ...
;                     for (int nt = 0; nt < 4; ++nt) { const int col = c0 + nt * 32 + (lane & 31); const float w0v = w0p[col];
; #pragma unroll
;                         for (int r = 0; r < 16; ++r) { const int t = t0 + mt * 32 + (r & 3) + 8 * (r >> 2) + 4 * (lane >> 5);
;                             const float sg = sigmoid1(w0v + acc[nt][r]);
;                             DEC[(size_t)t * 1024 + col] = __expf(-0.60653065971f * sg); }
.LBB0_366:
	v_lshl_add_u64 v[124:125], v[106:107], 0, s[8:9]
	v_add_co_u32_e32 v148, vcc, s64, v124
	v_lshl_add_u64 v[126:127], v[104:105], 0, s[8:9]
	s_nop 0
	v_addc_co_u32_e32 v149, vcc, 0, v125, vcc
	v_add_co_u32_e32 v152, vcc, s64, v126
	v_lshl_add_u64 v[136:137], v[102:103], 0, s[8:9]
	s_nop 0
	v_addc_co_u32_e32 v153, vcc, 0, v127, vcc
	v_add_co_u32_e32 v154, vcc, s64, v136
	v_lshl_add_u64 v[138:139], v[100:101], 0, s[8:9]
	s_nop 0
	v_addc_co_u32_e32 v155, vcc, 0, v137, vcc
	v_add_co_u32_e32 v156, vcc, s64, v138
	ds_read_b128 v[116:119], v96
	ds_read_b128 v[120:123], v96 offset:32
	v_addc_co_u32_e32 v157, vcc, 0, v139, vcc
	global_load_dwordx4 v[124:127], v[148:149], off
	global_load_dwordx4 v[136:139], v[152:153], off
	global_load_dwordx4 v[140:143], v[154:155], off
	global_load_dwordx4 v[144:147], v[156:157], off
	s_nop 0
	global_load_dwordx4 v[148:151], v[148:149], off offset:1024
	s_add_u32 s8, s8, 0x800
	s_addc_u32 s9, s9, 0
	s_cmpk_eq_i32 s8, 0x1000
	v_add_u32_e32 v96, 64, v96
	s_waitcnt vmcnt(4) lgkmcnt(1)
	v_mfma_f32_32x32x16_bf16 v[48:63], v[116:119], v[124:127], v[48:63]
	global_load_dwordx4 v[124:127], v[152:153], off offset:1024
	s_waitcnt vmcnt(4)
	v_mfma_f32_32x32x16_bf16 v[32:47], v[116:119], v[136:139], v[32:47]
	global_load_dwordx4 v[136:139], v[154:155], off offset:1024
	s_waitcnt vmcnt(4)
	v_mfma_f32_32x32x16_bf16 v[16:31], v[116:119], v[140:143], v[16:31]
	global_load_dwordx4 v[140:143], v[156:157], off offset:1024
	s_waitcnt vmcnt(4)
	v_mfma_f32_32x32x16_bf16 v[0:15], v[116:119], v[144:147], v[0:15]
	s_waitcnt vmcnt(3) lgkmcnt(0)
	v_mfma_f32_32x32x16_bf16 v[48:63], v[120:123], v[148:151], v[48:63]
	s_waitcnt vmcnt(2)
	v_mfma_f32_32x32x16_bf16 v[32:47], v[120:123], v[124:127], v[32:47]
	s_waitcnt vmcnt(1)
	v_mfma_f32_32x32x16_bf16 v[16:31], v[120:123], v[136:139], v[16:31]
	s_waitcnt vmcnt(0)
	v_mfma_f32_32x32x16_bf16 v[0:15], v[120:123], v[140:143], v[0:15]
	s_cbranch_scc0 .LBB0_366
	v_mov_b32_e32 v148, v230
	v_or_b32_e32 v96, s69, v209
	v_lshlrev_b32_e32 v96, 10, v96
	v_mov_b32_e32 v127, v97
	v_mov_b32_e32 v117, v97
	v_mov_b32_e32 v119, v97
	v_mov_b32_e32 v121, v97
	v_mov_b32_e32 v123, v97
	v_mov_b32_e32 v125, v97
	v_or_b32_e32 v126, 0x400, v96
	v_or_b32_e32 v116, 0x800, v96
	v_or_b32_e32 v118, 0xc00, v96
	v_or_b32_e32 v120, 0x2000, v96
	v_or_b32_e32 v122, 0x2400, v96
	v_or_b32_e32 v124, 0x2800, v96
	v_lshl_add_u64 v[164:165], v[96:97], 2, v[76:77]
	v_lshlrev_b64 v[162:163], 2, v[126:127]
	v_lshlrev_b64 v[160:161], 2, v[116:117]
	v_lshlrev_b64 v[158:159], 2, v[118:119]
	v_lshlrev_b64 v[156:157], 2, v[120:121]
	v_lshlrev_b64 v[154:155], 2, v[122:123]
	v_lshlrev_b64 v[152:153], 2, v[124:125]
	v_lshl_add_u64 v[126:127], v[76:77], 0, v[162:163]
	v_lshl_add_u64 v[136:137], v[76:77], 0, v[160:161]
	v_lshl_add_u64 v[138:139], v[76:77], 0, v[158:159]
	v_lshl_add_u64 v[140:141], v[76:77], 0, v[156:157]
	v_lshl_add_u64 v[142:143], v[76:77], 0, v[154:155]
	v_lshl_add_u64 v[144:145], v[76:77], 0, v[152:153]
	v_or_b32_e32 v146, 0x6400, v96
	v_mov_b32_e32 v147, v97
	v_lshlrev_b64 v[166:167], 2, v[146:147]
	v_mov_b32_e32 v149, v97
	v_or_b32_e32 v150, 0x6c00, v96
	v_mov_b32_e32 v151, v97
	s_mov_b64 s[8:9], 0
	v_add_f32_e32 v48, v148, v48
	v_add_f32_e32 v49, v148, v49
	v_mul_f32_e32 v48, 0xbfb8aa3b, v48
	v_add_f32_e32 v50, v148, v50
	v_mul_f32_e32 v49, 0xbfb8aa3b, v49
	v_exp_f32_e32 v48, v48
	v_add_f32_e32 v51, v148, v51
	v_mul_f32_e32 v50, 0xbfb8aa3b, v50
	v_exp_f32_e32 v49, v49
	v_add_f32_e32 v52, v148, v52
	v_add_f32_e32 v53, v148, v53
	v_add_f32_e32 v54, v148, v54
	v_mul_f32_e32 v51, 0xbfb8aa3b, v51
	v_exp_f32_e32 v50, v50
	v_mul_f32_e32 v52, 0xbfb8aa3b, v52
	v_mul_f32_e32 v53, 0xbfb8aa3b, v53
	v_mul_f32_e32 v54, 0xbfb8aa3b, v54
	v_exp_f32_e32 v51, v51
	v_exp_f32_e32 v52, v52
	v_exp_f32_e32 v53, v53
	v_exp_f32_e32 v54, v54
	v_add_f32_e32 v48, 1.0, v48
	v_add_f32_e32 v49, 1.0, v49
	v_rcp_f32_e32 v48, v48
	v_add_f32_e32 v50, 1.0, v50
	v_rcp_f32_e32 v49, v49
	v_add_f32_e32 v55, v148, v55
	v_add_f32_e32 v51, 1.0, v51
	v_rcp_f32_e32 v50, v50
	v_mul_f32_e32 v55, 0xbfb8aa3b, v55
	v_add_f32_e32 v52, 1.0, v52
	v_add_f32_e32 v53, 1.0, v53
	v_add_f32_e32 v54, 1.0, v54
	v_rcp_f32_e32 v51, v51
	v_exp_f32_e32 v55, v55
	v_rcp_f32_e32 v52, v52
	v_rcp_f32_e32 v53, v53
	v_rcp_f32_e32 v54, v54
	v_mul_f32_e32 v48, 0xbf1b4598, v48
	v_mul_f32_e32 v49, 0xbf1b4598, v49
	v_mul_f32_e32 v48, 0x3fb8aa3b, v48
	v_mul_f32_e32 v50, 0xbf1b4598, v50
	v_mul_f32_e32 v49, 0x3fb8aa3b, v49
	v_exp_f32_e32 v48, v48
	v_mul_f32_e32 v51, 0xbf1b4598, v51
	v_mul_f32_e32 v50, 0x3fb8aa3b, v50
	v_exp_f32_e32 v49, v49
	v_add_f32_e32 v55, 1.0, v55
	v_mul_f32_e32 v52, 0xbf1b4598, v52
	v_mul_f32_e32 v53, 0xbf1b4598, v53
	v_mul_f32_e32 v54, 0xbf1b4598, v54
	v_mul_f32_e32 v51, 0x3fb8aa3b, v51
	v_exp_f32_e32 v50, v50
	v_rcp_f32_e32 v55, v55
	v_mul_f32_e32 v52, 0x3fb8aa3b, v52
	v_mul_f32_e32 v53, 0x3fb8aa3b, v53
	v_mul_f32_e32 v54, 0x3fb8aa3b, v54
	v_exp_f32_e32 v51, v51
	v_exp_f32_e32 v52, v52
	v_exp_f32_e32 v53, v53
	v_exp_f32_e32 v54, v54
	global_store_dword v[164:165], v48, off
	global_store_dword v[126:127], v49, off
	global_store_dword v[136:137], v50, off
	global_store_dword v[138:139], v51, off
	global_store_dword v[140:141], v52, off
	global_store_dword v[142:143], v53, off
	global_store_dword v[144:145], v54, off
	v_add_f32_e32 v48, v148, v56
	v_mul_f32_e32 v48, 0xbfb8aa3b, v48
	v_exp_f32_e32 v48, v48
	v_mul_f32_e32 v55, 0xbf1b4598, v55
	v_mul_f32_e32 v55, 0x3fb8aa3b, v55
	v_exp_f32_e32 v52, v55
	v_or_b32_e32 v126, 0x2c00, v96
	v_mov_b32_e32 v127, v97
	v_add_f32_e32 v48, 1.0, v48
	v_rcp_f32_e32 v53, v48
	v_lshlrev_b64 v[48:49], 2, v[126:127]
	v_lshl_add_u64 v[50:51], v[76:77], 0, v[48:49]
; __device__ __forceinline__ float sigmoid1(float x) { return __builtin_amdgcn_rcpf(1.0f + __expf(-x)); }
; __global__ void __launch_bounds__(NT, 2) mk_fwd(Args args) {
;     ...
;                     for (int nt = 0; nt < 4; ++nt) { const int col = c0 + nt * 32 + (lane & 31); const float w0v = w0p[col];
; #pragma unroll
;                         for (int r = 0; r < 16; ++r) { const int t = t0 + mt * 32 + (r & 3) + 8 * (r >> 2) + 4 * (lane >> 5);
;                             const float sg = sigmoid1(w0v + acc[nt][r]);
;                             DEC[(size_t)t * 1024 + col] = __expf(-0.60653065971f * sg); }
;                         asm volatile("" ::: "memory"); }
	global_store_dword v[50:51], v52, off
	v_add_f32_e32 v51, v148, v57
	v_mul_f32_e32 v51, 0xbfb8aa3b, v51
	v_exp_f32_e32 v51, v51
	v_mul_f32_e32 v50, 0xbf1b4598, v53
	v_mul_f32_e32 v50, 0x3fb8aa3b, v50
	v_exp_f32_e32 v54, v50
	v_or_b32_e32 v136, 0x4000, v96
	v_mov_b32_e32 v137, v97
	v_add_f32_e32 v50, 1.0, v51
	v_rcp_f32_e32 v55, v50
	v_lshlrev_b64 v[50:51], 2, v[136:137]
	v_lshl_add_u64 v[52:53], v[76:77], 0, v[50:51]
	global_store_dword v[52:53], v54, off
	v_add_f32_e32 v53, v148, v58
	v_mul_f32_e32 v53, 0xbfb8aa3b, v53
	v_exp_f32_e32 v53, v53
	v_mul_f32_e32 v52, 0xbf1b4598, v55
	v_mul_f32_e32 v52, 0x3fb8aa3b, v52
	v_exp_f32_e32 v56, v52
	v_or_b32_e32 v138, 0x4400, v96
	v_mov_b32_e32 v139, v97
	v_add_f32_e32 v52, 1.0, v53
	v_rcp_f32_e32 v57, v52
	v_lshlrev_b64 v[52:53], 2, v[138:139]
	v_lshl_add_u64 v[54:55], v[76:77], 0, v[52:53]
	global_store_dword v[54:55], v56, off
	v_add_f32_e32 v55, v148, v59
	v_mul_f32_e32 v55, 0xbfb8aa3b, v55
	v_exp_f32_e32 v55, v55
	v_mul_f32_e32 v54, 0xbf1b4598, v57
	v_mul_f32_e32 v54, 0x3fb8aa3b, v54
	v_exp_f32_e32 v58, v54
	v_or_b32_e32 v140, 0x4800, v96
	v_mov_b32_e32 v141, v97
	v_add_f32_e32 v54, 1.0, v55
	v_rcp_f32_e32 v59, v54
	v_lshlrev_b64 v[54:55], 2, v[140:141]
	v_lshl_add_u64 v[56:57], v[76:77], 0, v[54:55]
	global_store_dword v[56:57], v58, off
	v_add_f32_e32 v57, v148, v60
	v_mul_f32_e32 v57, 0xbfb8aa3b, v57
	v_exp_f32_e32 v57, v57
	v_mul_f32_e32 v56, 0xbf1b4598, v59
	v_mul_f32_e32 v56, 0x3fb8aa3b, v56
	v_exp_f32_e32 v60, v56
	v_or_b32_e32 v142, 0x4c00, v96
	v_mov_b32_e32 v143, v97
	v_add_f32_e32 v56, 1.0, v57
	v_rcp_f32_e32 v117, v56
	v_lshlrev_b64 v[56:57], 2, v[142:143]
	v_lshl_add_u64 v[58:59], v[76:77], 0, v[56:57]
	global_store_dword v[58:59], v60, off
	v_add_f32_e32 v59, v148, v61
	v_mul_f32_e32 v59, 0xbfb8aa3b, v59
	v_exp_f32_e32 v59, v59
	v_mul_f32_e32 v58, 0xbf1b4598, v117
	v_mul_f32_e32 v58, 0x3fb8aa3b, v58
	v_exp_f32_e32 v117, v58
	v_or_b32_e32 v144, 0x6000, v96
	v_mov_b32_e32 v145, v97
	v_add_f32_e32 v58, 1.0, v59
	v_rcp_f32_e32 v119, v58
	v_lshlrev_b64 v[58:59], 2, v[144:145]
	v_lshl_add_u64 v[60:61], v[76:77], 0, v[58:59]
	global_store_dword v[60:61], v117, off
	v_add_f32_e32 v61, v148, v62
	v_mul_f32_e32 v61, 0xbfb8aa3b, v61
	v_mul_f32_e32 v60, 0xbf1b4598, v119
	v_exp_f32_e32 v61, v61
	v_mul_f32_e32 v60, 0x3fb8aa3b, v60
	v_exp_f32_e32 v62, v60
	v_add_f32_e32 v60, 1.0, v61
	v_rcp_f32_e32 v117, v60
	v_lshl_add_u64 v[60:61], v[76:77], 0, v[166:167]
	global_store_dword v[60:61], v62, off
	v_add_f32_e32 v61, v148, v63
	v_mul_f32_e32 v61, 0xbfb8aa3b, v61
	v_exp_f32_e32 v61, v61
	v_mul_f32_e32 v60, 0xbf1b4598, v117
	v_mul_f32_e32 v60, 0x3fb8aa3b, v60
	v_exp_f32_e32 v117, v60
	v_add_f32_e32 v60, 1.0, v61
	v_rcp_f32_e32 v119, v60
	v_or_b32_e32 v148, 0x6800, v96
	v_lshlrev_b64 v[60:61], 2, v[148:149]
	v_lshl_add_u64 v[62:63], v[76:77], 0, v[60:61]
	global_store_dword v[62:63], v117, off
	v_mul_f32_e32 v62, 0xbf1b4598, v119
	v_mul_f32_e32 v62, 0x3fb8aa3b, v62
	v_exp_f32_e32 v117, v62
	v_lshlrev_b64 v[62:63], 2, v[150:151]
	v_lshl_add_u64 v[212:213], v[76:77], 0, v[62:63]
	global_store_dword v[212:213], v117, off
	v_mov_b32_e32 v117, v231
	v_add_f32_e32 v32, v117, v32
	v_mul_f32_e32 v32, 0xbfb8aa3b, v32
	v_exp_f32_e32 v32, v32
	v_add_f32_e32 v33, v117, v33
	v_mul_f32_e32 v33, 0xbfb8aa3b, v33
	v_exp_f32_e32 v33, v33
	v_add_f32_e32 v32, 1.0, v32
	v_rcp_f32_e32 v32, v32
	v_add_f32_e32 v35, v117, v35
	v_add_f32_e32 v33, 1.0, v33
	v_rcp_f32_e32 v33, v33
	v_mul_f32_e32 v32, 0xbf1b4598, v32
	v_mul_f32_e32 v32, 0x3fb8aa3b, v32
	v_exp_f32_e32 v32, v32
	v_mul_f32_e32 v35, 0xbfb8aa3b, v35
	v_exp_f32_e32 v35, v35
	global_store_dword v[164:165], v32, off offset:128
	v_mul_f32_e32 v32, 0xbf1b4598, v33
	v_add_f32_e32 v33, v117, v34
	v_mul_f32_e32 v33, 0xbfb8aa3b, v33
	v_exp_f32_e32 v34, v33
	v_mul_f32_e32 v32, 0x3fb8aa3b, v32
	v_exp_f32_e32 v119, v32
	v_lshl_add_u64 v[32:33], v[84:85], 0, v[162:163]
	v_add_f32_e32 v34, 1.0, v34
	v_rcp_f32_e32 v34, v34
	global_store_dword v[32:33], v119, off
	v_lshl_add_u64 v[32:33], v[84:85], 0, v[160:161]
	v_add_f32_e32 v35, 1.0, v35
	v_mul_f32_e32 v34, 0xbf1b4598, v34
	v_mul_f32_e32 v34, 0x3fb8aa3b, v34
	v_exp_f32_e32 v34, v34
	v_rcp_f32_e32 v35, v35
	global_store_dword v[32:33], v34, off
	v_add_f32_e32 v33, v117, v36
	v_mul_f32_e32 v33, 0xbfb8aa3b, v33
	v_exp_f32_e32 v34, v33
	v_mul_f32_e32 v32, 0xbf1b4598, v35
	v_mul_f32_e32 v32, 0x3fb8aa3b, v32
	v_exp_f32_e32 v35, v32
	v_add_f32_e32 v34, 1.0, v34
	v_rcp_f32_e32 v34, v34
	v_lshl_add_u64 v[32:33], v[84:85], 0, v[158:159]
	v_add_f32_e32 v36, v117, v37
	global_store_dword v[32:33], v35, off
	v_mul_f32_e32 v34, 0xbf1b4598, v34
	v_mul_f32_e32 v34, 0x3fb8aa3b, v34
	v_exp_f32_e32 v34, v34
	v_lshl_add_u64 v[32:33], v[84:85], 0, v[156:157]
	v_mul_f32_e32 v36, 0xbfb8aa3b, v36
	v_exp_f32_e32 v36, v36
	global_store_dword v[32:33], v34, off
	v_add_f32_e32 v33, v117, v38
	v_mul_f32_e32 v33, 0xbfb8aa3b, v33
	v_exp_f32_e32 v34, v33
	v_add_f32_e32 v36, 1.0, v36
	v_rcp_f32_e32 v36, v36
	v_add_f32_e32 v34, 1.0, v34
	v_rcp_f32_e32 v34, v34
	v_mul_f32_e32 v32, 0xbf1b4598, v36
	v_mul_f32_e32 v32, 0x3fb8aa3b, v32
	v_exp_f32_e32 v35, v32
	v_mul_f32_e32 v34, 0xbf1b4598, v34
	v_mul_f32_e32 v34, 0x3fb8aa3b, v34
	v_exp_f32_e32 v34, v34
	v_lshl_add_u64 v[32:33], v[84:85], 0, v[154:155]
	v_add_f32_e32 v36, v117, v39
	global_store_dword v[32:33], v35, off
	v_lshl_add_u64 v[32:33], v[84:85], 0, v[152:153]
	v_mul_f32_e32 v36, 0xbfb8aa3b, v36
	global_store_dword v[32:33], v34, off
	v_add_f32_e32 v33, v117, v40
	v_exp_f32_e32 v36, v36
	v_mul_f32_e32 v33, 0xbfb8aa3b, v33
	v_exp_f32_e32 v34, v33
	v_add_f32_e32 v36, 1.0, v36
	v_rcp_f32_e32 v36, v36
; __device__ __forceinline__ float sigmoid1(float x) { return __builtin_amdgcn_rcpf(1.0f + __expf(-x)); }
; __global__ void __launch_bounds__(NT, 2) mk_fwd(Args args) {
;     ...
;                     for (int nt = 0; nt < 4; ++nt) { const int col = c0 + nt * 32 + (lane & 31); const float w0v = w0p[col];
; #pragma unroll
;                         for (int r = 0; r < 16; ++r) { const int t = t0 + mt * 32 + (r & 3) + 8 * (r >> 2) + 4 * (lane >> 5);
;                             const float sg = sigmoid1(w0v + acc[nt][r]);
;                             DEC[(size_t)t * 1024 + col] = __expf(-0.60653065971f * sg); }
;                         asm volatile("" ::: "memory"); }
	v_add_f32_e32 v34, 1.0, v34
	v_rcp_f32_e32 v34, v34
	v_mul_f32_e32 v32, 0xbf1b4598, v36
	v_mul_f32_e32 v32, 0x3fb8aa3b, v32
	v_mul_f32_e32 v34, 0xbf1b4598, v34
	v_exp_f32_e32 v35, v32
	v_mul_f32_e32 v34, 0x3fb8aa3b, v34
	v_exp_f32_e32 v34, v34
	v_lshl_add_u64 v[32:33], v[84:85], 0, v[48:49]
	v_add_f32_e32 v36, v117, v41
	global_store_dword v[32:33], v35, off
	v_lshl_add_u64 v[32:33], v[84:85], 0, v[50:51]
	v_mul_f32_e32 v36, 0xbfb8aa3b, v36
	global_store_dword v[32:33], v34, off
	v_add_f32_e32 v33, v117, v42
	v_exp_f32_e32 v36, v36
	v_mul_f32_e32 v33, 0xbfb8aa3b, v33
	v_exp_f32_e32 v34, v33
	v_add_f32_e32 v36, 1.0, v36
	v_rcp_f32_e32 v36, v36
	v_add_f32_e32 v34, 1.0, v34
	v_rcp_f32_e32 v34, v34
	v_mul_f32_e32 v32, 0xbf1b4598, v36
	v_mul_f32_e32 v32, 0x3fb8aa3b, v32
	v_mul_f32_e32 v34, 0xbf1b4598, v34
	v_exp_f32_e32 v35, v32
	v_add_f32_e32 v36, v117, v43
	v_mul_f32_e32 v34, 0x3fb8aa3b, v34
	v_mul_f32_e32 v36, 0xbfb8aa3b, v36
	v_exp_f32_e32 v34, v34
	v_exp_f32_e32 v36, v36
	v_lshl_add_u64 v[32:33], v[84:85], 0, v[52:53]
	global_store_dword v[32:33], v35, off
	v_lshl_add_u64 v[32:33], v[84:85], 0, v[54:55]
	global_store_dword v[32:33], v34, off
	v_add_f32_e32 v33, v117, v44
	v_add_f32_e32 v36, 1.0, v36
	v_mul_f32_e32 v33, 0xbfb8aa3b, v33
	v_rcp_f32_e32 v36, v36
	v_exp_f32_e32 v34, v33
	v_mul_f32_e32 v32, 0xbf1b4598, v36
	v_add_f32_e32 v34, 1.0, v34
	v_add_f32_e32 v36, v117, v45
	v_rcp_f32_e32 v34, v34
	v_mul_f32_e32 v36, 0xbfb8aa3b, v36
	v_exp_f32_e32 v36, v36
	v_mul_f32_e32 v32, 0x3fb8aa3b, v32
	v_mul_f32_e32 v34, 0xbf1b4598, v34
	v_exp_f32_e32 v35, v32
	v_mul_f32_e32 v34, 0x3fb8aa3b, v34
	v_add_f32_e32 v36, 1.0, v36
	v_exp_f32_e32 v34, v34
	v_rcp_f32_e32 v36, v36
	v_lshl_add_u64 v[32:33], v[84:85], 0, v[56:57]
	global_store_dword v[32:33], v35, off
	v_lshl_add_u64 v[32:33], v[84:85], 0, v[58:59]
	v_add_f32_e32 v35, v117, v46
	global_store_dword v[32:33], v34, off
	v_mul_f32_e32 v32, 0xbf1b4598, v36
	v_mul_f32_e32 v35, 0xbfb8aa3b, v35
	v_add_f32_e32 v36, v117, v47
	v_mul_f32_e32 v32, 0x3fb8aa3b, v32
	v_exp_f32_e32 v35, v35
	v_mul_f32_e32 v36, 0xbfb8aa3b, v36
	v_exp_f32_e32 v34, v32
	v_exp_f32_e32 v36, v36
	v_lshl_add_u64 v[32:33], v[84:85], 0, v[166:167]
	v_add_f32_e32 v35, 1.0, v35
	v_rcp_f32_e32 v35, v35
	global_store_dword v[32:33], v34, off
	v_add_f32_e32 v32, 1.0, v36
	v_rcp_f32_e32 v32, v32
	v_mul_f32_e32 v33, 0xbf1b4598, v35
	v_mul_f32_e32 v33, 0x3fb8aa3b, v33
	v_exp_f32_e32 v34, v33
	v_mul_f32_e32 v32, 0xbf1b4598, v32
	v_mul_f32_e32 v32, 0x3fb8aa3b, v32
	v_exp_f32_e32 v35, v32
	v_lshl_add_u64 v[32:33], v[84:85], 0, v[60:61]
	global_store_dword v[32:33], v34, off
	v_lshl_add_u64 v[32:33], v[84:85], 0, v[62:63]
	global_store_dword v[32:33], v35, off
	v_mov_b32_e32 v32, v232
	v_add_u32_e32 v117, v206, v210
	v_add_f32_e32 v16, v32, v16
	v_mul_f32_e32 v16, 0xbfb8aa3b, v16
	v_exp_f32_e32 v16, v16
	v_add_f32_e32 v17, v32, v17
	v_mul_f32_e32 v17, 0xbfb8aa3b, v17
	v_exp_f32_e32 v17, v17
	v_add_f32_e32 v16, 1.0, v16
	v_rcp_f32_e32 v16, v16
	v_add_f32_e32 v19, v32, v19
	v_add_f32_e32 v17, 1.0, v17
	v_rcp_f32_e32 v17, v17
	v_mul_f32_e32 v16, 0xbf1b4598, v16
	v_mul_f32_e32 v16, 0x3fb8aa3b, v16
	v_exp_f32_e32 v16, v16
	v_mul_f32_e32 v19, 0xbfb8aa3b, v19
	v_exp_f32_e32 v19, v19
	global_store_dword v[164:165], v16, off offset:256
	v_mul_f32_e32 v16, 0xbf1b4598, v17
	v_add_f32_e32 v17, v32, v18
	v_mul_f32_e32 v17, 0xbfb8aa3b, v17
	v_exp_f32_e32 v18, v17
	v_mul_f32_e32 v16, 0x3fb8aa3b, v16
	v_exp_f32_e32 v33, v16
	v_lshl_add_u64 v[16:17], v[86:87], 0, v[162:163]
	v_add_f32_e32 v18, 1.0, v18
	v_rcp_f32_e32 v18, v18
	global_store_dword v[16:17], v33, off
	v_lshl_add_u64 v[16:17], v[86:87], 0, v[160:161]
	v_add_f32_e32 v19, 1.0, v19
	v_mul_f32_e32 v18, 0xbf1b4598, v18
	v_mul_f32_e32 v18, 0x3fb8aa3b, v18
	v_exp_f32_e32 v18, v18
	v_rcp_f32_e32 v19, v19
	global_store_dword v[16:17], v18, off
	v_add_f32_e32 v17, v32, v20
	v_mul_f32_e32 v17, 0xbfb8aa3b, v17
	v_exp_f32_e32 v18, v17
	v_mul_f32_e32 v16, 0xbf1b4598, v19
	v_mul_f32_e32 v16, 0x3fb8aa3b, v16
	v_exp_f32_e32 v19, v16
	v_add_f32_e32 v18, 1.0, v18
	v_rcp_f32_e32 v18, v18
	v_lshl_add_u64 v[16:17], v[86:87], 0, v[158:159]
	v_add_f32_e32 v20, v32, v21
	global_store_dword v[16:17], v19, off
	v_mul_f32_e32 v18, 0xbf1b4598, v18
	v_mul_f32_e32 v18, 0x3fb8aa3b, v18
	v_exp_f32_e32 v18, v18
	v_lshl_add_u64 v[16:17], v[86:87], 0, v[156:157]
	v_mul_f32_e32 v20, 0xbfb8aa3b, v20
	v_exp_f32_e32 v20, v20
	global_store_dword v[16:17], v18, off
	v_add_f32_e32 v17, v32, v22
	v_mul_f32_e32 v17, 0xbfb8aa3b, v17
	v_exp_f32_e32 v18, v17
	v_add_f32_e32 v20, 1.0, v20
	v_rcp_f32_e32 v20, v20
	v_add_f32_e32 v18, 1.0, v18
	v_rcp_f32_e32 v18, v18
	v_mul_f32_e32 v16, 0xbf1b4598, v20
	v_mul_f32_e32 v16, 0x3fb8aa3b, v16
	v_exp_f32_e32 v19, v16
	v_mul_f32_e32 v18, 0xbf1b4598, v18
	v_mul_f32_e32 v18, 0x3fb8aa3b, v18
	v_exp_f32_e32 v18, v18
	v_lshl_add_u64 v[16:17], v[86:87], 0, v[154:155]
	v_add_f32_e32 v20, v32, v23
	global_store_dword v[16:17], v19, off
	v_lshl_add_u64 v[16:17], v[86:87], 0, v[152:153]
	v_mul_f32_e32 v20, 0xbfb8aa3b, v20
	global_store_dword v[16:17], v18, off
	v_add_f32_e32 v17, v32, v24
	v_exp_f32_e32 v20, v20
	v_mul_f32_e32 v17, 0xbfb8aa3b, v17
	v_exp_f32_e32 v18, v17
	v_add_f32_e32 v20, 1.0, v20
	v_rcp_f32_e32 v20, v20
	v_add_f32_e32 v18, 1.0, v18
	v_rcp_f32_e32 v18, v18
	v_mul_f32_e32 v16, 0xbf1b4598, v20
	v_mul_f32_e32 v16, 0x3fb8aa3b, v16
	v_mul_f32_e32 v18, 0xbf1b4598, v18
	v_exp_f32_e32 v19, v16
	v_mul_f32_e32 v18, 0x3fb8aa3b, v18
	v_exp_f32_e32 v18, v18
	v_lshl_add_u64 v[16:17], v[86:87], 0, v[48:49]
	v_add_f32_e32 v20, v32, v25
	global_store_dword v[16:17], v19, off
	v_lshl_add_u64 v[16:17], v[86:87], 0, v[50:51]
; __device__ __forceinline__ float sigmoid1(float x) { return __builtin_amdgcn_rcpf(1.0f + __expf(-x)); }
; __global__ void __launch_bounds__(NT, 2) mk_fwd(Args args) {
;     ...
;                     for (int nt = 0; nt < 4; ++nt) { const int col = c0 + nt * 32 + (lane & 31); const float w0v = w0p[col];
; #pragma unroll
;                         for (int r = 0; r < 16; ++r) { const int t = t0 + mt * 32 + (r & 3) + 8 * (r >> 2) + 4 * (lane >> 5);
;                             const float sg = sigmoid1(w0v + acc[nt][r]);
;                             DEC[(size_t)t * 1024 + col] = __expf(-0.60653065971f * sg); }
;                         asm volatile("" ::: "memory"); }
	v_mul_f32_e32 v20, 0xbfb8aa3b, v20
	global_store_dword v[16:17], v18, off
	v_add_f32_e32 v17, v32, v26
	v_exp_f32_e32 v20, v20
	v_mul_f32_e32 v17, 0xbfb8aa3b, v17
	v_exp_f32_e32 v18, v17
	v_add_f32_e32 v20, 1.0, v20
	v_rcp_f32_e32 v20, v20
	v_add_f32_e32 v18, 1.0, v18
	v_rcp_f32_e32 v18, v18
	v_mul_f32_e32 v16, 0xbf1b4598, v20
	v_mul_f32_e32 v16, 0x3fb8aa3b, v16
	v_mul_f32_e32 v18, 0xbf1b4598, v18
	v_exp_f32_e32 v19, v16
	v_add_f32_e32 v20, v32, v27
	v_mul_f32_e32 v18, 0x3fb8aa3b, v18
	v_mul_f32_e32 v20, 0xbfb8aa3b, v20
	v_exp_f32_e32 v18, v18
	v_exp_f32_e32 v20, v20
	v_lshl_add_u64 v[16:17], v[86:87], 0, v[52:53]
	global_store_dword v[16:17], v19, off
	v_lshl_add_u64 v[16:17], v[86:87], 0, v[54:55]
	global_store_dword v[16:17], v18, off
	v_add_f32_e32 v17, v32, v28
	v_add_f32_e32 v20, 1.0, v20
	v_mul_f32_e32 v17, 0xbfb8aa3b, v17
	v_rcp_f32_e32 v20, v20
	v_exp_f32_e32 v18, v17
	v_mul_f32_e32 v16, 0xbf1b4598, v20
	v_add_f32_e32 v18, 1.0, v18
	v_add_f32_e32 v20, v32, v29
	v_rcp_f32_e32 v18, v18
	v_mul_f32_e32 v20, 0xbfb8aa3b, v20
	v_exp_f32_e32 v20, v20
	v_mul_f32_e32 v16, 0x3fb8aa3b, v16
	v_mul_f32_e32 v18, 0xbf1b4598, v18
	v_exp_f32_e32 v19, v16
	v_mul_f32_e32 v18, 0x3fb8aa3b, v18
	v_add_f32_e32 v20, 1.0, v20
	v_exp_f32_e32 v18, v18
	v_rcp_f32_e32 v20, v20
	v_lshl_add_u64 v[16:17], v[86:87], 0, v[56:57]
	global_store_dword v[16:17], v19, off
	v_lshl_add_u64 v[16:17], v[86:87], 0, v[58:59]
	v_add_f32_e32 v19, v32, v30
	global_store_dword v[16:17], v18, off
	v_mul_f32_e32 v16, 0xbf1b4598, v20
	v_mul_f32_e32 v19, 0xbfb8aa3b, v19
	v_add_f32_e32 v20, v32, v31
	v_mul_f32_e32 v16, 0x3fb8aa3b, v16
	v_exp_f32_e32 v19, v19
	v_mul_f32_e32 v20, 0xbfb8aa3b, v20
	v_exp_f32_e32 v18, v16
	v_exp_f32_e32 v20, v20
	v_lshl_add_u64 v[16:17], v[86:87], 0, v[166:167]
	v_add_f32_e32 v19, 1.0, v19
	v_rcp_f32_e32 v19, v19
	global_store_dword v[16:17], v18, off
	v_add_f32_e32 v16, 1.0, v20
	v_rcp_f32_e32 v16, v16
	v_mul_f32_e32 v17, 0xbf1b4598, v19
	v_mul_f32_e32 v17, 0x3fb8aa3b, v17
	v_exp_f32_e32 v18, v17
	v_mul_f32_e32 v16, 0xbf1b4598, v16
	v_mul_f32_e32 v16, 0x3fb8aa3b, v16
	v_exp_f32_e32 v19, v16
	v_lshl_add_u64 v[16:17], v[86:87], 0, v[60:61]
	global_store_dword v[16:17], v18, off
	v_lshl_add_u64 v[16:17], v[86:87], 0, v[62:63]
	global_store_dword v[16:17], v19, off
	v_mov_b32_e32 v16, v233
	v_add_f32_e32 v0, v16, v0
	v_mul_f32_e32 v0, 0xbfb8aa3b, v0
	v_exp_f32_e32 v0, v0
	v_add_f32_e32 v1, v16, v1
	v_mul_f32_e32 v1, 0xbfb8aa3b, v1
	v_exp_f32_e32 v1, v1
	v_add_f32_e32 v0, 1.0, v0
	v_rcp_f32_e32 v0, v0
	v_add_f32_e32 v3, v16, v3
	v_add_f32_e32 v1, 1.0, v1
	v_rcp_f32_e32 v1, v1
	v_mul_f32_e32 v0, 0xbf1b4598, v0
	v_mul_f32_e32 v0, 0x3fb8aa3b, v0
	v_exp_f32_e32 v0, v0
	v_mul_f32_e32 v3, 0xbfb8aa3b, v3
	v_exp_f32_e32 v3, v3
	global_store_dword v[164:165], v0, off offset:384
	v_mul_f32_e32 v0, 0xbf1b4598, v1
	v_add_f32_e32 v1, v16, v2
	v_mul_f32_e32 v1, 0xbfb8aa3b, v1
	v_exp_f32_e32 v2, v1
	v_mul_f32_e32 v0, 0x3fb8aa3b, v0
	v_exp_f32_e32 v17, v0
	v_lshl_add_u64 v[0:1], v[88:89], 0, v[162:163]
	v_add_f32_e32 v2, 1.0, v2
	v_rcp_f32_e32 v2, v2
	global_store_dword v[0:1], v17, off
	v_lshl_add_u64 v[0:1], v[88:89], 0, v[160:161]
	v_add_f32_e32 v3, 1.0, v3
	v_mul_f32_e32 v2, 0xbf1b4598, v2
	v_mul_f32_e32 v2, 0x3fb8aa3b, v2
	v_exp_f32_e32 v2, v2
	v_rcp_f32_e32 v3, v3
	global_store_dword v[0:1], v2, off
	v_add_f32_e32 v1, v16, v4
	v_mul_f32_e32 v1, 0xbfb8aa3b, v1
	v_exp_f32_e32 v2, v1
	v_mul_f32_e32 v0, 0xbf1b4598, v3
	v_mul_f32_e32 v0, 0x3fb8aa3b, v0
	v_exp_f32_e32 v3, v0
	v_add_f32_e32 v2, 1.0, v2
	v_rcp_f32_e32 v2, v2
	v_lshl_add_u64 v[0:1], v[88:89], 0, v[158:159]
	v_add_f32_e32 v4, v16, v5
	global_store_dword v[0:1], v3, off
	v_mul_f32_e32 v2, 0xbf1b4598, v2
	v_mul_f32_e32 v2, 0x3fb8aa3b, v2
	v_exp_f32_e32 v2, v2
	v_lshl_add_u64 v[0:1], v[88:89], 0, v[156:157]
	v_mul_f32_e32 v4, 0xbfb8aa3b, v4
	v_exp_f32_e32 v4, v4
	global_store_dword v[0:1], v2, off
	v_add_f32_e32 v1, v16, v6
	v_mul_f32_e32 v1, 0xbfb8aa3b, v1
	v_exp_f32_e32 v2, v1
	v_add_f32_e32 v4, 1.0, v4
	v_rcp_f32_e32 v4, v4
	v_add_f32_e32 v2, 1.0, v2
	v_rcp_f32_e32 v2, v2
	v_mul_f32_e32 v0, 0xbf1b4598, v4
	v_mul_f32_e32 v0, 0x3fb8aa3b, v0
	v_exp_f32_e32 v3, v0
	v_mul_f32_e32 v2, 0xbf1b4598, v2
	v_mul_f32_e32 v2, 0x3fb8aa3b, v2
	v_exp_f32_e32 v2, v2
	v_lshl_add_u64 v[0:1], v[88:89], 0, v[154:155]
	v_add_f32_e32 v4, v16, v7
	global_store_dword v[0:1], v3, off
	v_lshl_add_u64 v[0:1], v[88:89], 0, v[152:153]
	v_mul_f32_e32 v4, 0xbfb8aa3b, v4
	global_store_dword v[0:1], v2, off
	v_add_f32_e32 v1, v16, v8
	v_exp_f32_e32 v4, v4
	v_mul_f32_e32 v1, 0xbfb8aa3b, v1
	v_exp_f32_e32 v2, v1
	v_add_f32_e32 v4, 1.0, v4
	v_rcp_f32_e32 v4, v4
	v_add_f32_e32 v2, 1.0, v2
	v_rcp_f32_e32 v2, v2
	v_mul_f32_e32 v0, 0xbf1b4598, v4
	v_mul_f32_e32 v0, 0x3fb8aa3b, v0
	v_mul_f32_e32 v2, 0xbf1b4598, v2
	v_exp_f32_e32 v3, v0
	v_mul_f32_e32 v2, 0x3fb8aa3b, v2
	v_exp_f32_e32 v2, v2
	v_lshl_add_u64 v[0:1], v[88:89], 0, v[48:49]
	v_add_f32_e32 v4, v16, v9
	global_store_dword v[0:1], v3, off
	v_lshl_add_u64 v[0:1], v[88:89], 0, v[50:51]
	v_mul_f32_e32 v4, 0xbfb8aa3b, v4
	global_store_dword v[0:1], v2, off
	v_add_f32_e32 v1, v16, v10
	v_exp_f32_e32 v4, v4
	v_mul_f32_e32 v1, 0xbfb8aa3b, v1
	v_exp_f32_e32 v2, v1
	v_mov_b32_e32 v48, 0
	v_add_f32_e32 v4, 1.0, v4
	v_rcp_f32_e32 v4, v4
	v_add_f32_e32 v2, 1.0, v2
	v_rcp_f32_e32 v2, v2
	v_mov_b32_e32 v49, v48
	v_mul_f32_e32 v0, 0xbf1b4598, v4
	v_mul_f32_e32 v0, 0x3fb8aa3b, v0
	v_mul_f32_e32 v2, 0xbf1b4598, v2
	v_exp_f32_e32 v3, v0
	v_add_f32_e32 v4, v16, v11
	v_mul_f32_e32 v2, 0x3fb8aa3b, v2
	v_mul_f32_e32 v4, 0xbfb8aa3b, v4
	v_exp_f32_e32 v2, v2
	v_exp_f32_e32 v4, v4
	v_lshl_add_u64 v[0:1], v[88:89], 0, v[52:53]
; __device__ __forceinline__ float sigmoid1(float x) { return __builtin_amdgcn_rcpf(1.0f + __expf(-x)); }
; #define RW_ZERO() do { _Pragma("unroll") for (int b_ = 0; b_ < 4; ++b_) _Pragma("unroll") for (int r_ = 0; r_ < 16; ++r_) acc[b_][r_] = 0.f; } while (0)
; __global__ void __launch_bounds__(NT, 2) mk_fwd(Args args) {
;     ...
;                     for (int nt = 0; nt < 4; ++nt) { const int col = c0 + nt * 32 + (lane & 31); const float w0v = w0p[col];
; #pragma unroll
;                         for (int r = 0; r < 16; ++r) { const int t = t0 + mt * 32 + (r & 3) + 8 * (r >> 2) + 4 * (lane >> 5);
;                             const float sg = sigmoid1(w0v + acc[nt][r]);
;                             DEC[(size_t)t * 1024 + col] = __expf(-0.60653065971f * sg); }
;                         asm volatile("" ::: "memory"); }
;                     RW_ZERO(); RW_MM(A2T, 64, 64, 4);
	global_store_dword v[0:1], v3, off
	v_lshl_add_u64 v[0:1], v[88:89], 0, v[54:55]
	global_store_dword v[0:1], v2, off
	v_add_f32_e32 v1, v16, v12
	v_add_f32_e32 v4, 1.0, v4
	v_mul_f32_e32 v1, 0xbfb8aa3b, v1
	v_rcp_f32_e32 v4, v4
	v_exp_f32_e32 v2, v1
	v_mov_b32_e32 v50, v48
	v_mov_b32_e32 v51, v48
	v_mul_f32_e32 v0, 0xbf1b4598, v4
	v_add_f32_e32 v2, 1.0, v2
	v_add_f32_e32 v4, v16, v13
	v_rcp_f32_e32 v2, v2
	v_mul_f32_e32 v4, 0xbfb8aa3b, v4
	v_exp_f32_e32 v4, v4
	v_mul_f32_e32 v0, 0x3fb8aa3b, v0
	v_mul_f32_e32 v2, 0xbf1b4598, v2
	v_exp_f32_e32 v3, v0
	v_mul_f32_e32 v2, 0x3fb8aa3b, v2
	v_add_f32_e32 v4, 1.0, v4
	v_exp_f32_e32 v2, v2
	v_rcp_f32_e32 v4, v4
	v_lshl_add_u64 v[0:1], v[88:89], 0, v[56:57]
	global_store_dword v[0:1], v3, off
	v_lshl_add_u64 v[0:1], v[88:89], 0, v[58:59]
	v_add_f32_e32 v3, v16, v14
	global_store_dword v[0:1], v2, off
	v_mul_f32_e32 v0, 0xbf1b4598, v4
	v_mul_f32_e32 v3, 0xbfb8aa3b, v3
	v_add_f32_e32 v4, v16, v15
	v_mul_f32_e32 v0, 0x3fb8aa3b, v0
	v_exp_f32_e32 v3, v3
	v_mul_f32_e32 v4, 0xbfb8aa3b, v4
	v_exp_f32_e32 v2, v0
	v_exp_f32_e32 v4, v4
	v_lshl_add_u64 v[0:1], v[88:89], 0, v[166:167]
	v_add_f32_e32 v3, 1.0, v3
	v_rcp_f32_e32 v3, v3
	global_store_dword v[0:1], v2, off
	v_add_f32_e32 v0, 1.0, v4
	v_rcp_f32_e32 v0, v0
	v_mul_f32_e32 v1, 0xbf1b4598, v3
	v_mul_f32_e32 v1, 0x3fb8aa3b, v1
	v_exp_f32_e32 v2, v1
	v_mul_f32_e32 v0, 0xbf1b4598, v0
	v_mul_f32_e32 v0, 0x3fb8aa3b, v0
	v_exp_f32_e32 v3, v0
	v_lshl_add_u64 v[0:1], v[88:89], 0, v[60:61]
	global_store_dword v[0:1], v2, off
	v_lshl_add_u64 v[0:1], v[88:89], 0, v[62:63]
	global_store_dword v[0:1], v3, off
	v_mov_b32_e32 v52, v48
	v_mov_b32_e32 v53, v48
	v_mov_b32_e32 v54, v48
	v_mov_b32_e32 v55, v48
	v_mov_b32_e32 v56, v48
	v_mov_b32_e32 v57, v48
	v_mov_b32_e32 v58, v48
	v_mov_b32_e32 v59, v48
	v_mov_b32_e32 v60, v48
	v_mov_b32_e32 v61, v48
	v_mov_b32_e32 v62, v48
	v_mov_b32_e32 v63, v48
	v_mov_b32_e32 v32, v48
	v_mov_b32_e32 v33, v48
	v_mov_b32_e32 v34, v48
	v_mov_b32_e32 v35, v48
	v_mov_b32_e32 v36, v48
	v_mov_b32_e32 v37, v48
	v_mov_b32_e32 v38, v48
	v_mov_b32_e32 v39, v48
	v_mov_b32_e32 v40, v48
	v_mov_b32_e32 v41, v48
	v_mov_b32_e32 v42, v48
	v_mov_b32_e32 v43, v48
	v_mov_b32_e32 v44, v48
	v_mov_b32_e32 v45, v48
	v_mov_b32_e32 v46, v48
	v_mov_b32_e32 v47, v48
	v_mov_b32_e32 v16, v48
	v_mov_b32_e32 v17, v48
	v_mov_b32_e32 v18, v48
	v_mov_b32_e32 v19, v48
	v_mov_b32_e32 v20, v48
	v_mov_b32_e32 v21, v48
	v_mov_b32_e32 v22, v48
	v_mov_b32_e32 v23, v48
	v_mov_b32_e32 v24, v48
	v_mov_b32_e32 v25, v48
	v_mov_b32_e32 v26, v48
	v_mov_b32_e32 v27, v48
	v_mov_b32_e32 v28, v48
	v_mov_b32_e32 v29, v48
	v_mov_b32_e32 v30, v48
	v_mov_b32_e32 v31, v48
	v_mov_b32_e32 v0, v48
	v_mov_b32_e32 v1, v48
	v_mov_b32_e32 v2, v48
	v_mov_b32_e32 v3, v48
	v_mov_b32_e32 v4, v48
	v_mov_b32_e32 v5, v48
	v_mov_b32_e32 v6, v48
	v_mov_b32_e32 v7, v48
	v_mov_b32_e32 v8, v48
	v_mov_b32_e32 v9, v48
	v_mov_b32_e32 v10, v48
	v_mov_b32_e32 v11, v48
	v_mov_b32_e32 v12, v48
	v_mov_b32_e32 v13, v48
	v_mov_b32_e32 v14, v48
	v_mov_b32_e32 v15, v48
.LBB0_368:
	v_lshl_add_u64 v[160:161], v[106:107], 0, s[8:9]
	v_add_co_u32_e32 v220, vcc, s65, v160
	v_lshl_add_u64 v[162:163], v[104:105], 0, s[8:9]
	s_nop 0
	v_addc_co_u32_e32 v221, vcc, 0, v161, vcc
	v_add_co_u32_e32 v224, vcc, s65, v162
	v_lshl_add_u64 v[164:165], v[102:103], 0, s[8:9]
	s_nop 0
	v_addc_co_u32_e32 v225, vcc, 0, v163, vcc
	v_add_co_u32_e32 v226, vcc, s65, v164
	v_lshl_add_u64 v[166:167], v[100:101], 0, s[8:9]
	s_nop 0
	v_addc_co_u32_e32 v227, vcc, 0, v165, vcc
	v_add_co_u32_e32 v228, vcc, s65, v166
	ds_read_b128 v[152:155], v117
	ds_read_b128 v[156:159], v117 offset:32
	v_addc_co_u32_e32 v229, vcc, 0, v167, vcc
	global_load_dwordx4 v[160:163], v[220:221], off
	global_load_dwordx4 v[164:167], v[224:225], off
	global_load_dwordx4 v[212:215], v[226:227], off
	global_load_dwordx4 v[216:219], v[228:229], off
	s_nop 0
	global_load_dwordx4 v[220:223], v[220:221], off offset:1024
	s_add_u32 s8, s8, 0x800
	s_addc_u32 s9, s9, 0
	s_cmpk_eq_i32 s8, 0x1000
	v_add_u32_e32 v117, 64, v117
	s_waitcnt vmcnt(4) lgkmcnt(1)
	v_mfma_f32_32x32x16_bf16 v[48:63], v[152:155], v[160:163], v[48:63]
	global_load_dwordx4 v[160:163], v[224:225], off offset:1024
	s_waitcnt vmcnt(4)
	v_mfma_f32_32x32x16_bf16 v[32:47], v[152:155], v[164:167], v[32:47]
	global_load_dwordx4 v[164:167], v[226:227], off offset:1024
	s_waitcnt vmcnt(4)
	v_mfma_f32_32x32x16_bf16 v[16:31], v[152:155], v[212:215], v[16:31]
	global_load_dwordx4 v[212:215], v[228:229], off offset:1024
	s_waitcnt vmcnt(4)
	v_mfma_f32_32x32x16_bf16 v[0:15], v[152:155], v[216:219], v[0:15]
	s_waitcnt vmcnt(3) lgkmcnt(0)
	v_mfma_f32_32x32x16_bf16 v[48:63], v[156:159], v[220:223], v[48:63]
	s_waitcnt vmcnt(2)
	v_mfma_f32_32x32x16_bf16 v[32:47], v[156:159], v[160:163], v[32:47]
	s_waitcnt vmcnt(1)
	v_mfma_f32_32x32x16_bf16 v[16:31], v[156:159], v[164:167], v[16:31]
	s_waitcnt vmcnt(0)
	v_mfma_f32_32x32x16_bf16 v[0:15], v[156:159], v[212:215], v[0:15]
	s_cbranch_scc0 .LBB0_368
; __device__ __forceinline__ float bf1(bf16 h) { return __uint_as_float((unsigned)h << 16); }
; __device__ __forceinline__ bf16 f2bf(float f) { return (bf16)(pg8::cvt_pk_bf16(f, 0.f) & 0xffffu); }
; __device__ __forceinline__ float half32_sum(float v) { v = row16_sum(v); v += __shfl_xor(v, 16); return v; }
; __device__ __forceinline__ float sigmoid1(float x) { return __builtin_amdgcn_rcpf(1.0f + __expf(-x)); }
; __global__ void __launch_bounds__(NT, 2) mk_fwd(Args args) {
;     ...
;                     for (int hh = 0; hh < 2; ++hh) {
;                         const int colA = c0 + hh * 64 + (lane & 31), colB = colA + 32;
;                         const float a0A = a0p[colA], a0B = a0p[colB], kkA = kkw[colA], kkB = kkw[colB], kaA = kaw[colA], kaB = kaw[colB];
; #pragma unroll
;                         for (int r = 0; r < 16; ++r) { const int tl = (r & 3) + 8 * (r >> 2) + 4 * (lane >> 5); const int t = t0 + mt * 32 + tl;
;                             const float kA = bf1(Ks[tl * 1032 + colA]), kB = bf1(Ks[tl * 1032 + colB]);
;                             const float aA = sigmoid1(a0A + acc[hh * 2][r]), aB = sigmoid1(a0B + acc[hh * 2 + 1][r]);
;                             const float qA = kA * kkA, qB = kB * kkB;
;                             const float ss = half32_sum(qA * qA + qB * qB);
;                             const float inv = __builtin_amdgcn_rsqf(fmaxf(ss, 1e-24f));
;                             const float nA = qA * inv, nB = qB * inv;
;                             const size_t oA = (size_t)t * 1024 + colA, oB = oA + 32;
;                             KP[oA] = f2bf(kA * (1.0f + (aA - 1.0f) * kaA)); KP[oB] = f2bf(kB * (1.0f + (aB - 1.0f) * kaB));
;                             KKn[oA] = f2bf(nA); KKn[oB] = f2bf(nB); BB[oA] = f2bf(nA * aA); BB[oB] = f2bf(nB * aB);
;                             if ((r & 3) == 3) asm volatile("" ::: "memory"); }
	v_mov_b32_e32 v139, v234
	v_mov_b32_e32 v123, v235
	v_mov_b32_e32 v125, v238
	v_mov_b32_e32 v127, v239
	v_mov_b32_e32 v121, v242
	v_mov_b32_e32 v119, v243
	v_or_b32_e32 v141, s33, v131
	ds_read_u16 v145, v171 offset:40960
	ds_read_u16 v147, v171 offset:41024
	ds_read_u16 v149, v173 offset:40960
	ds_read_u16 v151, v173 offset:41024
	ds_read_u16 v166, v175 offset:40960
	ds_read_u16 v167, v175 offset:41024
	ds_read_u16 v211, v177 offset:40960
	ds_read_u16 v212, v177 offset:41024
	v_lshlrev_b32_e32 v152, 10, v141
	s_waitcnt lgkmcnt(7)
	v_lshlrev_b32_e32 v141, 16, v145
	s_waitcnt lgkmcnt(6)
	v_lshlrev_b32_e32 v145, 16, v147
	s_waitcnt lgkmcnt(5)
	v_lshlrev_b32_e32 v147, 16, v149
	s_waitcnt lgkmcnt(4)
	v_lshlrev_b32_e32 v149, 16, v151
	v_and_b32_e32 v117, 64, v208
	v_xor_b32_e32 v137, 16, v208
	v_add_u32_e32 v117, 64, v117
	v_cmp_lt_i32_e32 vcc, v137, v117
	v_mov_b32_e32 v153, v97
	v_lshl_add_u64 v[154:155], v[152:153], 0, v[64:65]
	v_cndmask_b32_e32 v137, v208, v137, vcc
	v_lshlrev_b32_e32 v137, 2, v137
	v_lshlrev_b64 v[154:155], 1, v[154:155]
	v_lshl_add_u64 v[156:157], s[96:97], 0, v[154:155]
	v_or_b32_e32 v158, 64, v154
	v_mov_b32_e32 v159, v155
	v_lshl_add_u64 v[162:163], s[96:97], 0, v[158:159]
	v_lshl_add_u64 v[160:161], s[30:31], 0, v[154:155]
	v_lshl_add_u64 v[154:155], s[34:35], 0, v[154:155]
	v_or_b32_e32 v143, s33, v172
	v_lshl_add_u64 v[164:165], s[30:31], 0, v[158:159]
	v_lshl_add_u64 v[158:159], s[34:35], 0, v[158:159]
	v_lshl_add_u64 v[152:153], v[152:153], 0, v[70:71]
	v_lshlrev_b64 v[152:153], 1, v[152:153]
	s_mov_b64 s[8:9], 0
	v_add_f32_e32 v48, v139, v48
	v_add_f32_e32 v32, v123, v32
	v_mul_f32_e32 v151, v125, v141
	v_mul_f32_e32 v213, v127, v145
	v_mul_f32_e32 v216, v213, v213
	v_fmac_f32_e32 v216, v151, v151
	v_mul_f32_e32 v48, 0xbfb8aa3b, v48
	v_mul_f32_e32 v32, 0xbfb8aa3b, v32
	v_add_f32_dpp v216, v216, v216 quad_perm:[1,0,3,2] row_mask:0xf bank_mask:0xf bound_ctrl:1
	v_add_f32_e32 v49, v139, v49
	v_mul_f32_e32 v215, v127, v149
	v_add_f32_dpp v216, v216, v216 quad_perm:[2,3,0,1] row_mask:0xf bank_mask:0xf bound_ctrl:1
	v_exp_f32_e32 v48, v48
	v_exp_f32_e32 v32, v32
	v_add_f32_dpp v216, v216, v216 row_half_mirror row_mask:0xf bank_mask:0xf bound_ctrl:1
	v_mul_f32_e32 v214, v125, v147
	v_mul_f32_e32 v49, 0xbfb8aa3b, v49
	v_mul_f32_e32 v217, v215, v215
	v_add_f32_dpp v216, v216, v216 row_mirror row_mask:0xf bank_mask:0xf bound_ctrl:1
	v_exp_f32_e32 v49, v49
	v_fmac_f32_e32 v217, v214, v214
	ds_bpermute_b32 v218, v137, v216
	v_add_f32_e32 v48, 1.0, v48
	v_add_f32_dpp v217, v217, v217 quad_perm:[1,0,3,2] row_mask:0xf bank_mask:0xf bound_ctrl:1
	v_add_f32_e32 v32, 1.0, v32
	v_rcp_f32_e32 v48, v48
	v_add_f32_dpp v217, v217, v217 quad_perm:[2,3,0,1] row_mask:0xf bank_mask:0xf bound_ctrl:1
	v_rcp_f32_e32 v32, v32
	v_add_f32_e32 v49, 1.0, v49
	v_add_f32_dpp v217, v217, v217 row_half_mirror row_mask:0xf bank_mask:0xf bound_ctrl:1
	v_rcp_f32_e32 v219, v49
	s_waitcnt lgkmcnt(0)
	v_add_f32_e32 v216, v216, v218
	v_add_f32_dpp v217, v217, v217 row_mirror row_mask:0xf bank_mask:0xf bound_ctrl:1
	ds_bpermute_b32 v49, v137, v217
	v_max_f32_e32 v216, 0x179abe15, v216
	v_add_f32_e32 v220, -1.0, v48
	v_add_f32_e32 v221, -1.0, v32
	v_rsq_f32_e32 v216, v216
	v_add_f32_e32 v33, v123, v33
	v_fma_f32 v218, v121, v220, 1.0
	v_fma_f32 v220, v119, v221, 1.0
	v_mul_f32_e32 v33, 0xbfb8aa3b, v33
	v_mul_f32_e32 v141, v218, v141
	v_mul_f32_e32 v145, v220, v145
	v_exp_f32_e32 v33, v33
	s_waitcnt lgkmcnt(0)
	v_add_f32_e32 v49, v217, v49
	v_cvt_pk_bf16_f32 v141, v141, v97
	v_cvt_pk_bf16_f32 v145, v145, v97
	v_max_f32_e32 v49, 0x179abe15, v49
	global_store_short v[156:157], v141, off
	global_store_short v[162:163], v145, off
	v_mul_f32_e32 v141, v151, v216
	v_mul_f32_e32 v145, v213, v216
	v_rsq_f32_e32 v49, v49
	v_mul_f32_e32 v48, v48, v141
	v_mul_f32_e32 v32, v32, v145
	v_cvt_pk_bf16_f32 v151, v141, v97
	v_cvt_pk_bf16_f32 v48, v48, v97
	v_cvt_pk_bf16_f32 v32, v32, v97
	v_cvt_pk_bf16_f32 v156, v145, v97
	global_store_short v[160:161], v151, off
	global_store_short v[164:165], v156, off
	global_store_short v[154:155], v48, off
	global_store_short v[158:159], v32, off
	v_add_f32_e32 v32, 1.0, v33
	v_rcp_f32_e32 v141, v32
	v_lshlrev_b32_e32 v32, 10, v143
	v_mov_b32_e32 v33, v97
	v_add_f32_e32 v143, -1.0, v219
	v_mul_f32_e32 v145, v214, v49
	v_mul_f32_e32 v151, v215, v49
	v_lshl_add_u64 v[48:49], v[32:33], 0, v[64:65]
	v_fma_f32 v143, v121, v143, 1.0
	v_mul_f32_e32 v143, v143, v147
	v_lshlrev_b64 v[48:49], 1, v[48:49]
	v_cvt_pk_bf16_f32 v143, v143, v97
	v_lshl_add_u64 v[154:155], s[96:97], 0, v[48:49]
	global_store_short v[154:155], v143, off
	v_add_f32_e32 v143, -1.0, v141
	v_fma_f32 v143, v119, v143, 1.0
	v_mul_f32_e32 v143, v143, v149
	v_or_b32_e32 v154, 64, v48
	v_mov_b32_e32 v155, v49
	v_cvt_pk_bf16_f32 v143, v143, v97
	v_lshl_add_u64 v[156:157], s[96:97], 0, v[154:155]
	global_store_short v[156:157], v143, off
	v_cvt_pk_bf16_f32 v143, v145, v97
	v_lshl_add_u64 v[156:157], s[30:31], 0, v[48:49]
	global_store_short v[156:157], v143, off
	v_cvt_pk_bf16_f32 v143, v151, v97
	v_lshl_add_u64 v[156:157], s[30:31], 0, v[154:155]
	global_store_short v[156:157], v143, off
	v_mul_f32_e32 v143, v219, v145
	v_lshl_add_u64 v[48:49], s[34:35], 0, v[48:49]
	v_cvt_pk_bf16_f32 v143, v143, v97
	global_store_short v[48:49], v143, off
	v_mul_f32_e32 v48, v141, v151
	v_cvt_pk_bf16_f32 v141, v48, v97
	v_lshl_add_u64 v[48:49], s[34:35], 0, v[154:155]
	v_lshlrev_b32_e32 v143, 16, v167
	global_store_short v[48:49], v141, off
	v_lshlrev_b32_e32 v141, 16, v166
	v_mul_f32_e32 v145, v127, v143
	v_add_f32_e32 v49, v139, v50
	v_mul_f32_e32 v50, v125, v141
	v_mul_f32_e32 v147, v145, v145
	v_fmac_f32_e32 v147, v50, v50
	v_mul_f32_e32 v49, 0xbfb8aa3b, v49
	v_exp_f32_e32 v49, v49
	v_add_f32_dpp v147, v147, v147 quad_perm:[1,0,3,2] row_mask:0xf bank_mask:0xf bound_ctrl:1
	v_add_f32_e32 v34, v123, v34
	v_mul_f32_e32 v34, 0xbfb8aa3b, v34
	v_add_f32_dpp v147, v147, v147 quad_perm:[2,3,0,1] row_mask:0xf bank_mask:0xf bound_ctrl:1
	v_add_f32_e32 v49, 1.0, v49
	v_exp_f32_e32 v34, v34
	v_add_f32_dpp v147, v147, v147 row_half_mirror row_mask:0xf bank_mask:0xf bound_ctrl:1
	v_or_b32_e32 v48, s33, v174
	v_lshlrev_b32_e32 v48, 10, v48
	v_add_f32_dpp v147, v147, v147 row_mirror row_mask:0xf bank_mask:0xf bound_ctrl:1
	ds_bpermute_b32 v149, v137, v147
	v_add_f32_e32 v34, 1.0, v34
	v_rcp_f32_e32 v34, v34
	v_add_f32_e32 v35, v123, v35
	v_mul_f32_e32 v35, 0xbfb8aa3b, v35
	s_waitcnt lgkmcnt(0)
; __device__ __forceinline__ float bf1(bf16 h) { return __uint_as_float((unsigned)h << 16); }
; __device__ __forceinline__ bf16 f2bf(float f) { return (bf16)(pg8::cvt_pk_bf16(f, 0.f) & 0xffffu); }
; __device__ __forceinline__ float half32_sum(float v) { v = row16_sum(v); v += __shfl_xor(v, 16); return v; }
; __device__ __forceinline__ float sigmoid1(float x) { return __builtin_amdgcn_rcpf(1.0f + __expf(-x)); }
; __global__ void __launch_bounds__(NT, 2) mk_fwd(Args args) {
;     ...
;                     for (int hh = 0; hh < 2; ++hh) {
;                         const int colA = c0 + hh * 64 + (lane & 31), colB = colA + 32;
;                         const float a0A = a0p[colA], a0B = a0p[colB], kkA = kkw[colA], kkB = kkw[colB], kaA = kaw[colA], kaB = kaw[colB];
; #pragma unroll
;                         for (int r = 0; r < 16; ++r) { const int tl = (r & 3) + 8 * (r >> 2) + 4 * (lane >> 5); const int t = t0 + mt * 32 + tl;
;                             const float kA = bf1(Ks[tl * 1032 + colA]), kB = bf1(Ks[tl * 1032 + colB]);
;                             const float aA = sigmoid1(a0A + acc[hh * 2][r]), aB = sigmoid1(a0B + acc[hh * 2 + 1][r]);
;                             const float qA = kA * kkA, qB = kB * kkB;
;                             const float ss = half32_sum(qA * qA + qB * qB);
;                             const float inv = __builtin_amdgcn_rsqf(fmaxf(ss, 1e-24f));
;                             const float nA = qA * inv, nB = qB * inv;
;                             const size_t oA = (size_t)t * 1024 + colA, oB = oA + 32;
;                             KP[oA] = f2bf(kA * (1.0f + (aA - 1.0f) * kaA)); KP[oB] = f2bf(kB * (1.0f + (aB - 1.0f) * kaB));
;                             KKn[oA] = f2bf(nA); KKn[oB] = f2bf(nB); BB[oA] = f2bf(nA * aA); BB[oB] = f2bf(nB * aB);
;                             if ((r & 3) == 3) asm volatile("" ::: "memory"); }
	v_add_f32_e32 v147, v147, v149
	v_max_f32_e32 v147, 0x179abe15, v147
	v_rsq_f32_e32 v147, v147
	v_rcp_f32_e32 v149, v49
	v_mov_b32_e32 v49, v97
	v_lshl_add_u64 v[154:155], v[48:49], 0, v[64:65]
	v_mul_f32_e32 v50, v50, v147
	v_mul_f32_e32 v145, v145, v147
	v_add_f32_e32 v147, -1.0, v149
	v_fma_f32 v147, v121, v147, 1.0
	v_mul_f32_e32 v141, v147, v141
	v_lshlrev_b64 v[154:155], 1, v[154:155]
	v_cvt_pk_bf16_f32 v141, v141, v97
	v_lshl_add_u64 v[156:157], s[96:97], 0, v[154:155]
	global_store_short v[156:157], v141, off
	v_add_f32_e32 v141, -1.0, v34
	v_fma_f32 v141, v119, v141, 1.0
	v_mul_f32_e32 v141, v141, v143
	v_or_b32_e32 v156, 64, v154
	v_mov_b32_e32 v157, v155
	v_cvt_pk_bf16_f32 v141, v141, v97
	v_lshl_add_u64 v[158:159], s[96:97], 0, v[156:157]
	global_store_short v[158:159], v141, off
	v_cvt_pk_bf16_f32 v141, v50, v97
	v_lshl_add_u64 v[158:159], s[30:31], 0, v[154:155]
	global_store_short v[158:159], v141, off
	v_cvt_pk_bf16_f32 v141, v145, v97
	v_lshl_add_u64 v[158:159], s[30:31], 0, v[156:157]
	v_mul_f32_e32 v50, v149, v50
	v_lshlrev_b32_e32 v143, 16, v212
	global_store_short v[158:159], v141, off
	v_cvt_pk_bf16_f32 v50, v50, v97
	v_lshl_add_u64 v[154:155], s[34:35], 0, v[154:155]
	v_mul_f32_e32 v34, v34, v145
	v_lshlrev_b32_e32 v141, 16, v211
	v_mul_f32_e32 v145, v127, v143
	global_store_short v[154:155], v50, off
	v_add_f32_e32 v50, v139, v51
	v_mul_f32_e32 v51, v125, v141
	v_mul_f32_e32 v147, v145, v145
	v_fmac_f32_e32 v147, v51, v51
	v_mul_f32_e32 v50, 0xbfb8aa3b, v50
	v_exp_f32_e32 v50, v50
	v_add_f32_dpp v147, v147, v147 quad_perm:[1,0,3,2] row_mask:0xf bank_mask:0xf bound_ctrl:1
	v_exp_f32_e32 v35, v35
	v_cvt_pk_bf16_f32 v34, v34, v97
	v_add_f32_e32 v50, 1.0, v50
	v_add_f32_dpp v147, v147, v147 quad_perm:[2,3,0,1] row_mask:0xf bank_mask:0xf bound_ctrl:1
	v_lshl_add_u64 v[154:155], s[34:35], 0, v[156:157]
	global_store_short v[154:155], v34, off
	v_add_f32_dpp v147, v147, v147 row_half_mirror row_mask:0xf bank_mask:0xf bound_ctrl:1
	v_or_b32_e32 v34, s33, v176
	v_add_f32_e32 v35, 1.0, v35
	v_add_f32_dpp v147, v147, v147 row_mirror row_mask:0xf bank_mask:0xf bound_ctrl:1
	ds_bpermute_b32 v149, v137, v147
	v_rcp_f32_e32 v151, v35
	v_lshlrev_b32_e32 v34, 10, v34
	v_mov_b32_e32 v35, v97
	v_add_f32_e32 v36, v123, v36
	s_waitcnt lgkmcnt(0)
	v_add_f32_e32 v147, v147, v149
	v_max_f32_e32 v147, 0x179abe15, v147
	v_rsq_f32_e32 v147, v147
	v_rcp_f32_e32 v149, v50
	v_mul_f32_e32 v36, 0xbfb8aa3b, v36
	v_exp_f32_e32 v36, v36
	v_mul_f32_e32 v158, v51, v147
	v_mul_f32_e32 v145, v145, v147
	v_add_f32_e32 v147, -1.0, v149
	v_lshl_add_u64 v[50:51], v[34:35], 0, v[64:65]
	v_fma_f32 v147, v121, v147, 1.0
	v_mul_f32_e32 v141, v147, v141
	v_lshlrev_b64 v[50:51], 1, v[50:51]
	v_cvt_pk_bf16_f32 v141, v141, v97
	v_lshl_add_u64 v[154:155], s[96:97], 0, v[50:51]
	global_store_short v[154:155], v141, off
	v_add_f32_e32 v141, -1.0, v151
	v_fma_f32 v141, v119, v141, 1.0
	v_mul_f32_e32 v141, v141, v143
	v_or_b32_e32 v154, 64, v50
	v_mov_b32_e32 v155, v51
	v_cvt_pk_bf16_f32 v141, v141, v97
	v_lshl_add_u64 v[156:157], s[96:97], 0, v[154:155]
	global_store_short v[156:157], v141, off
	v_cvt_pk_bf16_f32 v141, v158, v97
	v_lshl_add_u64 v[156:157], s[30:31], 0, v[50:51]
	global_store_short v[156:157], v141, off
	v_cvt_pk_bf16_f32 v141, v145, v97
	v_lshl_add_u64 v[156:157], s[30:31], 0, v[154:155]
	global_store_short v[156:157], v141, off
	v_mul_f32_e32 v141, v149, v158
	v_lshl_add_u64 v[50:51], s[34:35], 0, v[50:51]
	v_cvt_pk_bf16_f32 v141, v141, v97
	global_store_short v[50:51], v141, off
	v_mul_f32_e32 v50, v151, v145
	v_cvt_pk_bf16_f32 v141, v50, v97
	v_lshl_add_u64 v[50:51], s[34:35], 0, v[154:155]
	global_store_short v[50:51], v141, off
	ds_read_u16 v51, v179 offset:40960
	ds_read_u16 v141, v179 offset:41024
	ds_read_u16 v143, v181 offset:40960
	ds_read_u16 v145, v181 offset:41024
	ds_read_u16 v147, v183 offset:40960
	ds_read_u16 v149, v183 offset:41024
	ds_read_u16 v151, v185 offset:40960
	ds_read_u16 v160, v185 offset:41024
	s_waitcnt lgkmcnt(6)
	v_lshlrev_b32_e32 v141, 16, v141
	v_lshlrev_b32_e32 v156, 16, v51
	v_mul_f32_e32 v154, v127, v141
	v_add_f32_e32 v51, v139, v52
	v_mul_f32_e32 v52, v125, v156
	v_mul_f32_e32 v155, v154, v154
	v_fmac_f32_e32 v155, v52, v52
	v_mul_f32_e32 v51, 0xbfb8aa3b, v51
	v_exp_f32_e32 v51, v51
	v_add_f32_dpp v155, v155, v155 quad_perm:[1,0,3,2] row_mask:0xf bank_mask:0xf bound_ctrl:1
	v_or_b32_e32 v50, s33, v178
	v_add_f32_e32 v36, 1.0, v36
	v_add_f32_dpp v155, v155, v155 quad_perm:[2,3,0,1] row_mask:0xf bank_mask:0xf bound_ctrl:1
	v_add_f32_e32 v51, 1.0, v51
	v_rcp_f32_e32 v161, v51
	v_add_f32_dpp v155, v155, v155 row_half_mirror row_mask:0xf bank_mask:0xf bound_ctrl:1
	v_rcp_f32_e32 v36, v36
	v_lshlrev_b32_e32 v50, 10, v50
	v_add_f32_dpp v155, v155, v155 row_mirror row_mask:0xf bank_mask:0xf bound_ctrl:1
	ds_bpermute_b32 v157, v137, v155
	v_mov_b32_e32 v51, v97
	v_add_f32_e32 v37, v123, v37
	v_mul_f32_e32 v37, 0xbfb8aa3b, v37
	v_exp_f32_e32 v37, v37
	s_waitcnt lgkmcnt(0)
; __device__ __forceinline__ float bf1(bf16 h) { return __uint_as_float((unsigned)h << 16); }
; __device__ __forceinline__ bf16 f2bf(float f) { return (bf16)(pg8::cvt_pk_bf16(f, 0.f) & 0xffffu); }
; __device__ __forceinline__ float half32_sum(float v) { v = row16_sum(v); v += __shfl_xor(v, 16); return v; }
; __device__ __forceinline__ float sigmoid1(float x) { return __builtin_amdgcn_rcpf(1.0f + __expf(-x)); }
; __global__ void __launch_bounds__(NT, 2) mk_fwd(Args args) {
;     ...
;                     for (int hh = 0; hh < 2; ++hh) {
;                         const int colA = c0 + hh * 64 + (lane & 31), colB = colA + 32;
;                         const float a0A = a0p[colA], a0B = a0p[colB], kkA = kkw[colA], kkB = kkw[colB], kaA = kaw[colA], kaB = kaw[colB];
; #pragma unroll
;                         for (int r = 0; r < 16; ++r) { const int tl = (r & 3) + 8 * (r >> 2) + 4 * (lane >> 5); const int t = t0 + mt * 32 + tl;
;                             const float kA = bf1(Ks[tl * 1032 + colA]), kB = bf1(Ks[tl * 1032 + colB]);
;                             const float aA = sigmoid1(a0A + acc[hh * 2][r]), aB = sigmoid1(a0B + acc[hh * 2 + 1][r]);
;                             const float qA = kA * kkA, qB = kB * kkB;
;                             const float ss = half32_sum(qA * qA + qB * qB);
;                             const float inv = __builtin_amdgcn_rsqf(fmaxf(ss, 1e-24f));
;                             const float nA = qA * inv, nB = qB * inv;
;                             const size_t oA = (size_t)t * 1024 + colA, oB = oA + 32;
;                             KP[oA] = f2bf(kA * (1.0f + (aA - 1.0f) * kaA)); KP[oB] = f2bf(kB * (1.0f + (aB - 1.0f) * kaB));
;                             KKn[oA] = f2bf(nA); KKn[oB] = f2bf(nB); BB[oA] = f2bf(nA * aA); BB[oB] = f2bf(nB * aB);
;                             if ((r & 3) == 3) asm volatile("" ::: "memory"); }
	v_add_f32_e32 v155, v155, v157
	v_max_f32_e32 v155, 0x179abe15, v155
	v_rsq_f32_e32 v155, v155
	v_add_f32_e32 v157, -1.0, v161
	v_fma_f32 v157, v121, v157, 1.0
	v_mul_f32_e32 v156, v157, v156
	v_mul_f32_e32 v52, v52, v155
	v_mul_f32_e32 v162, v154, v155
	v_lshl_add_u64 v[154:155], v[50:51], 0, v[64:65]
	v_lshlrev_b64 v[154:155], 1, v[154:155]
	v_cvt_pk_bf16_f32 v158, v156, v97
	v_lshl_add_u64 v[156:157], s[96:97], 0, v[154:155]
	global_store_short v[156:157], v158, off
	v_add_f32_e32 v156, -1.0, v36
	v_fma_f32 v156, v119, v156, 1.0
	v_mul_f32_e32 v141, v156, v141
	v_or_b32_e32 v156, 64, v154
	v_mov_b32_e32 v157, v155
	v_cvt_pk_bf16_f32 v141, v141, v97
	v_lshl_add_u64 v[158:159], s[96:97], 0, v[156:157]
	global_store_short v[158:159], v141, off
	v_cvt_pk_bf16_f32 v141, v52, v97
	v_lshl_add_u64 v[158:159], s[30:31], 0, v[154:155]
	global_store_short v[158:159], v141, off
	v_cvt_pk_bf16_f32 v141, v162, v97
	v_lshl_add_u64 v[158:159], s[30:31], 0, v[156:157]
	global_store_short v[158:159], v141, off
	v_mul_f32_e32 v52, v161, v52
	v_lshl_add_u64 v[154:155], s[34:35], 0, v[154:155]
	v_lshlrev_b32_e32 v141, 16, v143
	v_lshlrev_b32_e32 v143, 16, v145
	v_cvt_pk_bf16_f32 v52, v52, v97
	global_store_short v[154:155], v52, off
	v_mul_f32_e32 v36, v36, v162
	v_lshl_add_u64 v[154:155], s[34:35], 0, v[156:157]
	v_mul_f32_e32 v145, v127, v143
	v_cvt_pk_bf16_f32 v36, v36, v97
	global_store_short v[154:155], v36, off
	v_add_f32_e32 v52, v139, v53
	v_mul_f32_e32 v53, v125, v141
	v_mul_f32_e32 v154, v145, v145
	v_fmac_f32_e32 v154, v53, v53
	v_mul_f32_e32 v52, 0xbfb8aa3b, v52
	v_exp_f32_e32 v52, v52
	v_add_f32_dpp v154, v154, v154 quad_perm:[1,0,3,2] row_mask:0xf bank_mask:0xf bound_ctrl:1
	v_or_b32_e32 v36, s33, v180
	v_add_f32_e32 v37, 1.0, v37
	v_add_f32_dpp v154, v154, v154 quad_perm:[2,3,0,1] row_mask:0xf bank_mask:0xf bound_ctrl:1
	v_add_f32_e32 v52, 1.0, v52
	v_rcp_f32_e32 v158, v52
	v_add_f32_dpp v154, v154, v154 row_half_mirror row_mask:0xf bank_mask:0xf bound_ctrl:1
	v_rcp_f32_e32 v159, v37
	v_lshlrev_b32_e32 v36, 10, v36
	v_add_f32_dpp v154, v154, v154 row_mirror row_mask:0xf bank_mask:0xf bound_ctrl:1
	ds_bpermute_b32 v155, v137, v154
	v_mov_b32_e32 v37, v97
	v_add_f32_e32 v38, v123, v38
	v_mul_f32_e32 v38, 0xbfb8aa3b, v38
	v_exp_f32_e32 v38, v38
	s_waitcnt lgkmcnt(0)
	v_add_f32_e32 v154, v154, v155
	v_max_f32_e32 v154, 0x179abe15, v154
	v_rsq_f32_e32 v154, v154
	v_add_f32_e32 v38, 1.0, v38
	v_rcp_f32_e32 v38, v38
	v_add_f32_e32 v39, v123, v39
	v_mul_f32_e32 v161, v53, v154
	v_mul_f32_e32 v145, v145, v154
	v_add_f32_e32 v154, -1.0, v158
	v_lshl_add_u64 v[52:53], v[36:37], 0, v[64:65]
	v_fma_f32 v154, v121, v154, 1.0
	v_mul_f32_e32 v141, v154, v141
	v_lshlrev_b64 v[52:53], 1, v[52:53]
	v_cvt_pk_bf16_f32 v141, v141, v97
	v_lshl_add_u64 v[154:155], s[96:97], 0, v[52:53]
	global_store_short v[154:155], v141, off
	v_add_f32_e32 v141, -1.0, v159
	v_fma_f32 v141, v119, v141, 1.0
	v_mul_f32_e32 v141, v141, v143
	v_or_b32_e32 v154, 64, v52
	v_mov_b32_e32 v155, v53
	v_cvt_pk_bf16_f32 v141, v141, v97
	v_lshl_add_u64 v[156:157], s[96:97], 0, v[154:155]
	global_store_short v[156:157], v141, off
	v_cvt_pk_bf16_f32 v141, v161, v97
	v_lshl_add_u64 v[156:157], s[30:31], 0, v[52:53]
	global_store_short v[156:157], v141, off
	v_cvt_pk_bf16_f32 v141, v145, v97
	v_lshl_add_u64 v[156:157], s[30:31], 0, v[154:155]
	global_store_short v[156:157], v141, off
	v_mul_f32_e32 v141, v158, v161
	v_lshl_add_u64 v[52:53], s[34:35], 0, v[52:53]
	v_cvt_pk_bf16_f32 v141, v141, v97
	global_store_short v[52:53], v141, off
	v_mul_f32_e32 v52, v159, v145
	v_cvt_pk_bf16_f32 v141, v52, v97
	v_lshl_add_u64 v[52:53], s[34:35], 0, v[154:155]
	v_lshlrev_b32_e32 v143, 16, v149
	global_store_short v[52:53], v141, off
	v_lshlrev_b32_e32 v141, 16, v147
	v_mul_f32_e32 v145, v127, v143
	v_add_f32_e32 v53, v139, v54
	v_mul_f32_e32 v54, v125, v141
	v_mul_f32_e32 v147, v145, v145
	v_fmac_f32_e32 v147, v54, v54
	v_mul_f32_e32 v53, 0xbfb8aa3b, v53
	v_exp_f32_e32 v53, v53
	v_add_f32_dpp v147, v147, v147 quad_perm:[1,0,3,2] row_mask:0xf bank_mask:0xf bound_ctrl:1
	v_or_b32_e32 v52, s33, v182
	v_lshlrev_b32_e32 v52, 10, v52
	v_add_f32_dpp v147, v147, v147 quad_perm:[2,3,0,1] row_mask:0xf bank_mask:0xf bound_ctrl:1
	v_add_f32_e32 v53, 1.0, v53
	v_mul_f32_e32 v39, 0xbfb8aa3b, v39
	v_add_f32_dpp v147, v147, v147 row_half_mirror row_mask:0xf bank_mask:0xf bound_ctrl:1
	v_exp_f32_e32 v39, v39
	v_add_f32_e32 v40, v123, v40
	v_add_f32_dpp v147, v147, v147 row_mirror row_mask:0xf bank_mask:0xf bound_ctrl:1
	ds_bpermute_b32 v149, v137, v147
	v_add_f32_e32 v39, 1.0, v39
	v_mul_f32_e32 v40, 0xbfb8aa3b, v40
	v_exp_f32_e32 v40, v40
	v_add_f32_e32 v41, v123, v41
	s_waitcnt lgkmcnt(0)
; __device__ __forceinline__ float bf1(bf16 h) { return __uint_as_float((unsigned)h << 16); }
; __device__ __forceinline__ bf16 f2bf(float f) { return (bf16)(pg8::cvt_pk_bf16(f, 0.f) & 0xffffu); }
; __device__ __forceinline__ float half32_sum(float v) { v = row16_sum(v); v += __shfl_xor(v, 16); return v; }
; __device__ __forceinline__ float sigmoid1(float x) { return __builtin_amdgcn_rcpf(1.0f + __expf(-x)); }
; __global__ void __launch_bounds__(NT, 2) mk_fwd(Args args) {
;     ...
;                     for (int hh = 0; hh < 2; ++hh) {
;                         const int colA = c0 + hh * 64 + (lane & 31), colB = colA + 32;
;                         const float a0A = a0p[colA], a0B = a0p[colB], kkA = kkw[colA], kkB = kkw[colB], kaA = kaw[colA], kaB = kaw[colB];
; #pragma unroll
;                         for (int r = 0; r < 16; ++r) { const int tl = (r & 3) + 8 * (r >> 2) + 4 * (lane >> 5); const int t = t0 + mt * 32 + tl;
;                             const float kA = bf1(Ks[tl * 1032 + colA]), kB = bf1(Ks[tl * 1032 + colB]);
;                             const float aA = sigmoid1(a0A + acc[hh * 2][r]), aB = sigmoid1(a0B + acc[hh * 2 + 1][r]);
;                             const float qA = kA * kkA, qB = kB * kkB;
;                             const float ss = half32_sum(qA * qA + qB * qB);
;                             const float inv = __builtin_amdgcn_rsqf(fmaxf(ss, 1e-24f));
;                             const float nA = qA * inv, nB = qB * inv;
;                             const size_t oA = (size_t)t * 1024 + colA, oB = oA + 32;
;                             KP[oA] = f2bf(kA * (1.0f + (aA - 1.0f) * kaA)); KP[oB] = f2bf(kB * (1.0f + (aB - 1.0f) * kaB));
;                             KKn[oA] = f2bf(nA); KKn[oB] = f2bf(nB); BB[oA] = f2bf(nA * aA); BB[oB] = f2bf(nB * aB);
;                             if ((r & 3) == 3) asm volatile("" ::: "memory"); }
	v_add_f32_e32 v147, v147, v149
	v_max_f32_e32 v147, 0x179abe15, v147
	v_rsq_f32_e32 v147, v147
	v_rcp_f32_e32 v149, v53
	v_mov_b32_e32 v53, v97
	v_lshl_add_u64 v[154:155], v[52:53], 0, v[64:65]
	v_mul_f32_e32 v54, v54, v147
	v_mul_f32_e32 v145, v145, v147
	v_add_f32_e32 v147, -1.0, v149
	v_fma_f32 v147, v121, v147, 1.0
	v_mul_f32_e32 v141, v147, v141
	v_lshlrev_b64 v[154:155], 1, v[154:155]
	v_cvt_pk_bf16_f32 v141, v141, v97
	v_lshl_add_u64 v[156:157], s[96:97], 0, v[154:155]
	global_store_short v[156:157], v141, off
	v_add_f32_e32 v141, -1.0, v38
	v_fma_f32 v141, v119, v141, 1.0
	v_mul_f32_e32 v141, v141, v143
	v_or_b32_e32 v156, 64, v154
	v_mov_b32_e32 v157, v155
	v_cvt_pk_bf16_f32 v141, v141, v97
	v_lshl_add_u64 v[158:159], s[96:97], 0, v[156:157]
	global_store_short v[158:159], v141, off
	v_cvt_pk_bf16_f32 v141, v54, v97
	v_lshl_add_u64 v[158:159], s[30:31], 0, v[154:155]
	global_store_short v[158:159], v141, off
	v_cvt_pk_bf16_f32 v141, v145, v97
	v_lshl_add_u64 v[158:159], s[30:31], 0, v[156:157]
	v_mul_f32_e32 v54, v149, v54
	v_lshlrev_b32_e32 v143, 16, v160
	global_store_short v[158:159], v141, off
	v_cvt_pk_bf16_f32 v54, v54, v97
	v_lshl_add_u64 v[154:155], s[34:35], 0, v[154:155]
	v_mul_f32_e32 v38, v38, v145
	v_lshlrev_b32_e32 v141, 16, v151
	v_mul_f32_e32 v145, v127, v143
	global_store_short v[154:155], v54, off
	v_add_f32_e32 v54, v139, v55
	v_mul_f32_e32 v55, v125, v141
	v_mul_f32_e32 v147, v145, v145
	v_fmac_f32_e32 v147, v55, v55
	v_mul_f32_e32 v54, 0xbfb8aa3b, v54
	v_exp_f32_e32 v54, v54
	v_add_f32_dpp v147, v147, v147 quad_perm:[1,0,3,2] row_mask:0xf bank_mask:0xf bound_ctrl:1
	v_cvt_pk_bf16_f32 v38, v38, v97
	v_lshl_add_u64 v[154:155], s[34:35], 0, v[156:157]
	v_add_f32_e32 v54, 1.0, v54
	v_add_f32_dpp v147, v147, v147 quad_perm:[2,3,0,1] row_mask:0xf bank_mask:0xf bound_ctrl:1
	global_store_short v[154:155], v38, off
	v_or_b32_e32 v38, s33, v184
	v_add_f32_dpp v147, v147, v147 row_half_mirror row_mask:0xf bank_mask:0xf bound_ctrl:1
	v_rcp_f32_e32 v151, v39
	v_lshlrev_b32_e32 v38, 10, v38
	v_add_f32_dpp v147, v147, v147 row_mirror row_mask:0xf bank_mask:0xf bound_ctrl:1
	ds_bpermute_b32 v149, v137, v147
	v_mov_b32_e32 v39, v97
	v_add_f32_e32 v40, 1.0, v40
	v_rcp_f32_e32 v40, v40
	v_mul_f32_e32 v41, 0xbfb8aa3b, v41
	s_waitcnt lgkmcnt(0)
	v_add_f32_e32 v147, v147, v149
	v_max_f32_e32 v147, 0x179abe15, v147
	v_rsq_f32_e32 v147, v147
	v_rcp_f32_e32 v149, v54
	v_exp_f32_e32 v41, v41
	v_add_f32_e32 v42, v123, v42
	v_mul_f32_e32 v158, v55, v147
	v_mul_f32_e32 v145, v145, v147
	v_add_f32_e32 v147, -1.0, v149
	v_lshl_add_u64 v[54:55], v[38:39], 0, v[64:65]
	v_fma_f32 v147, v121, v147, 1.0
	v_mul_f32_e32 v141, v147, v141
	v_lshlrev_b64 v[54:55], 1, v[54:55]
	v_cvt_pk_bf16_f32 v141, v141, v97
	v_lshl_add_u64 v[154:155], s[96:97], 0, v[54:55]
	global_store_short v[154:155], v141, off
	v_add_f32_e32 v141, -1.0, v151
	v_fma_f32 v141, v119, v141, 1.0
	v_mul_f32_e32 v141, v141, v143
	v_or_b32_e32 v154, 64, v54
	v_mov_b32_e32 v155, v55
	v_cvt_pk_bf16_f32 v141, v141, v97
	v_lshl_add_u64 v[156:157], s[96:97], 0, v[154:155]
	global_store_short v[156:157], v141, off
	v_cvt_pk_bf16_f32 v141, v158, v97
	v_lshl_add_u64 v[156:157], s[30:31], 0, v[54:55]
	global_store_short v[156:157], v141, off
	v_cvt_pk_bf16_f32 v141, v145, v97
	v_lshl_add_u64 v[156:157], s[30:31], 0, v[154:155]
	global_store_short v[156:157], v141, off
	v_mul_f32_e32 v141, v149, v158
	v_lshl_add_u64 v[54:55], s[34:35], 0, v[54:55]
	v_cvt_pk_bf16_f32 v141, v141, v97
	global_store_short v[54:55], v141, off
	v_mul_f32_e32 v54, v151, v145
	v_cvt_pk_bf16_f32 v141, v54, v97
	v_lshl_add_u64 v[54:55], s[34:35], 0, v[154:155]
	global_store_short v[54:55], v141, off
	ds_read_u16 v55, v187 offset:40960
	ds_read_u16 v141, v187 offset:41024
	ds_read_u16 v143, v189 offset:40960
	ds_read_u16 v145, v189 offset:41024
	ds_read_u16 v147, v191 offset:40960
	ds_read_u16 v149, v191 offset:41024
	ds_read_u16 v151, v193 offset:40960
	ds_read_u16 v160, v193 offset:41024
	s_waitcnt lgkmcnt(6)
	v_lshlrev_b32_e32 v141, 16, v141
	v_lshlrev_b32_e32 v156, 16, v55
	v_mul_f32_e32 v154, v127, v141
	v_add_f32_e32 v55, v139, v56
	v_mul_f32_e32 v56, v125, v156
	v_mul_f32_e32 v155, v154, v154
	v_fmac_f32_e32 v155, v56, v56
	v_mul_f32_e32 v55, 0xbfb8aa3b, v55
	v_exp_f32_e32 v55, v55
	v_add_f32_dpp v155, v155, v155 quad_perm:[1,0,3,2] row_mask:0xf bank_mask:0xf bound_ctrl:1
	v_or_b32_e32 v54, s33, v186
	v_lshlrev_b32_e32 v54, 10, v54
	v_add_f32_dpp v155, v155, v155 quad_perm:[2,3,0,1] row_mask:0xf bank_mask:0xf bound_ctrl:1
	v_add_f32_e32 v55, 1.0, v55
	v_rcp_f32_e32 v161, v55
	v_add_f32_dpp v155, v155, v155 row_half_mirror row_mask:0xf bank_mask:0xf bound_ctrl:1
	v_mov_b32_e32 v55, v97
	v_add_f32_e32 v41, 1.0, v41
	v_add_f32_dpp v155, v155, v155 row_mirror row_mask:0xf bank_mask:0xf bound_ctrl:1
	ds_bpermute_b32 v157, v137, v155
	v_mul_f32_e32 v42, 0xbfb8aa3b, v42
	v_exp_f32_e32 v42, v42
	v_add_f32_e32 v43, v123, v43
	v_mul_f32_e32 v43, 0xbfb8aa3b, v43
	s_waitcnt lgkmcnt(0)
; __device__ __forceinline__ float bf1(bf16 h) { return __uint_as_float((unsigned)h << 16); }
; __device__ __forceinline__ bf16 f2bf(float f) { return (bf16)(pg8::cvt_pk_bf16(f, 0.f) & 0xffffu); }
; __device__ __forceinline__ float half32_sum(float v) { v = row16_sum(v); v += __shfl_xor(v, 16); return v; }
; __device__ __forceinline__ float sigmoid1(float x) { return __builtin_amdgcn_rcpf(1.0f + __expf(-x)); }
; __global__ void __launch_bounds__(NT, 2) mk_fwd(Args args) {
;     ...
;                     for (int hh = 0; hh < 2; ++hh) {
;                         const int colA = c0 + hh * 64 + (lane & 31), colB = colA + 32;
;                         const float a0A = a0p[colA], a0B = a0p[colB], kkA = kkw[colA], kkB = kkw[colB], kaA = kaw[colA], kaB = kaw[colB];
; #pragma unroll
;                         for (int r = 0; r < 16; ++r) { const int tl = (r & 3) + 8 * (r >> 2) + 4 * (lane >> 5); const int t = t0 + mt * 32 + tl;
;                             const float kA = bf1(Ks[tl * 1032 + colA]), kB = bf1(Ks[tl * 1032 + colB]);
;                             const float aA = sigmoid1(a0A + acc[hh * 2][r]), aB = sigmoid1(a0B + acc[hh * 2 + 1][r]);
;                             const float qA = kA * kkA, qB = kB * kkB;
;                             const float ss = half32_sum(qA * qA + qB * qB);
;                             const float inv = __builtin_amdgcn_rsqf(fmaxf(ss, 1e-24f));
;                             const float nA = qA * inv, nB = qB * inv;
;                             const size_t oA = (size_t)t * 1024 + colA, oB = oA + 32;
;                             KP[oA] = f2bf(kA * (1.0f + (aA - 1.0f) * kaA)); KP[oB] = f2bf(kB * (1.0f + (aB - 1.0f) * kaB));
;                             KKn[oA] = f2bf(nA); KKn[oB] = f2bf(nB); BB[oA] = f2bf(nA * aA); BB[oB] = f2bf(nB * aB);
;                             if ((r & 3) == 3) asm volatile("" ::: "memory"); }
	v_add_f32_e32 v155, v155, v157
	v_max_f32_e32 v155, 0x179abe15, v155
	v_rsq_f32_e32 v155, v155
	v_add_f32_e32 v157, -1.0, v161
	v_fma_f32 v157, v121, v157, 1.0
	v_mul_f32_e32 v156, v157, v156
	v_mul_f32_e32 v56, v56, v155
	v_mul_f32_e32 v162, v154, v155
	v_lshl_add_u64 v[154:155], v[54:55], 0, v[64:65]
	v_lshlrev_b64 v[154:155], 1, v[154:155]
	v_cvt_pk_bf16_f32 v158, v156, v97
	v_lshl_add_u64 v[156:157], s[96:97], 0, v[154:155]
	global_store_short v[156:157], v158, off
	v_add_f32_e32 v156, -1.0, v40
	v_fma_f32 v156, v119, v156, 1.0
	v_mul_f32_e32 v141, v156, v141
	v_or_b32_e32 v156, 64, v154
	v_mov_b32_e32 v157, v155
	v_cvt_pk_bf16_f32 v141, v141, v97
	v_lshl_add_u64 v[158:159], s[96:97], 0, v[156:157]
	global_store_short v[158:159], v141, off
	v_cvt_pk_bf16_f32 v141, v56, v97
	v_lshl_add_u64 v[158:159], s[30:31], 0, v[154:155]
	global_store_short v[158:159], v141, off
	v_cvt_pk_bf16_f32 v141, v162, v97
	v_lshl_add_u64 v[158:159], s[30:31], 0, v[156:157]
	global_store_short v[158:159], v141, off
	v_mul_f32_e32 v56, v161, v56
	v_lshl_add_u64 v[154:155], s[34:35], 0, v[154:155]
	v_lshlrev_b32_e32 v141, 16, v143
	v_lshlrev_b32_e32 v143, 16, v145
	v_cvt_pk_bf16_f32 v56, v56, v97
	global_store_short v[154:155], v56, off
	v_mul_f32_e32 v40, v40, v162
	v_lshl_add_u64 v[154:155], s[34:35], 0, v[156:157]
	v_mul_f32_e32 v145, v127, v143
	v_cvt_pk_bf16_f32 v40, v40, v97
	global_store_short v[154:155], v40, off
	v_add_f32_e32 v56, v139, v57
	v_mul_f32_e32 v57, v125, v141
	v_mul_f32_e32 v154, v145, v145
	v_fmac_f32_e32 v154, v57, v57
	v_mul_f32_e32 v56, 0xbfb8aa3b, v56
	v_exp_f32_e32 v56, v56
	v_add_f32_dpp v154, v154, v154 quad_perm:[1,0,3,2] row_mask:0xf bank_mask:0xf bound_ctrl:1
	v_or_b32_e32 v40, s33, v188
	v_rcp_f32_e32 v159, v41
	v_add_f32_dpp v154, v154, v154 quad_perm:[2,3,0,1] row_mask:0xf bank_mask:0xf bound_ctrl:1
	v_add_f32_e32 v56, 1.0, v56
	v_rcp_f32_e32 v158, v56
	v_add_f32_dpp v154, v154, v154 row_half_mirror row_mask:0xf bank_mask:0xf bound_ctrl:1
	v_lshlrev_b32_e32 v40, 10, v40
	v_mov_b32_e32 v41, v97
	v_add_f32_dpp v154, v154, v154 row_mirror row_mask:0xf bank_mask:0xf bound_ctrl:1
	ds_bpermute_b32 v155, v137, v154
	v_add_f32_e32 v42, 1.0, v42
	v_rcp_f32_e32 v42, v42
	v_exp_f32_e32 v43, v43
	v_add_f32_e32 v44, v123, v44
	s_waitcnt lgkmcnt(0)
	v_add_f32_e32 v154, v154, v155
	v_max_f32_e32 v154, 0x179abe15, v154
	v_rsq_f32_e32 v154, v154
	v_add_f32_e32 v43, 1.0, v43
	v_mul_f32_e32 v44, 0xbfb8aa3b, v44
	v_exp_f32_e32 v44, v44
	v_mul_f32_e32 v161, v57, v154
	v_mul_f32_e32 v145, v145, v154
	v_add_f32_e32 v154, -1.0, v158
	v_lshl_add_u64 v[56:57], v[40:41], 0, v[64:65]
	v_fma_f32 v154, v121, v154, 1.0
	v_mul_f32_e32 v141, v154, v141
	v_lshlrev_b64 v[56:57], 1, v[56:57]
	v_cvt_pk_bf16_f32 v141, v141, v97
	v_lshl_add_u64 v[154:155], s[96:97], 0, v[56:57]
	global_store_short v[154:155], v141, off
	v_add_f32_e32 v141, -1.0, v159
	v_fma_f32 v141, v119, v141, 1.0
	v_mul_f32_e32 v141, v141, v143
	v_or_b32_e32 v154, 64, v56
	v_mov_b32_e32 v155, v57
	v_cvt_pk_bf16_f32 v141, v141, v97
	v_lshl_add_u64 v[156:157], s[96:97], 0, v[154:155]
	global_store_short v[156:157], v141, off
	v_cvt_pk_bf16_f32 v141, v161, v97
	v_lshl_add_u64 v[156:157], s[30:31], 0, v[56:57]
	global_store_short v[156:157], v141, off
	v_cvt_pk_bf16_f32 v141, v145, v97
	v_lshl_add_u64 v[156:157], s[30:31], 0, v[154:155]
	global_store_short v[156:157], v141, off
	v_mul_f32_e32 v141, v158, v161
	v_lshl_add_u64 v[56:57], s[34:35], 0, v[56:57]
	v_cvt_pk_bf16_f32 v141, v141, v97
	global_store_short v[56:57], v141, off
	v_mul_f32_e32 v56, v159, v145
	v_cvt_pk_bf16_f32 v141, v56, v97
	v_lshl_add_u64 v[56:57], s[34:35], 0, v[154:155]
	v_lshlrev_b32_e32 v143, 16, v149
	global_store_short v[56:57], v141, off
	v_lshlrev_b32_e32 v141, 16, v147
	v_mul_f32_e32 v145, v127, v143
	v_add_f32_e32 v57, v139, v58
	v_mul_f32_e32 v58, v125, v141
	v_mul_f32_e32 v147, v145, v145
	v_fmac_f32_e32 v147, v58, v58
	v_mul_f32_e32 v57, 0xbfb8aa3b, v57
	v_exp_f32_e32 v57, v57
	v_add_f32_dpp v147, v147, v147 quad_perm:[1,0,3,2] row_mask:0xf bank_mask:0xf bound_ctrl:1
	v_or_b32_e32 v56, s33, v190
	v_lshlrev_b32_e32 v56, 10, v56
	v_add_f32_dpp v147, v147, v147 quad_perm:[2,3,0,1] row_mask:0xf bank_mask:0xf bound_ctrl:1
	v_add_f32_e32 v57, 1.0, v57
	v_add_f32_e32 v44, 1.0, v44
	v_add_f32_dpp v147, v147, v147 row_half_mirror row_mask:0xf bank_mask:0xf bound_ctrl:1
	v_rcp_f32_e32 v44, v44
	v_add_f32_e32 v45, v123, v45
	v_add_f32_dpp v147, v147, v147 row_mirror row_mask:0xf bank_mask:0xf bound_ctrl:1
	ds_bpermute_b32 v149, v137, v147
	v_mul_f32_e32 v45, 0xbfb8aa3b, v45
	v_exp_f32_e32 v45, v45
	v_add_f32_e32 v46, v123, v46
	v_mul_f32_e32 v46, 0xbfb8aa3b, v46
	s_waitcnt lgkmcnt(0)
; __device__ __forceinline__ float bf1(bf16 h) { return __uint_as_float((unsigned)h << 16); }
; __device__ __forceinline__ bf16 f2bf(float f) { return (bf16)(pg8::cvt_pk_bf16(f, 0.f) & 0xffffu); }
; __device__ __forceinline__ float half32_sum(float v) { v = row16_sum(v); v += __shfl_xor(v, 16); return v; }
; __device__ __forceinline__ float sigmoid1(float x) { return __builtin_amdgcn_rcpf(1.0f + __expf(-x)); }
; __global__ void __launch_bounds__(NT, 2) mk_fwd(Args args) {
;     ...
;                     for (int hh = 0; hh < 2; ++hh) {
;                         const int colA = c0 + hh * 64 + (lane & 31), colB = colA + 32;
;                         const float a0A = a0p[colA], a0B = a0p[colB], kkA = kkw[colA], kkB = kkw[colB], kaA = kaw[colA], kaB = kaw[colB];
; #pragma unroll
;                         for (int r = 0; r < 16; ++r) { const int tl = (r & 3) + 8 * (r >> 2) + 4 * (lane >> 5); const int t = t0 + mt * 32 + tl;
;                             const float kA = bf1(Ks[tl * 1032 + colA]), kB = bf1(Ks[tl * 1032 + colB]);
;                             const float aA = sigmoid1(a0A + acc[hh * 2][r]), aB = sigmoid1(a0B + acc[hh * 2 + 1][r]);
;                             const float qA = kA * kkA, qB = kB * kkB;
;                             const float ss = half32_sum(qA * qA + qB * qB);
;                             const float inv = __builtin_amdgcn_rsqf(fmaxf(ss, 1e-24f));
;                             const float nA = qA * inv, nB = qB * inv;
;                             const size_t oA = (size_t)t * 1024 + colA, oB = oA + 32;
;                             KP[oA] = f2bf(kA * (1.0f + (aA - 1.0f) * kaA)); KP[oB] = f2bf(kB * (1.0f + (aB - 1.0f) * kaB));
;                             KKn[oA] = f2bf(nA); KKn[oB] = f2bf(nB); BB[oA] = f2bf(nA * aA); BB[oB] = f2bf(nB * aB);
;                             if ((r & 3) == 3) asm volatile("" ::: "memory"); }
	v_add_f32_e32 v147, v147, v149
	v_max_f32_e32 v147, 0x179abe15, v147
	v_rsq_f32_e32 v147, v147
	v_rcp_f32_e32 v149, v57
	v_mov_b32_e32 v57, v97
	v_lshl_add_u64 v[154:155], v[56:57], 0, v[64:65]
	v_mul_f32_e32 v58, v58, v147
	v_mul_f32_e32 v145, v145, v147
	v_add_f32_e32 v147, -1.0, v149
	v_fma_f32 v147, v121, v147, 1.0
	v_mul_f32_e32 v141, v147, v141
	v_lshlrev_b64 v[154:155], 1, v[154:155]
	v_cvt_pk_bf16_f32 v141, v141, v97
	v_lshl_add_u64 v[156:157], s[96:97], 0, v[154:155]
	global_store_short v[156:157], v141, off
	v_add_f32_e32 v141, -1.0, v42
	v_fma_f32 v141, v119, v141, 1.0
	v_mul_f32_e32 v141, v141, v143
	v_or_b32_e32 v156, 64, v154
	v_mov_b32_e32 v157, v155
	v_cvt_pk_bf16_f32 v141, v141, v97
	v_lshl_add_u64 v[158:159], s[96:97], 0, v[156:157]
	global_store_short v[158:159], v141, off
	v_cvt_pk_bf16_f32 v141, v58, v97
	v_lshl_add_u64 v[158:159], s[30:31], 0, v[154:155]
	global_store_short v[158:159], v141, off
	v_cvt_pk_bf16_f32 v141, v145, v97
	v_lshl_add_u64 v[158:159], s[30:31], 0, v[156:157]
	v_mul_f32_e32 v58, v149, v58
	v_lshlrev_b32_e32 v143, 16, v160
	global_store_short v[158:159], v141, off
	v_cvt_pk_bf16_f32 v58, v58, v97
	v_lshl_add_u64 v[154:155], s[34:35], 0, v[154:155]
	v_mul_f32_e32 v42, v42, v145
	v_lshlrev_b32_e32 v141, 16, v151
	v_mul_f32_e32 v145, v127, v143
	global_store_short v[154:155], v58, off
	v_add_f32_e32 v58, v139, v59
	v_mul_f32_e32 v59, v125, v141
	v_mul_f32_e32 v147, v145, v145
	v_fmac_f32_e32 v147, v59, v59
	v_mul_f32_e32 v58, 0xbfb8aa3b, v58
	v_exp_f32_e32 v58, v58
	v_add_f32_dpp v147, v147, v147 quad_perm:[1,0,3,2] row_mask:0xf bank_mask:0xf bound_ctrl:1
	v_cvt_pk_bf16_f32 v42, v42, v97
	v_lshl_add_u64 v[154:155], s[34:35], 0, v[156:157]
	v_add_f32_e32 v58, 1.0, v58
	v_add_f32_dpp v147, v147, v147 quad_perm:[2,3,0,1] row_mask:0xf bank_mask:0xf bound_ctrl:1
	global_store_short v[154:155], v42, off
	v_or_b32_e32 v42, s33, v192
	v_add_f32_dpp v147, v147, v147 row_half_mirror row_mask:0xf bank_mask:0xf bound_ctrl:1
	v_rcp_f32_e32 v151, v43
	v_lshlrev_b32_e32 v42, 10, v42
	v_add_f32_dpp v147, v147, v147 row_mirror row_mask:0xf bank_mask:0xf bound_ctrl:1
	ds_bpermute_b32 v149, v137, v147
	v_mov_b32_e32 v43, v97
	v_add_f32_e32 v45, 1.0, v45
	v_exp_f32_e32 v46, v46
	v_add_f32_e32 v47, v123, v47
	s_waitcnt lgkmcnt(0)
	v_add_f32_e32 v147, v147, v149
	v_max_f32_e32 v147, 0x179abe15, v147
	v_rsq_f32_e32 v147, v147
	v_rcp_f32_e32 v149, v58
	v_add_f32_e32 v46, 1.0, v46
	v_rcp_f32_e32 v46, v46
	v_mul_f32_e32 v158, v59, v147
	v_mul_f32_e32 v145, v145, v147
	v_add_f32_e32 v147, -1.0, v149
	v_lshl_add_u64 v[58:59], v[42:43], 0, v[64:65]
	v_fma_f32 v147, v121, v147, 1.0
	v_mul_f32_e32 v141, v147, v141
	v_lshlrev_b64 v[58:59], 1, v[58:59]
	v_cvt_pk_bf16_f32 v141, v141, v97
	v_lshl_add_u64 v[154:155], s[96:97], 0, v[58:59]
	global_store_short v[154:155], v141, off
	v_add_f32_e32 v141, -1.0, v151
	v_fma_f32 v141, v119, v141, 1.0
	v_mul_f32_e32 v141, v141, v143
	v_or_b32_e32 v154, 64, v58
	v_mov_b32_e32 v155, v59
	v_cvt_pk_bf16_f32 v141, v141, v97
	v_lshl_add_u64 v[156:157], s[96:97], 0, v[154:155]
	global_store_short v[156:157], v141, off
	v_cvt_pk_bf16_f32 v141, v158, v97
	v_lshl_add_u64 v[156:157], s[30:31], 0, v[58:59]
	global_store_short v[156:157], v141, off
	v_cvt_pk_bf16_f32 v141, v145, v97
	v_lshl_add_u64 v[156:157], s[30:31], 0, v[154:155]
	global_store_short v[156:157], v141, off
	v_mul_f32_e32 v141, v149, v158
	v_lshl_add_u64 v[58:59], s[34:35], 0, v[58:59]
	v_cvt_pk_bf16_f32 v141, v141, v97
	global_store_short v[58:59], v141, off
	v_mul_f32_e32 v58, v151, v145
	v_cvt_pk_bf16_f32 v141, v58, v97
	v_lshl_add_u64 v[58:59], s[34:35], 0, v[154:155]
	global_store_short v[58:59], v141, off
	ds_read_u16 v59, v195 offset:40960
	ds_read_u16 v141, v195 offset:41024
	ds_read_u16 v143, v197 offset:40960
	ds_read_u16 v145, v197 offset:41024
	ds_read_u16 v147, v199 offset:40960
	ds_read_u16 v149, v199 offset:41024
	ds_read_u16 v151, v201 offset:40960
	ds_read_u16 v160, v201 offset:41024
	s_waitcnt lgkmcnt(6)
	v_lshlrev_b32_e32 v141, 16, v141
	v_lshlrev_b32_e32 v156, 16, v59
	v_mul_f32_e32 v154, v127, v141
	v_add_f32_e32 v59, v139, v60
	v_mul_f32_e32 v60, v125, v156
	v_mul_f32_e32 v155, v154, v154
	v_fmac_f32_e32 v155, v60, v60
	v_mul_f32_e32 v59, 0xbfb8aa3b, v59
	v_exp_f32_e32 v59, v59
	v_add_f32_dpp v155, v155, v155 quad_perm:[1,0,3,2] row_mask:0xf bank_mask:0xf bound_ctrl:1
	v_or_b32_e32 v58, s33, v194
	v_lshlrev_b32_e32 v58, 10, v58
	v_add_f32_dpp v155, v155, v155 quad_perm:[2,3,0,1] row_mask:0xf bank_mask:0xf bound_ctrl:1
	v_add_f32_e32 v59, 1.0, v59
	v_rcp_f32_e32 v161, v59
	v_add_f32_dpp v155, v155, v155 row_half_mirror row_mask:0xf bank_mask:0xf bound_ctrl:1
	v_mov_b32_e32 v59, v97
	v_mul_f32_e32 v47, 0xbfb8aa3b, v47
	v_add_f32_dpp v155, v155, v155 row_mirror row_mask:0xf bank_mask:0xf bound_ctrl:1
	ds_bpermute_b32 v157, v137, v155
	v_exp_f32_e32 v47, v47
	s_waitcnt lgkmcnt(0)
; __device__ __forceinline__ float bf1(bf16 h) { return __uint_as_float((unsigned)h << 16); }
; __device__ __forceinline__ bf16 f2bf(float f) { return (bf16)(pg8::cvt_pk_bf16(f, 0.f) & 0xffffu); }
; __device__ __forceinline__ float half32_sum(float v) { v = row16_sum(v); v += __shfl_xor(v, 16); return v; }
; __device__ __forceinline__ float sigmoid1(float x) { return __builtin_amdgcn_rcpf(1.0f + __expf(-x)); }
; __global__ void __launch_bounds__(NT, 2) mk_fwd(Args args) {
;     ...
;                     for (int hh = 0; hh < 2; ++hh) {
;                         const int colA = c0 + hh * 64 + (lane & 31), colB = colA + 32;
;                         const float a0A = a0p[colA], a0B = a0p[colB], kkA = kkw[colA], kkB = kkw[colB], kaA = kaw[colA], kaB = kaw[colB];
; #pragma unroll
;                         for (int r = 0; r < 16; ++r) { const int tl = (r & 3) + 8 * (r >> 2) + 4 * (lane >> 5); const int t = t0 + mt * 32 + tl;
;                             const float kA = bf1(Ks[tl * 1032 + colA]), kB = bf1(Ks[tl * 1032 + colB]);
;                             const float aA = sigmoid1(a0A + acc[hh * 2][r]), aB = sigmoid1(a0B + acc[hh * 2 + 1][r]);
;                             const float qA = kA * kkA, qB = kB * kkB;
;                             const float ss = half32_sum(qA * qA + qB * qB);
;                             const float inv = __builtin_amdgcn_rsqf(fmaxf(ss, 1e-24f));
;                             const float nA = qA * inv, nB = qB * inv;
;                             const size_t oA = (size_t)t * 1024 + colA, oB = oA + 32;
;                             KP[oA] = f2bf(kA * (1.0f + (aA - 1.0f) * kaA)); KP[oB] = f2bf(kB * (1.0f + (aB - 1.0f) * kaB));
;                             KKn[oA] = f2bf(nA); KKn[oB] = f2bf(nB); BB[oA] = f2bf(nA * aA); BB[oB] = f2bf(nB * aB);
;                             if ((r & 3) == 3) asm volatile("" ::: "memory"); }
;                     }
	v_add_f32_e32 v155, v155, v157
	v_max_f32_e32 v155, 0x179abe15, v155
	v_rsq_f32_e32 v155, v155
	v_add_f32_e32 v157, -1.0, v161
	v_fma_f32 v157, v121, v157, 1.0
	v_mul_f32_e32 v156, v157, v156
	v_mul_f32_e32 v60, v60, v155
	v_mul_f32_e32 v162, v154, v155
	v_lshl_add_u64 v[154:155], v[58:59], 0, v[64:65]
	v_lshlrev_b64 v[154:155], 1, v[154:155]
	v_cvt_pk_bf16_f32 v158, v156, v97
	v_lshl_add_u64 v[156:157], s[96:97], 0, v[154:155]
	global_store_short v[156:157], v158, off
	v_add_f32_e32 v156, -1.0, v44
	v_fma_f32 v156, v119, v156, 1.0
	v_mul_f32_e32 v141, v156, v141
	v_or_b32_e32 v156, 64, v154
	v_mov_b32_e32 v157, v155
	v_cvt_pk_bf16_f32 v141, v141, v97
	v_lshl_add_u64 v[158:159], s[96:97], 0, v[156:157]
	global_store_short v[158:159], v141, off
	v_cvt_pk_bf16_f32 v141, v60, v97
	v_lshl_add_u64 v[158:159], s[30:31], 0, v[154:155]
	global_store_short v[158:159], v141, off
	v_cvt_pk_bf16_f32 v141, v162, v97
	v_lshl_add_u64 v[158:159], s[30:31], 0, v[156:157]
	global_store_short v[158:159], v141, off
	v_mul_f32_e32 v60, v161, v60
	v_lshl_add_u64 v[154:155], s[34:35], 0, v[154:155]
	v_lshlrev_b32_e32 v141, 16, v143
	v_lshlrev_b32_e32 v143, 16, v145
	v_cvt_pk_bf16_f32 v60, v60, v97
	global_store_short v[154:155], v60, off
	v_mul_f32_e32 v44, v44, v162
	v_lshl_add_u64 v[154:155], s[34:35], 0, v[156:157]
	v_mul_f32_e32 v145, v127, v143
	v_cvt_pk_bf16_f32 v44, v44, v97
	global_store_short v[154:155], v44, off
	v_add_f32_e32 v60, v139, v61
	v_mul_f32_e32 v61, v125, v141
	v_mul_f32_e32 v154, v145, v145
	v_fmac_f32_e32 v154, v61, v61
	v_mul_f32_e32 v60, 0xbfb8aa3b, v60
	v_exp_f32_e32 v60, v60
	v_add_f32_dpp v154, v154, v154 quad_perm:[1,0,3,2] row_mask:0xf bank_mask:0xf bound_ctrl:1
	v_or_b32_e32 v44, s33, v196
	v_rcp_f32_e32 v159, v45
	v_add_f32_dpp v154, v154, v154 quad_perm:[2,3,0,1] row_mask:0xf bank_mask:0xf bound_ctrl:1
	v_add_f32_e32 v60, 1.0, v60
	v_rcp_f32_e32 v158, v60
	v_add_f32_dpp v154, v154, v154 row_half_mirror row_mask:0xf bank_mask:0xf bound_ctrl:1
	v_lshlrev_b32_e32 v44, 10, v44
	v_mov_b32_e32 v45, v97
	v_add_f32_dpp v154, v154, v154 row_mirror row_mask:0xf bank_mask:0xf bound_ctrl:1
	ds_bpermute_b32 v155, v137, v154
	v_add_f32_e32 v47, 1.0, v47
	s_waitcnt lgkmcnt(0)
	v_add_f32_e32 v154, v154, v155
	v_max_f32_e32 v154, 0x179abe15, v154
	v_rsq_f32_e32 v154, v154
	s_nop 0
	v_mul_f32_e32 v161, v61, v154
	v_mul_f32_e32 v145, v145, v154
	v_add_f32_e32 v154, -1.0, v158
	v_lshl_add_u64 v[60:61], v[44:45], 0, v[64:65]
	v_fma_f32 v154, v121, v154, 1.0
	v_mul_f32_e32 v141, v154, v141
	v_lshlrev_b64 v[60:61], 1, v[60:61]
	v_cvt_pk_bf16_f32 v141, v141, v97
	v_lshl_add_u64 v[154:155], s[96:97], 0, v[60:61]
	global_store_short v[154:155], v141, off
	v_add_f32_e32 v141, -1.0, v159
	v_fma_f32 v141, v119, v141, 1.0
	v_mul_f32_e32 v141, v141, v143
	v_or_b32_e32 v154, 64, v60
	v_mov_b32_e32 v155, v61
	v_cvt_pk_bf16_f32 v141, v141, v97
	v_lshl_add_u64 v[156:157], s[96:97], 0, v[154:155]
	global_store_short v[156:157], v141, off
	v_cvt_pk_bf16_f32 v141, v161, v97
	v_lshl_add_u64 v[156:157], s[30:31], 0, v[60:61]
	global_store_short v[156:157], v141, off
	v_cvt_pk_bf16_f32 v141, v145, v97
	v_lshl_add_u64 v[156:157], s[30:31], 0, v[154:155]
	global_store_short v[156:157], v141, off
	v_mul_f32_e32 v141, v158, v161
	v_lshl_add_u64 v[60:61], s[34:35], 0, v[60:61]
	v_cvt_pk_bf16_f32 v141, v141, v97
	global_store_short v[60:61], v141, off
	v_mul_f32_e32 v60, v159, v145
	v_cvt_pk_bf16_f32 v141, v60, v97
	v_lshl_add_u64 v[60:61], s[34:35], 0, v[154:155]
	v_lshlrev_b32_e32 v143, 16, v149
	global_store_short v[60:61], v141, off
	v_lshlrev_b32_e32 v141, 16, v147
	v_mul_f32_e32 v145, v127, v143
	v_add_f32_e32 v61, v139, v62
	v_mul_f32_e32 v62, v125, v141
	v_mul_f32_e32 v147, v145, v145
	v_fmac_f32_e32 v147, v62, v62
	v_mul_f32_e32 v61, 0xbfb8aa3b, v61
	v_exp_f32_e32 v61, v61
	v_add_f32_dpp v147, v147, v147 quad_perm:[1,0,3,2] row_mask:0xf bank_mask:0xf bound_ctrl:1
	v_or_b32_e32 v60, s33, v198
	v_lshlrev_b32_e32 v60, 10, v60
	v_add_f32_dpp v147, v147, v147 quad_perm:[2,3,0,1] row_mask:0xf bank_mask:0xf bound_ctrl:1
	v_add_f32_e32 v61, 1.0, v61
	s_nop 0
	v_add_f32_dpp v147, v147, v147 row_half_mirror row_mask:0xf bank_mask:0xf bound_ctrl:1
	s_nop 1
	v_add_f32_dpp v147, v147, v147 row_mirror row_mask:0xf bank_mask:0xf bound_ctrl:1
	ds_bpermute_b32 v149, v137, v147
	s_waitcnt lgkmcnt(0)
	v_add_f32_e32 v147, v147, v149
	v_max_f32_e32 v147, 0x179abe15, v147
	v_rsq_f32_e32 v147, v147
	v_rcp_f32_e32 v149, v61
	v_mov_b32_e32 v61, v97
	v_lshl_add_u64 v[154:155], v[60:61], 0, v[64:65]
	v_mul_f32_e32 v62, v62, v147
	v_mul_f32_e32 v145, v145, v147
	v_add_f32_e32 v147, -1.0, v149
	v_fma_f32 v147, v121, v147, 1.0
	v_mul_f32_e32 v141, v147, v141
	v_lshlrev_b64 v[154:155], 1, v[154:155]
	v_cvt_pk_bf16_f32 v141, v141, v97
	v_lshl_add_u64 v[156:157], s[96:97], 0, v[154:155]
	global_store_short v[156:157], v141, off
	v_add_f32_e32 v141, -1.0, v46
	v_fma_f32 v141, v119, v141, 1.0
	v_mul_f32_e32 v141, v141, v143
	v_or_b32_e32 v156, 64, v154
	v_mov_b32_e32 v157, v155
	v_cvt_pk_bf16_f32 v141, v141, v97
	v_lshl_add_u64 v[158:159], s[96:97], 0, v[156:157]
	global_store_short v[158:159], v141, off
	v_cvt_pk_bf16_f32 v141, v62, v97
	v_lshl_add_u64 v[158:159], s[30:31], 0, v[154:155]
	global_store_short v[158:159], v141, off
	v_cvt_pk_bf16_f32 v141, v145, v97
	v_lshl_add_u64 v[158:159], s[30:31], 0, v[156:157]
	v_mul_f32_e32 v62, v149, v62
	global_store_short v[158:159], v141, off
	v_cvt_pk_bf16_f32 v62, v62, v97
	v_lshl_add_u64 v[154:155], s[34:35], 0, v[154:155]
	v_lshlrev_b32_e32 v141, 16, v151
	v_lshlrev_b32_e32 v143, 16, v160
	global_store_short v[154:155], v62, off
	v_add_f32_e32 v62, v139, v63
	v_mul_f32_e32 v63, v125, v141
	v_mul_f32_e32 v125, v127, v143
	v_mul_f32_e32 v127, v125, v125
	v_fmac_f32_e32 v127, v63, v63
	v_mul_f32_e32 v62, 0xbfb8aa3b, v62
	v_exp_f32_e32 v62, v62
	v_add_f32_dpp v127, v127, v127 quad_perm:[1,0,3,2] row_mask:0xf bank_mask:0xf bound_ctrl:1
	v_mul_f32_e32 v46, v46, v145
	v_cvt_pk_bf16_f32 v46, v46, v97
	v_add_f32_e32 v62, 1.0, v62
	v_add_f32_dpp v127, v127, v127 quad_perm:[2,3,0,1] row_mask:0xf bank_mask:0xf bound_ctrl:1
	v_lshl_add_u64 v[154:155], s[34:35], 0, v[156:157]
	global_store_short v[154:155], v46, off
	v_add_f32_dpp v127, v127, v127 row_half_mirror row_mask:0xf bank_mask:0xf bound_ctrl:1
	v_or_b32_e32 v46, s33, v200
	v_lshlrev_b32_e32 v46, 10, v46
	v_add_f32_dpp v127, v127, v127 row_mirror row_mask:0xf bank_mask:0xf bound_ctrl:1
	ds_bpermute_b32 v139, v137, v127
	s_waitcnt lgkmcnt(0)
; __device__ __forceinline__ float bf1(bf16 h) { return __uint_as_float((unsigned)h << 16); }
; __device__ __forceinline__ bf16 f2bf(float f) { return (bf16)(pg8::cvt_pk_bf16(f, 0.f) & 0xffffu); }
; __device__ __forceinline__ float half32_sum(float v) { v = row16_sum(v); v += __shfl_xor(v, 16); return v; }
; __device__ __forceinline__ float sigmoid1(float x) { return __builtin_amdgcn_rcpf(1.0f + __expf(-x)); }
; __global__ void __launch_bounds__(NT, 2) mk_fwd(Args args) {
;     ...
;                     for (int hh = 0; hh < 2; ++hh) {
;                         const int colA = c0 + hh * 64 + (lane & 31), colB = colA + 32;
;                         const float a0A = a0p[colA], a0B = a0p[colB], kkA = kkw[colA], kkB = kkw[colB], kaA = kaw[colA], kaB = kaw[colB];
; #pragma unroll
;                         for (int r = 0; r < 16; ++r) { const int tl = (r & 3) + 8 * (r >> 2) + 4 * (lane >> 5); const int t = t0 + mt * 32 + tl;
;                             const float kA = bf1(Ks[tl * 1032 + colA]), kB = bf1(Ks[tl * 1032 + colB]);
;                             const float aA = sigmoid1(a0A + acc[hh * 2][r]), aB = sigmoid1(a0B + acc[hh * 2 + 1][r]);
;                             const float qA = kA * kkA, qB = kB * kkB;
;                             const float ss = half32_sum(qA * qA + qB * qB);
;                             const float inv = __builtin_amdgcn_rsqf(fmaxf(ss, 1e-24f));
;                             const float nA = qA * inv, nB = qB * inv;
;                             const size_t oA = (size_t)t * 1024 + colA, oB = oA + 32;
;                             KP[oA] = f2bf(kA * (1.0f + (aA - 1.0f) * kaA)); KP[oB] = f2bf(kB * (1.0f + (aB - 1.0f) * kaB));
;                             KKn[oA] = f2bf(nA); KKn[oB] = f2bf(nB); BB[oA] = f2bf(nA * aA); BB[oB] = f2bf(nB * aB);
;                             if ((r & 3) == 3) asm volatile("" ::: "memory"); }
;                     }
	v_add_f32_e32 v123, v127, v139
	v_max_f32_e32 v123, 0x179abe15, v123
	v_rsq_f32_e32 v123, v123
	v_rcp_f32_e32 v127, v62
	v_rcp_f32_e32 v139, v47
	v_mov_b32_e32 v47, v97
	v_mul_f32_e32 v145, v63, v123
	v_mul_f32_e32 v123, v125, v123
	v_add_f32_e32 v125, -1.0, v127
	v_lshl_add_u64 v[62:63], v[46:47], 0, v[64:65]
	v_fma_f32 v121, v121, v125, 1.0
	v_mul_f32_e32 v121, v121, v141
	v_lshlrev_b64 v[62:63], 1, v[62:63]
	v_cvt_pk_bf16_f32 v121, v121, v97
	v_lshl_add_u64 v[154:155], s[96:97], 0, v[62:63]
	global_store_short v[154:155], v121, off
	v_add_f32_e32 v121, -1.0, v139
	v_fma_f32 v119, v119, v121, 1.0
	v_mul_f32_e32 v119, v119, v143
	v_or_b32_e32 v154, 64, v62
	v_mov_b32_e32 v155, v63
	v_cvt_pk_bf16_f32 v119, v119, v97
	v_lshl_add_u64 v[156:157], s[96:97], 0, v[154:155]
	global_store_short v[156:157], v119, off
	v_cvt_pk_bf16_f32 v119, v145, v97
	v_lshl_add_u64 v[156:157], s[30:31], 0, v[62:63]
	global_store_short v[156:157], v119, off
	v_cvt_pk_bf16_f32 v119, v123, v97
	v_lshl_add_u64 v[156:157], s[30:31], 0, v[154:155]
	global_store_short v[156:157], v119, off
	v_mul_f32_e32 v119, v127, v145
	v_lshl_add_u64 v[62:63], s[34:35], 0, v[62:63]
	v_cvt_pk_bf16_f32 v119, v119, v97
	global_store_short v[62:63], v119, off
	v_mul_f32_e32 v62, v139, v123
	v_cvt_pk_bf16_f32 v119, v62, v97
	v_lshl_add_u64 v[62:63], s[34:35], 0, v[154:155]
	global_store_short v[62:63], v119, off
	v_mov_b32_e32 v125, v236
	v_mov_b32_e32 v121, v240
	v_mov_b32_e32 v123, v241
	v_mov_b32_e32 v119, v237
	v_mov_b32_e32 v63, v244
	v_mov_b32_e32 v62, v245
	ds_read_u16 v127, v171 offset:41088
	ds_read_u16 v139, v171 offset:41152
	ds_read_u16 v141, v173 offset:41088
	ds_read_u16 v143, v173 offset:41152
	ds_read_u16 v145, v175 offset:41088
	ds_read_u16 v147, v175 offset:41152
	ds_read_u16 v149, v177 offset:41088
	ds_read_u16 v151, v177 offset:41152
	s_waitcnt lgkmcnt(6)
	v_lshlrev_b32_e32 v139, 16, v139
	v_lshlrev_b32_e32 v127, 16, v127
	v_add_f32_e32 v16, v125, v16
	v_mul_f32_e32 v154, v121, v127
	v_mul_f32_e32 v155, v123, v139
	v_mul_f32_e32 v156, v155, v155
	v_fmac_f32_e32 v156, v154, v154
	v_mul_f32_e32 v16, 0xbfb8aa3b, v16
	v_exp_f32_e32 v16, v16
	v_add_f32_dpp v156, v156, v156 quad_perm:[1,0,3,2] row_mask:0xf bank_mask:0xf bound_ctrl:1
	v_add_f32_e32 v0, v119, v0
	v_mul_f32_e32 v0, 0xbfb8aa3b, v0
	v_add_f32_dpp v156, v156, v156 quad_perm:[2,3,0,1] row_mask:0xf bank_mask:0xf bound_ctrl:1
	v_add_f32_e32 v16, 1.0, v16
	v_exp_f32_e32 v0, v0
	v_add_f32_dpp v156, v156, v156 row_half_mirror row_mask:0xf bank_mask:0xf bound_ctrl:1
	v_rcp_f32_e32 v16, v16
	v_add_f32_e32 v1, v119, v1
	v_add_f32_dpp v156, v156, v156 row_mirror row_mask:0xf bank_mask:0xf bound_ctrl:1
	ds_bpermute_b32 v157, v137, v156
	v_add_f32_e32 v0, 1.0, v0
	v_rcp_f32_e32 v0, v0
	v_mul_f32_e32 v1, 0xbfb8aa3b, v1
	v_exp_f32_e32 v1, v1
	s_waitcnt lgkmcnt(0)
	v_add_f32_e32 v156, v156, v157
	v_max_f32_e32 v156, 0x179abe15, v156
	v_rsq_f32_e32 v156, v156
	v_add_f32_e32 v2, v119, v2
	v_mul_f32_e32 v2, 0xbfb8aa3b, v2
	v_exp_f32_e32 v2, v2
	v_mul_f32_e32 v158, v154, v156
	v_add_f32_e32 v154, -1.0, v16
	v_fma_f32 v154, v63, v154, 1.0
	v_mul_f32_e32 v127, v154, v127
	v_mul_f32_e32 v159, v155, v156
	v_cvt_pk_bf16_f32 v127, v127, v97
	v_lshl_add_u64 v[154:155], s[96:97], 0, v[152:153]
	global_store_short v[154:155], v127, off
	v_add_f32_e32 v127, -1.0, v0
	v_fma_f32 v127, v62, v127, 1.0
	v_mul_f32_e32 v127, v127, v139
	v_or_b32_e32 v154, 64, v152
	v_mov_b32_e32 v155, v153
	v_cvt_pk_bf16_f32 v127, v127, v97
	v_lshl_add_u64 v[156:157], s[96:97], 0, v[154:155]
	global_store_short v[156:157], v127, off
	v_cvt_pk_bf16_f32 v127, v158, v97
	v_lshl_add_u64 v[156:157], s[30:31], 0, v[152:153]
	global_store_short v[156:157], v127, off
	v_cvt_pk_bf16_f32 v127, v159, v97
	v_lshl_add_u64 v[156:157], s[30:31], 0, v[154:155]
	v_mul_f32_e32 v16, v16, v158
	global_store_short v[156:157], v127, off
	v_cvt_pk_bf16_f32 v16, v16, v97
	v_lshl_add_u64 v[152:153], s[34:35], 0, v[152:153]
	v_mul_f32_e32 v0, v0, v159
	v_lshlrev_b32_e32 v127, 16, v143
	global_store_short v[152:153], v16, off
	v_cvt_pk_bf16_f32 v0, v0, v97
	v_lshl_add_u64 v[152:153], s[34:35], 0, v[154:155]
	v_lshlrev_b32_e32 v16, 16, v141
	v_mul_f32_e32 v139, v123, v127
	global_store_short v[152:153], v0, off
	v_add_f32_e32 v0, v125, v17
	v_mul_f32_e32 v17, v121, v16
	v_mul_f32_e32 v141, v139, v139
	v_fmac_f32_e32 v141, v17, v17
	v_mul_f32_e32 v0, 0xbfb8aa3b, v0
	v_exp_f32_e32 v0, v0
	v_add_f32_dpp v141, v141, v141 quad_perm:[1,0,3,2] row_mask:0xf bank_mask:0xf bound_ctrl:1
	v_add_f32_e32 v3, v119, v3
	v_mul_f32_e32 v3, 0xbfb8aa3b, v3
	v_add_f32_dpp v141, v141, v141 quad_perm:[2,3,0,1] row_mask:0xf bank_mask:0xf bound_ctrl:1
	v_add_f32_e32 v0, 1.0, v0
	v_exp_f32_e32 v3, v3
	v_add_f32_dpp v141, v141, v141 row_half_mirror row_mask:0xf bank_mask:0xf bound_ctrl:1
	v_add_f32_e32 v4, v119, v4
	v_mul_f32_e32 v4, 0xbfb8aa3b, v4
	v_add_f32_dpp v141, v141, v141 row_mirror row_mask:0xf bank_mask:0xf bound_ctrl:1
	ds_bpermute_b32 v143, v137, v141
	v_exp_f32_e32 v4, v4
	v_add_f32_e32 v5, v119, v5
	v_mul_f32_e32 v5, 0xbfb8aa3b, v5
	v_exp_f32_e32 v5, v5
	s_waitcnt lgkmcnt(0)
; __device__ __forceinline__ float bf1(bf16 h) { return __uint_as_float((unsigned)h << 16); }
; __device__ __forceinline__ bf16 f2bf(float f) { return (bf16)(pg8::cvt_pk_bf16(f, 0.f) & 0xffffu); }
; __device__ __forceinline__ float half32_sum(float v) { v = row16_sum(v); v += __shfl_xor(v, 16); return v; }
; __device__ __forceinline__ float sigmoid1(float x) { return __builtin_amdgcn_rcpf(1.0f + __expf(-x)); }
; __global__ void __launch_bounds__(NT, 2) mk_fwd(Args args) {
;     ...
;                     for (int hh = 0; hh < 2; ++hh) {
;                         const int colA = c0 + hh * 64 + (lane & 31), colB = colA + 32;
;                         const float a0A = a0p[colA], a0B = a0p[colB], kkA = kkw[colA], kkB = kkw[colB], kaA = kaw[colA], kaB = kaw[colB];
; #pragma unroll
;                         for (int r = 0; r < 16; ++r) { const int tl = (r & 3) + 8 * (r >> 2) + 4 * (lane >> 5); const int t = t0 + mt * 32 + tl;
;                             const float kA = bf1(Ks[tl * 1032 + colA]), kB = bf1(Ks[tl * 1032 + colB]);
;                             const float aA = sigmoid1(a0A + acc[hh * 2][r]), aB = sigmoid1(a0B + acc[hh * 2 + 1][r]);
;                             const float qA = kA * kkA, qB = kB * kkB;
;                             const float ss = half32_sum(qA * qA + qB * qB);
;                             const float inv = __builtin_amdgcn_rsqf(fmaxf(ss, 1e-24f));
;                             const float nA = qA * inv, nB = qB * inv;
;                             const size_t oA = (size_t)t * 1024 + colA, oB = oA + 32;
;                             KP[oA] = f2bf(kA * (1.0f + (aA - 1.0f) * kaA)); KP[oB] = f2bf(kB * (1.0f + (aB - 1.0f) * kaB));
;                             KKn[oA] = f2bf(nA); KKn[oB] = f2bf(nB); BB[oA] = f2bf(nA * aA); BB[oB] = f2bf(nB * aB);
;                             if ((r & 3) == 3) asm volatile("" ::: "memory"); }
;                     }
	v_add_f32_e32 v141, v141, v143
	v_max_f32_e32 v141, 0x179abe15, v141
	v_rsq_f32_e32 v141, v141
	v_rcp_f32_e32 v143, v0
	v_add_f32_e32 v0, 1.0, v1
	v_rcp_f32_e32 v152, v0
	v_mul_f32_e32 v153, v17, v141
	v_add_f32_e32 v17, -1.0, v143
	v_lshl_add_u64 v[0:1], v[32:33], 0, v[70:71]
	v_fma_f32 v17, v63, v17, 1.0
	v_mul_f32_e32 v16, v17, v16
	v_lshlrev_b64 v[0:1], 1, v[0:1]
	v_cvt_pk_bf16_f32 v32, v16, v97
	v_lshl_add_u64 v[16:17], s[96:97], 0, v[0:1]
	global_store_short v[16:17], v32, off
	v_add_f32_e32 v16, -1.0, v152
	v_fma_f32 v16, v62, v16, 1.0
	v_mul_f32_e32 v16, v16, v127
	v_cvt_pk_bf16_f32 v127, v16, v97
	v_or_b32_e32 v16, 64, v0
	v_mov_b32_e32 v17, v1
	v_lshl_add_u64 v[32:33], s[96:97], 0, v[16:17]
	global_store_short v[32:33], v127, off
	v_lshl_add_u64 v[32:33], s[30:31], 0, v[0:1]
	v_cvt_pk_bf16_f32 v127, v153, v97
	global_store_short v[32:33], v127, off
	v_lshl_add_u64 v[32:33], s[30:31], 0, v[16:17]
	v_mul_f32_e32 v139, v139, v141
	v_cvt_pk_bf16_f32 v127, v139, v97
	global_store_short v[32:33], v127, off
	v_mul_f32_e32 v32, v143, v153
	v_lshl_add_u64 v[0:1], s[34:35], 0, v[0:1]
	v_cvt_pk_bf16_f32 v32, v32, v97
	global_store_short v[0:1], v32, off
	v_mul_f32_e32 v0, v152, v139
	v_cvt_pk_bf16_f32 v32, v0, v97
	v_lshl_add_u64 v[0:1], s[34:35], 0, v[16:17]
	global_store_short v[0:1], v32, off
	v_lshlrev_b32_e32 v32, 16, v147
	v_lshlrev_b32_e32 v16, 16, v145
	v_mul_f32_e32 v17, v123, v32
	v_add_f32_e32 v0, v125, v18
	v_mul_f32_e32 v1, v121, v16
	v_mul_f32_e32 v18, v17, v17
	v_fmac_f32_e32 v18, v1, v1
	v_mul_f32_e32 v0, 0xbfb8aa3b, v0
	v_exp_f32_e32 v0, v0
	v_add_f32_dpp v18, v18, v18 quad_perm:[1,0,3,2] row_mask:0xf bank_mask:0xf bound_ctrl:1
	v_add_f32_e32 v6, v119, v6
	v_mul_f32_e32 v6, 0xbfb8aa3b, v6
	v_add_f32_dpp v18, v18, v18 quad_perm:[2,3,0,1] row_mask:0xf bank_mask:0xf bound_ctrl:1
	v_add_f32_e32 v0, 1.0, v0
	v_rcp_f32_e32 v127, v0
	v_add_f32_dpp v18, v18, v18 row_half_mirror row_mask:0xf bank_mask:0xf bound_ctrl:1
	v_add_f32_e32 v0, 1.0, v2
	v_rcp_f32_e32 v2, v0
	v_add_f32_dpp v18, v18, v18 row_mirror row_mask:0xf bank_mask:0xf bound_ctrl:1
	ds_bpermute_b32 v33, v137, v18
	v_exp_f32_e32 v6, v6
	v_add_f32_e32 v7, v119, v7
	v_mul_f32_e32 v7, 0xbfb8aa3b, v7
	v_exp_f32_e32 v7, v7
	s_waitcnt lgkmcnt(0)
	v_add_f32_e32 v18, v18, v33
	v_max_f32_e32 v18, 0x179abe15, v18
	v_rsq_f32_e32 v18, v18
	v_add_f32_e32 v8, v119, v8
	v_mul_f32_e32 v8, 0xbfb8aa3b, v8
	v_exp_f32_e32 v8, v8
	v_mul_f32_e32 v139, v1, v18
	v_mul_f32_e32 v18, v17, v18
	v_add_f32_e32 v17, -1.0, v127
	v_lshl_add_u64 v[0:1], v[48:49], 0, v[70:71]
	v_fma_f32 v17, v63, v17, 1.0
	v_mul_f32_e32 v16, v17, v16
	v_lshlrev_b64 v[0:1], 1, v[0:1]
	v_cvt_pk_bf16_f32 v33, v16, v97
	v_lshl_add_u64 v[16:17], s[96:97], 0, v[0:1]
	global_store_short v[16:17], v33, off
	v_add_f32_e32 v16, -1.0, v2
	v_fma_f32 v16, v62, v16, 1.0
	v_mul_f32_e32 v16, v16, v32
	v_cvt_pk_bf16_f32 v48, v16, v97
	v_or_b32_e32 v16, 64, v0
	v_mov_b32_e32 v17, v1
	v_lshl_add_u64 v[32:33], s[96:97], 0, v[16:17]
	global_store_short v[32:33], v48, off
	v_lshl_add_u64 v[32:33], s[30:31], 0, v[0:1]
	v_cvt_pk_bf16_f32 v48, v139, v97
	global_store_short v[32:33], v48, off
	v_lshl_add_u64 v[32:33], s[30:31], 0, v[16:17]
	v_cvt_pk_bf16_f32 v48, v18, v97
	global_store_short v[32:33], v48, off
	v_mul_f32_e32 v32, v127, v139
	v_lshl_add_u64 v[0:1], s[34:35], 0, v[0:1]
	v_cvt_pk_bf16_f32 v32, v32, v97
	global_store_short v[0:1], v32, off
	v_mul_f32_e32 v0, v2, v18
	v_cvt_pk_bf16_f32 v2, v0, v97
	v_lshl_add_u64 v[0:1], s[34:35], 0, v[16:17]
	v_lshlrev_b32_e32 v16, 16, v151
	global_store_short v[0:1], v2, off
	v_lshlrev_b32_e32 v2, 16, v149
	v_mul_f32_e32 v17, v123, v16
	v_mul_f32_e32 v1, v121, v2
	v_mul_f32_e32 v18, v17, v17
	v_fmac_f32_e32 v18, v1, v1
	v_add_f32_e32 v0, v125, v19
	v_mul_f32_e32 v0, 0xbfb8aa3b, v0
	v_add_f32_dpp v18, v18, v18 quad_perm:[1,0,3,2] row_mask:0xf bank_mask:0xf bound_ctrl:1
	v_exp_f32_e32 v0, v0
	v_add_f32_e32 v12, v119, v12
	v_add_f32_dpp v18, v18, v18 quad_perm:[2,3,0,1] row_mask:0xf bank_mask:0xf bound_ctrl:1
	v_mul_f32_e32 v12, 0xbfb8aa3b, v12
	v_add_f32_e32 v0, 1.0, v0
	v_add_f32_dpp v18, v18, v18 row_half_mirror row_mask:0xf bank_mask:0xf bound_ctrl:1
	v_exp_f32_e32 v12, v12
	s_nop 0
	v_add_f32_dpp v18, v18, v18 row_mirror row_mask:0xf bank_mask:0xf bound_ctrl:1
	ds_bpermute_b32 v19, v137, v18
	s_waitcnt lgkmcnt(0)
	v_add_f32_e32 v18, v18, v19
	v_max_f32_e32 v18, 0x179abe15, v18
	v_rcp_f32_e32 v19, v0
	v_rsq_f32_e32 v18, v18
	v_add_f32_e32 v0, 1.0, v3
	v_rcp_f32_e32 v32, v0
	v_add_f32_e32 v3, -1.0, v19
	v_mul_f32_e32 v33, v1, v18
	v_lshl_add_u64 v[0:1], v[34:35], 0, v[70:71]
	v_fma_f32 v3, v63, v3, 1.0
	v_mul_f32_e32 v2, v3, v2
	v_lshlrev_b64 v[0:1], 1, v[0:1]
	v_mul_f32_e32 v18, v17, v18
	v_cvt_pk_bf16_f32 v17, v2, v97
	v_lshl_add_u64 v[2:3], s[96:97], 0, v[0:1]
	global_store_short v[2:3], v17, off
	v_add_f32_e32 v2, -1.0, v32
	v_fma_f32 v2, v62, v2, 1.0
	v_mul_f32_e32 v2, v2, v16
	v_cvt_pk_bf16_f32 v34, v2, v97
	v_or_b32_e32 v2, 64, v0
	v_mov_b32_e32 v3, v1
	v_lshl_add_u64 v[16:17], s[96:97], 0, v[2:3]
	global_store_short v[16:17], v34, off
	v_lshl_add_u64 v[16:17], s[30:31], 0, v[0:1]
	v_cvt_pk_bf16_f32 v34, v33, v97
	global_store_short v[16:17], v34, off
	v_lshl_add_u64 v[16:17], s[30:31], 0, v[2:3]
	v_cvt_pk_bf16_f32 v34, v18, v97
	global_store_short v[16:17], v34, off
	v_mul_f32_e32 v16, v19, v33
	v_lshl_add_u64 v[0:1], s[34:35], 0, v[0:1]
	v_cvt_pk_bf16_f32 v16, v16, v97
	global_store_short v[0:1], v16, off
	v_mul_f32_e32 v0, v32, v18
	v_cvt_pk_bf16_f32 v16, v0, v97
	v_lshl_add_u64 v[0:1], s[34:35], 0, v[2:3]
	global_store_short v[0:1], v16, off
	ds_read_u16 v0, v179 offset:41088
	ds_read_u16 v1, v179 offset:41152
	ds_read_u16 v18, v181 offset:41088
	ds_read_u16 v19, v181 offset:41152
	ds_read_u16 v32, v183 offset:41088
	ds_read_u16 v33, v183 offset:41152
	ds_read_u16 v34, v185 offset:41088
	ds_read_u16 v35, v185 offset:41152
	s_waitcnt lgkmcnt(6)
; __device__ __forceinline__ float bf1(bf16 h) { return __uint_as_float((unsigned)h << 16); }
; __device__ __forceinline__ bf16 f2bf(float f) { return (bf16)(pg8::cvt_pk_bf16(f, 0.f) & 0xffffu); }
; __device__ __forceinline__ float half32_sum(float v) { v = row16_sum(v); v += __shfl_xor(v, 16); return v; }
; __device__ __forceinline__ float sigmoid1(float x) { return __builtin_amdgcn_rcpf(1.0f + __expf(-x)); }
; #define RW_ZERO() do { _Pragma("unroll") for (int b_ = 0; b_ < 4; ++b_) _Pragma("unroll") for (int r_ = 0; r_ < 16; ++r_) acc[b_][r_] = 0.f; } while (0)
; __global__ void __launch_bounds__(NT, 2) mk_fwd(Args args) {
;     ...
;                     for (int hh = 0; hh < 2; ++hh) {
;                         const int colA = c0 + hh * 64 + (lane & 31), colB = colA + 32;
;                         const float a0A = a0p[colA], a0B = a0p[colB], kkA = kkw[colA], kkB = kkw[colB], kaA = kaw[colA], kaB = kaw[colB];
; #pragma unroll
;                         for (int r = 0; r < 16; ++r) { const int tl = (r & 3) + 8 * (r >> 2) + 4 * (lane >> 5); const int t = t0 + mt * 32 + tl;
;                             const float kA = bf1(Ks[tl * 1032 + colA]), kB = bf1(Ks[tl * 1032 + colB]);
;                             const float aA = sigmoid1(a0A + acc[hh * 2][r]), aB = sigmoid1(a0B + acc[hh * 2 + 1][r]);
;                             const float qA = kA * kkA, qB = kB * kkB;
;                             const float ss = half32_sum(qA * qA + qB * qB);
;                             const float inv = __builtin_amdgcn_rsqf(fmaxf(ss, 1e-24f));
;                             const float nA = qA * inv, nB = qB * inv;
;                             const size_t oA = (size_t)t * 1024 + colA, oB = oA + 32;
;                             KP[oA] = f2bf(kA * (1.0f + (aA - 1.0f) * kaA)); KP[oB] = f2bf(kB * (1.0f + (aB - 1.0f) * kaB));
;                             KKn[oA] = f2bf(nA); KKn[oB] = f2bf(nB); BB[oA] = f2bf(nA * aA); BB[oB] = f2bf(nB * aB);
;                             if ((r & 3) == 3) asm volatile("" ::: "memory"); }
;                     }
;                     RW_ZERO(); RW_MM(G2T, 160, 128, 10);
	v_lshlrev_b32_e32 v16, 16, v1
	v_lshlrev_b32_e32 v2, 16, v0
	v_mul_f32_e32 v3, v123, v16
	v_mul_f32_e32 v1, v121, v2
	v_mul_f32_e32 v17, v3, v3
	v_fmac_f32_e32 v17, v1, v1
	v_add_f32_e32 v0, v125, v20
	v_mul_f32_e32 v0, 0xbfb8aa3b, v0
	v_add_f32_dpp v17, v17, v17 quad_perm:[1,0,3,2] row_mask:0xf bank_mask:0xf bound_ctrl:1
	v_exp_f32_e32 v0, v0
	s_nop 0
	v_add_f32_dpp v17, v17, v17 quad_perm:[2,3,0,1] row_mask:0xf bank_mask:0xf bound_ctrl:1
	v_add_f32_e32 v0, 1.0, v0
	s_nop 0
	v_add_f32_dpp v17, v17, v17 row_half_mirror row_mask:0xf bank_mask:0xf bound_ctrl:1
	s_nop 1
	v_add_f32_dpp v17, v17, v17 row_mirror row_mask:0xf bank_mask:0xf bound_ctrl:1
	ds_bpermute_b32 v20, v137, v17
	s_waitcnt lgkmcnt(0)
	v_add_f32_e32 v17, v17, v20
	v_max_f32_e32 v17, 0x179abe15, v17
	v_rsq_f32_e32 v17, v17
	v_rcp_f32_e32 v20, v0
	v_add_f32_e32 v0, 1.0, v4
	v_rcp_f32_e32 v4, v0
	v_mul_f32_e32 v49, v3, v17
	v_add_f32_e32 v3, -1.0, v20
	v_mul_f32_e32 v48, v1, v17
	v_lshl_add_u64 v[0:1], v[50:51], 0, v[70:71]
	v_fma_f32 v3, v63, v3, 1.0
	v_mul_f32_e32 v2, v3, v2
	v_lshlrev_b64 v[0:1], 1, v[0:1]
	v_cvt_pk_bf16_f32 v17, v2, v97
	v_lshl_add_u64 v[2:3], s[96:97], 0, v[0:1]
	global_store_short v[2:3], v17, off
	v_add_f32_e32 v2, -1.0, v4
	v_fma_f32 v2, v62, v2, 1.0
	v_mul_f32_e32 v2, v2, v16
	v_cvt_pk_bf16_f32 v50, v2, v97
	v_or_b32_e32 v2, 64, v0
	v_mov_b32_e32 v3, v1
	v_lshl_add_u64 v[16:17], s[96:97], 0, v[2:3]
	global_store_short v[16:17], v50, off
	v_lshl_add_u64 v[16:17], s[30:31], 0, v[0:1]
	v_cvt_pk_bf16_f32 v50, v48, v97
	global_store_short v[16:17], v50, off
	v_lshl_add_u64 v[16:17], s[30:31], 0, v[2:3]
	v_cvt_pk_bf16_f32 v50, v49, v97
	global_store_short v[16:17], v50, off
	v_mul_f32_e32 v16, v20, v48
	v_lshl_add_u64 v[0:1], s[34:35], 0, v[0:1]
	v_cvt_pk_bf16_f32 v16, v16, v97
	global_store_short v[0:1], v16, off
	v_mul_f32_e32 v0, v4, v49
	v_cvt_pk_bf16_f32 v4, v0, v97
	v_lshl_add_u64 v[0:1], s[34:35], 0, v[2:3]
	global_store_short v[0:1], v4, off
	v_lshlrev_b32_e32 v4, 16, v19
	v_lshlrev_b32_e32 v2, 16, v18
	v_mul_f32_e32 v3, v123, v4
	v_mul_f32_e32 v1, v121, v2
	v_mul_f32_e32 v16, v3, v3
	v_fmac_f32_e32 v16, v1, v1
	v_add_f32_e32 v0, v125, v21
	v_mul_f32_e32 v0, 0xbfb8aa3b, v0
	v_add_f32_dpp v16, v16, v16 quad_perm:[1,0,3,2] row_mask:0xf bank_mask:0xf bound_ctrl:1
	v_exp_f32_e32 v0, v0
	v_mov_b32_e32 v48, 0
	v_add_f32_dpp v16, v16, v16 quad_perm:[2,3,0,1] row_mask:0xf bank_mask:0xf bound_ctrl:1
	v_mov_b32_e32 v49, v48
	v_add_f32_e32 v0, 1.0, v0
	v_add_f32_dpp v16, v16, v16 row_half_mirror row_mask:0xf bank_mask:0xf bound_ctrl:1
	v_mov_b32_e32 v50, v48
	v_mov_b32_e32 v51, v48
	v_add_f32_dpp v16, v16, v16 row_mirror row_mask:0xf bank_mask:0xf bound_ctrl:1
	ds_bpermute_b32 v17, v137, v16
	s_waitcnt lgkmcnt(0)
	v_add_f32_e32 v16, v16, v17
	v_max_f32_e32 v16, 0x179abe15, v16
	v_rsq_f32_e32 v16, v16
	v_rcp_f32_e32 v17, v0
	v_add_f32_e32 v0, 1.0, v5
	v_rcp_f32_e32 v18, v0
	v_mul_f32_e32 v19, v1, v16
	v_mul_f32_e32 v16, v3, v16
	v_add_f32_e32 v3, -1.0, v17
	v_lshl_add_u64 v[0:1], v[36:37], 0, v[70:71]
	v_fma_f32 v3, v63, v3, 1.0
	v_mul_f32_e32 v2, v3, v2
	v_lshlrev_b64 v[0:1], 1, v[0:1]
	v_cvt_pk_bf16_f32 v5, v2, v97
	v_lshl_add_u64 v[2:3], s[96:97], 0, v[0:1]
	global_store_short v[2:3], v5, off
	v_add_f32_e32 v2, -1.0, v18
	v_fma_f32 v2, v62, v2, 1.0
	v_mul_f32_e32 v2, v2, v4
	v_cvt_pk_bf16_f32 v20, v2, v97
	v_or_b32_e32 v2, 64, v0
	v_mov_b32_e32 v3, v1
	v_lshl_add_u64 v[4:5], s[96:97], 0, v[2:3]
	global_store_short v[4:5], v20, off
	v_lshl_add_u64 v[4:5], s[30:31], 0, v[0:1]
	v_cvt_pk_bf16_f32 v20, v19, v97
	global_store_short v[4:5], v20, off
	v_lshl_add_u64 v[4:5], s[30:31], 0, v[2:3]
	v_cvt_pk_bf16_f32 v20, v16, v97
	global_store_short v[4:5], v20, off
	v_mul_f32_e32 v4, v17, v19
	v_lshl_add_u64 v[0:1], s[34:35], 0, v[0:1]
	v_cvt_pk_bf16_f32 v4, v4, v97
	global_store_short v[0:1], v4, off
	v_mul_f32_e32 v0, v18, v16
	v_cvt_pk_bf16_f32 v4, v0, v97
	v_lshl_add_u64 v[0:1], s[34:35], 0, v[2:3]
	global_store_short v[0:1], v4, off
	v_lshlrev_b32_e32 v4, 16, v33
	v_lshlrev_b32_e32 v2, 16, v32
	v_mul_f32_e32 v3, v123, v4
	v_mul_f32_e32 v1, v121, v2
	v_mul_f32_e32 v5, v3, v3
	v_fmac_f32_e32 v5, v1, v1
	v_add_f32_e32 v0, v125, v22
	v_mul_f32_e32 v0, 0xbfb8aa3b, v0
	v_add_f32_dpp v5, v5, v5 quad_perm:[1,0,3,2] row_mask:0xf bank_mask:0xf bound_ctrl:1
	v_exp_f32_e32 v0, v0
	v_mov_b32_e32 v32, v48
	v_add_f32_dpp v5, v5, v5 quad_perm:[2,3,0,1] row_mask:0xf bank_mask:0xf bound_ctrl:1
	v_mov_b32_e32 v33, v48
	v_add_f32_e32 v0, 1.0, v0
	v_add_f32_dpp v5, v5, v5 row_half_mirror row_mask:0xf bank_mask:0xf bound_ctrl:1
	v_mov_b32_e32 v36, v48
	v_mov_b32_e32 v37, v48
	v_add_f32_dpp v5, v5, v5 row_mirror row_mask:0xf bank_mask:0xf bound_ctrl:1
	ds_bpermute_b32 v16, v137, v5
	s_waitcnt lgkmcnt(0)
; __device__ __forceinline__ float bf1(bf16 h) { return __uint_as_float((unsigned)h << 16); }
; __device__ __forceinline__ bf16 f2bf(float f) { return (bf16)(pg8::cvt_pk_bf16(f, 0.f) & 0xffffu); }
; __device__ __forceinline__ float half32_sum(float v) { v = row16_sum(v); v += __shfl_xor(v, 16); return v; }
; __device__ __forceinline__ float sigmoid1(float x) { return __builtin_amdgcn_rcpf(1.0f + __expf(-x)); }
; #define RW_ZERO() do { _Pragma("unroll") for (int b_ = 0; b_ < 4; ++b_) _Pragma("unroll") for (int r_ = 0; r_ < 16; ++r_) acc[b_][r_] = 0.f; } while (0)
; __global__ void __launch_bounds__(NT, 2) mk_fwd(Args args) {
;     ...
;                     for (int hh = 0; hh < 2; ++hh) {
;                         const int colA = c0 + hh * 64 + (lane & 31), colB = colA + 32;
;                         const float a0A = a0p[colA], a0B = a0p[colB], kkA = kkw[colA], kkB = kkw[colB], kaA = kaw[colA], kaB = kaw[colB];
; #pragma unroll
;                         for (int r = 0; r < 16; ++r) { const int tl = (r & 3) + 8 * (r >> 2) + 4 * (lane >> 5); const int t = t0 + mt * 32 + tl;
;                             const float kA = bf1(Ks[tl * 1032 + colA]), kB = bf1(Ks[tl * 1032 + colB]);
;                             const float aA = sigmoid1(a0A + acc[hh * 2][r]), aB = sigmoid1(a0B + acc[hh * 2 + 1][r]);
;                             const float qA = kA * kkA, qB = kB * kkB;
;                             const float ss = half32_sum(qA * qA + qB * qB);
;                             const float inv = __builtin_amdgcn_rsqf(fmaxf(ss, 1e-24f));
;                             const float nA = qA * inv, nB = qB * inv;
;                             const size_t oA = (size_t)t * 1024 + colA, oB = oA + 32;
;                             KP[oA] = f2bf(kA * (1.0f + (aA - 1.0f) * kaA)); KP[oB] = f2bf(kB * (1.0f + (aB - 1.0f) * kaB));
;                             KKn[oA] = f2bf(nA); KKn[oB] = f2bf(nB); BB[oA] = f2bf(nA * aA); BB[oB] = f2bf(nB * aB);
;                             if ((r & 3) == 3) asm volatile("" ::: "memory"); }
;                     }
;                     RW_ZERO(); RW_MM(G2T, 160, 128, 10);
	v_add_f32_e32 v5, v5, v16
	v_max_f32_e32 v5, 0x179abe15, v5
	v_rsq_f32_e32 v5, v5
	v_rcp_f32_e32 v16, v0
	v_add_f32_e32 v0, 1.0, v6
	v_rcp_f32_e32 v6, v0
	v_mul_f32_e32 v18, v3, v5
	v_add_f32_e32 v3, -1.0, v16
	v_mul_f32_e32 v17, v1, v5
	v_lshl_add_u64 v[0:1], v[52:53], 0, v[70:71]
	v_fma_f32 v3, v63, v3, 1.0
	v_mul_f32_e32 v2, v3, v2
	v_lshlrev_b64 v[0:1], 1, v[0:1]
	v_cvt_pk_bf16_f32 v5, v2, v97
	v_lshl_add_u64 v[2:3], s[96:97], 0, v[0:1]
	global_store_short v[2:3], v5, off
	v_add_f32_e32 v2, -1.0, v6
	v_fma_f32 v2, v62, v2, 1.0
	v_mul_f32_e32 v2, v2, v4
	v_cvt_pk_bf16_f32 v19, v2, v97
	v_or_b32_e32 v2, 64, v0
	v_mov_b32_e32 v3, v1
	v_lshl_add_u64 v[4:5], s[96:97], 0, v[2:3]
	global_store_short v[4:5], v19, off
	v_lshl_add_u64 v[4:5], s[30:31], 0, v[0:1]
	v_cvt_pk_bf16_f32 v19, v17, v97
	global_store_short v[4:5], v19, off
	v_lshl_add_u64 v[4:5], s[30:31], 0, v[2:3]
	v_cvt_pk_bf16_f32 v19, v18, v97
	global_store_short v[4:5], v19, off
	v_mul_f32_e32 v4, v16, v17
	v_lshl_add_u64 v[0:1], s[34:35], 0, v[0:1]
	v_cvt_pk_bf16_f32 v4, v4, v97
	global_store_short v[0:1], v4, off
	v_mul_f32_e32 v0, v6, v18
	v_cvt_pk_bf16_f32 v4, v0, v97
	v_lshl_add_u64 v[0:1], s[34:35], 0, v[2:3]
	global_store_short v[0:1], v4, off
	v_lshlrev_b32_e32 v4, 16, v35
	v_lshlrev_b32_e32 v2, 16, v34
	v_mul_f32_e32 v3, v123, v4
	v_mul_f32_e32 v1, v121, v2
	v_mul_f32_e32 v5, v3, v3
	v_fmac_f32_e32 v5, v1, v1
	v_add_f32_e32 v0, v125, v23
	v_mul_f32_e32 v0, 0xbfb8aa3b, v0
	v_add_f32_dpp v5, v5, v5 quad_perm:[1,0,3,2] row_mask:0xf bank_mask:0xf bound_ctrl:1
	v_exp_f32_e32 v0, v0
	v_mov_b32_e32 v52, v48
	v_add_f32_dpp v5, v5, v5 quad_perm:[2,3,0,1] row_mask:0xf bank_mask:0xf bound_ctrl:1
	v_mov_b32_e32 v53, v48
	v_add_f32_e32 v0, 1.0, v0
	v_add_f32_dpp v5, v5, v5 row_half_mirror row_mask:0xf bank_mask:0xf bound_ctrl:1
	v_mov_b32_e32 v34, v48
	v_mov_b32_e32 v35, v48
	v_add_f32_dpp v5, v5, v5 row_mirror row_mask:0xf bank_mask:0xf bound_ctrl:1
	ds_bpermute_b32 v6, v137, v5
	s_waitcnt lgkmcnt(0)
	v_add_f32_e32 v5, v5, v6
	v_max_f32_e32 v5, 0x179abe15, v5
	v_rsq_f32_e32 v5, v5
	v_rcp_f32_e32 v6, v0
	v_add_f32_e32 v0, 1.0, v7
	v_rcp_f32_e32 v7, v0
	v_mul_f32_e32 v17, v3, v5
	v_add_f32_e32 v3, -1.0, v6
	v_mul_f32_e32 v16, v1, v5
	v_lshl_add_u64 v[0:1], v[38:39], 0, v[70:71]
	v_fma_f32 v3, v63, v3, 1.0
	v_mul_f32_e32 v2, v3, v2
	v_lshlrev_b64 v[0:1], 1, v[0:1]
	v_cvt_pk_bf16_f32 v5, v2, v97
	v_lshl_add_u64 v[2:3], s[96:97], 0, v[0:1]
	global_store_short v[2:3], v5, off
	v_add_f32_e32 v2, -1.0, v7
	v_fma_f32 v2, v62, v2, 1.0
	v_mul_f32_e32 v2, v2, v4
	v_cvt_pk_bf16_f32 v18, v2, v97
	v_or_b32_e32 v2, 64, v0
	v_mov_b32_e32 v3, v1
	v_lshl_add_u64 v[4:5], s[96:97], 0, v[2:3]
	global_store_short v[4:5], v18, off
	v_lshl_add_u64 v[4:5], s[30:31], 0, v[0:1]
	v_cvt_pk_bf16_f32 v18, v16, v97
	global_store_short v[4:5], v18, off
	v_lshl_add_u64 v[4:5], s[30:31], 0, v[2:3]
	v_cvt_pk_bf16_f32 v18, v17, v97
	global_store_short v[4:5], v18, off
	v_mul_f32_e32 v4, v6, v16
	v_lshl_add_u64 v[0:1], s[34:35], 0, v[0:1]
	v_cvt_pk_bf16_f32 v4, v4, v97
	global_store_short v[0:1], v4, off
	v_mul_f32_e32 v0, v7, v17
	v_cvt_pk_bf16_f32 v4, v0, v97
	v_lshl_add_u64 v[0:1], s[34:35], 0, v[2:3]
	global_store_short v[0:1], v4, off
	ds_read_u16 v0, v187 offset:41088
	ds_read_u16 v1, v187 offset:41152
	ds_read_u16 v6, v189 offset:41088
	ds_read_u16 v7, v189 offset:41152
	ds_read_u16 v16, v191 offset:41088
	ds_read_u16 v17, v191 offset:41152
	ds_read_u16 v18, v193 offset:41088
	ds_read_u16 v19, v193 offset:41152
	s_waitcnt lgkmcnt(6)
	v_lshlrev_b32_e32 v4, 16, v1
	v_lshlrev_b32_e32 v2, 16, v0
	v_mul_f32_e32 v3, v123, v4
	v_mul_f32_e32 v1, v121, v2
	v_mul_f32_e32 v5, v3, v3
	v_fmac_f32_e32 v5, v1, v1
	v_add_f32_e32 v0, v125, v24
	v_mul_f32_e32 v0, 0xbfb8aa3b, v0
	v_add_f32_dpp v5, v5, v5 quad_perm:[1,0,3,2] row_mask:0xf bank_mask:0xf bound_ctrl:1
	v_exp_f32_e32 v0, v0
	v_mov_b32_e32 v38, v48
	v_add_f32_dpp v5, v5, v5 quad_perm:[2,3,0,1] row_mask:0xf bank_mask:0xf bound_ctrl:1
	v_mov_b32_e32 v39, v48
	v_add_f32_e32 v0, 1.0, v0
	v_add_f32_dpp v5, v5, v5 row_half_mirror row_mask:0xf bank_mask:0xf bound_ctrl:1
	v_mov_b32_e32 v24, v48
	s_nop 0
	v_add_f32_dpp v5, v5, v5 row_mirror row_mask:0xf bank_mask:0xf bound_ctrl:1
	ds_bpermute_b32 v20, v137, v5
	s_waitcnt lgkmcnt(0)
	v_add_f32_e32 v5, v5, v20
	v_max_f32_e32 v5, 0x179abe15, v5
	v_rsq_f32_e32 v5, v5
	v_rcp_f32_e32 v20, v0
	v_add_f32_e32 v0, 1.0, v8
	v_rcp_f32_e32 v8, v0
	v_mul_f32_e32 v22, v3, v5
	v_add_f32_e32 v3, -1.0, v20
	v_mul_f32_e32 v21, v1, v5
	v_lshl_add_u64 v[0:1], v[54:55], 0, v[70:71]
	v_fma_f32 v3, v63, v3, 1.0
	v_mul_f32_e32 v2, v3, v2
	v_lshlrev_b64 v[0:1], 1, v[0:1]
	v_cvt_pk_bf16_f32 v5, v2, v97
	v_lshl_add_u64 v[2:3], s[96:97], 0, v[0:1]
	global_store_short v[2:3], v5, off
	v_add_f32_e32 v2, -1.0, v8
	v_fma_f32 v2, v62, v2, 1.0
	v_mul_f32_e32 v2, v2, v4
	v_cvt_pk_bf16_f32 v23, v2, v97
	v_or_b32_e32 v2, 64, v0
	v_mov_b32_e32 v3, v1
	v_lshl_add_u64 v[4:5], s[96:97], 0, v[2:3]
	global_store_short v[4:5], v23, off
	v_lshl_add_u64 v[4:5], s[30:31], 0, v[0:1]
	v_cvt_pk_bf16_f32 v23, v21, v97
	global_store_short v[4:5], v23, off
	v_lshl_add_u64 v[4:5], s[30:31], 0, v[2:3]
	v_cvt_pk_bf16_f32 v23, v22, v97
	global_store_short v[4:5], v23, off
	v_mul_f32_e32 v4, v20, v21
	v_lshl_add_u64 v[0:1], s[34:35], 0, v[0:1]
	v_cvt_pk_bf16_f32 v4, v4, v97
	global_store_short v[0:1], v4, off
	v_mul_f32_e32 v0, v8, v22
	v_cvt_pk_bf16_f32 v4, v0, v97
	v_lshl_add_u64 v[0:1], s[34:35], 0, v[2:3]
	global_store_short v[0:1], v4, off
	v_lshlrev_b32_e32 v4, 16, v7
	v_lshlrev_b32_e32 v2, 16, v6
	v_mul_f32_e32 v3, v123, v4
	v_mul_f32_e32 v1, v121, v2
	v_mul_f32_e32 v5, v3, v3
	v_fmac_f32_e32 v5, v1, v1
	v_add_f32_e32 v0, v125, v25
	v_mul_f32_e32 v0, 0xbfb8aa3b, v0
	v_add_f32_dpp v5, v5, v5 quad_perm:[1,0,3,2] row_mask:0xf bank_mask:0xf bound_ctrl:1
	v_exp_f32_e32 v0, v0
	v_add_f32_e32 v7, v119, v9
	v_add_f32_dpp v5, v5, v5 quad_perm:[2,3,0,1] row_mask:0xf bank_mask:0xf bound_ctrl:1
	v_mul_f32_e32 v7, 0xbfb8aa3b, v7
	v_add_f32_e32 v0, 1.0, v0
	v_add_f32_dpp v5, v5, v5 row_half_mirror row_mask:0xf bank_mask:0xf bound_ctrl:1
	v_exp_f32_e32 v7, v7
	v_mov_b32_e32 v54, v48
	v_add_f32_dpp v5, v5, v5 row_mirror row_mask:0xf bank_mask:0xf bound_ctrl:1
	ds_bpermute_b32 v6, v137, v5
	v_mov_b32_e32 v55, v48
	v_mov_b32_e32 v21, v48
	v_mov_b32_e32 v22, v48
	v_mov_b32_e32 v23, v48
	s_waitcnt lgkmcnt(0)
; __device__ __forceinline__ float bf1(bf16 h) { return __uint_as_float((unsigned)h << 16); }
; __device__ __forceinline__ bf16 f2bf(float f) { return (bf16)(pg8::cvt_pk_bf16(f, 0.f) & 0xffffu); }
; __device__ __forceinline__ float half32_sum(float v) { v = row16_sum(v); v += __shfl_xor(v, 16); return v; }
; __device__ __forceinline__ float sigmoid1(float x) { return __builtin_amdgcn_rcpf(1.0f + __expf(-x)); }
; #define RW_ZERO() do { _Pragma("unroll") for (int b_ = 0; b_ < 4; ++b_) _Pragma("unroll") for (int r_ = 0; r_ < 16; ++r_) acc[b_][r_] = 0.f; } while (0)
; __global__ void __launch_bounds__(NT, 2) mk_fwd(Args args) {
;     ...
;                     for (int hh = 0; hh < 2; ++hh) {
;                         const int colA = c0 + hh * 64 + (lane & 31), colB = colA + 32;
;                         const float a0A = a0p[colA], a0B = a0p[colB], kkA = kkw[colA], kkB = kkw[colB], kaA = kaw[colA], kaB = kaw[colB];
; #pragma unroll
;                         for (int r = 0; r < 16; ++r) { const int tl = (r & 3) + 8 * (r >> 2) + 4 * (lane >> 5); const int t = t0 + mt * 32 + tl;
;                             const float kA = bf1(Ks[tl * 1032 + colA]), kB = bf1(Ks[tl * 1032 + colB]);
;                             const float aA = sigmoid1(a0A + acc[hh * 2][r]), aB = sigmoid1(a0B + acc[hh * 2 + 1][r]);
;                             const float qA = kA * kkA, qB = kB * kkB;
;                             const float ss = half32_sum(qA * qA + qB * qB);
;                             const float inv = __builtin_amdgcn_rsqf(fmaxf(ss, 1e-24f));
;                             const float nA = qA * inv, nB = qB * inv;
;                             const size_t oA = (size_t)t * 1024 + colA, oB = oA + 32;
;                             KP[oA] = f2bf(kA * (1.0f + (aA - 1.0f) * kaA)); KP[oB] = f2bf(kB * (1.0f + (aB - 1.0f) * kaB));
;                             KKn[oA] = f2bf(nA); KKn[oB] = f2bf(nB); BB[oA] = f2bf(nA * aA); BB[oB] = f2bf(nB * aB);
;                             if ((r & 3) == 3) asm volatile("" ::: "memory"); }
;                     }
;                     RW_ZERO(); RW_MM(G2T, 160, 128, 10);
	v_add_f32_e32 v5, v5, v6
	v_max_f32_e32 v5, 0x179abe15, v5
	v_rsq_f32_e32 v5, v5
	v_rcp_f32_e32 v6, v0
	v_add_f32_e32 v0, 1.0, v7
	v_rcp_f32_e32 v7, v0
	v_mul_f32_e32 v9, v3, v5
	v_add_f32_e32 v3, -1.0, v6
	v_mul_f32_e32 v8, v1, v5
	v_lshl_add_u64 v[0:1], v[40:41], 0, v[70:71]
	v_fma_f32 v3, v63, v3, 1.0
	v_mul_f32_e32 v2, v3, v2
	v_lshlrev_b64 v[0:1], 1, v[0:1]
	v_cvt_pk_bf16_f32 v5, v2, v97
	v_lshl_add_u64 v[2:3], s[96:97], 0, v[0:1]
	global_store_short v[2:3], v5, off
	v_add_f32_e32 v2, -1.0, v7
	v_fma_f32 v2, v62, v2, 1.0
	v_mul_f32_e32 v2, v2, v4
	v_cvt_pk_bf16_f32 v20, v2, v97
	v_or_b32_e32 v2, 64, v0
	v_mov_b32_e32 v3, v1
	v_lshl_add_u64 v[4:5], s[96:97], 0, v[2:3]
	global_store_short v[4:5], v20, off
	v_lshl_add_u64 v[4:5], s[30:31], 0, v[0:1]
	v_cvt_pk_bf16_f32 v20, v8, v97
	global_store_short v[4:5], v20, off
	v_lshl_add_u64 v[4:5], s[30:31], 0, v[2:3]
	v_cvt_pk_bf16_f32 v20, v9, v97
	global_store_short v[4:5], v20, off
	v_mul_f32_e32 v4, v6, v8
	v_lshl_add_u64 v[0:1], s[34:35], 0, v[0:1]
	v_cvt_pk_bf16_f32 v4, v4, v97
	global_store_short v[0:1], v4, off
	v_mul_f32_e32 v0, v7, v9
	v_cvt_pk_bf16_f32 v4, v0, v97
	v_lshl_add_u64 v[0:1], s[34:35], 0, v[2:3]
	global_store_short v[0:1], v4, off
	v_lshlrev_b32_e32 v4, 16, v17
	v_lshlrev_b32_e32 v2, 16, v16
	v_mul_f32_e32 v3, v123, v4
	v_mul_f32_e32 v1, v121, v2
	v_mul_f32_e32 v5, v3, v3
	v_fmac_f32_e32 v5, v1, v1
	v_add_f32_e32 v0, v125, v26
	v_mul_f32_e32 v0, 0xbfb8aa3b, v0
	v_add_f32_dpp v5, v5, v5 quad_perm:[1,0,3,2] row_mask:0xf bank_mask:0xf bound_ctrl:1
	v_exp_f32_e32 v0, v0
	v_add_f32_e32 v7, v119, v10
	v_add_f32_dpp v5, v5, v5 quad_perm:[2,3,0,1] row_mask:0xf bank_mask:0xf bound_ctrl:1
	v_mul_f32_e32 v7, 0xbfb8aa3b, v7
	v_add_f32_e32 v0, 1.0, v0
	v_add_f32_dpp v5, v5, v5 row_half_mirror row_mask:0xf bank_mask:0xf bound_ctrl:1
	v_exp_f32_e32 v7, v7
	v_mov_b32_e32 v40, v48
	v_add_f32_dpp v5, v5, v5 row_mirror row_mask:0xf bank_mask:0xf bound_ctrl:1
	ds_bpermute_b32 v6, v137, v5
	v_mov_b32_e32 v41, v48
	v_mov_b32_e32 v20, v48
	v_mov_b32_e32 v25, v48
	v_mov_b32_e32 v26, v48
	s_waitcnt lgkmcnt(0)
	v_add_f32_e32 v5, v5, v6
	v_max_f32_e32 v5, 0x179abe15, v5
	v_rsq_f32_e32 v5, v5
	v_rcp_f32_e32 v6, v0
	v_add_f32_e32 v0, 1.0, v7
	v_rcp_f32_e32 v7, v0
	v_mul_f32_e32 v9, v3, v5
	v_add_f32_e32 v3, -1.0, v6
	v_mul_f32_e32 v8, v1, v5
	v_lshl_add_u64 v[0:1], v[56:57], 0, v[70:71]
	v_fma_f32 v3, v63, v3, 1.0
	v_mul_f32_e32 v2, v3, v2
	v_lshlrev_b64 v[0:1], 1, v[0:1]
	v_cvt_pk_bf16_f32 v5, v2, v97
	v_lshl_add_u64 v[2:3], s[96:97], 0, v[0:1]
	global_store_short v[2:3], v5, off
	v_add_f32_e32 v2, -1.0, v7
	v_fma_f32 v2, v62, v2, 1.0
	v_mul_f32_e32 v2, v2, v4
	v_cvt_pk_bf16_f32 v10, v2, v97
	v_or_b32_e32 v2, 64, v0
	v_mov_b32_e32 v3, v1
	v_lshl_add_u64 v[4:5], s[96:97], 0, v[2:3]
	global_store_short v[4:5], v10, off
	v_lshl_add_u64 v[4:5], s[30:31], 0, v[0:1]
	v_cvt_pk_bf16_f32 v10, v8, v97
	global_store_short v[4:5], v10, off
	v_lshl_add_u64 v[4:5], s[30:31], 0, v[2:3]
	v_cvt_pk_bf16_f32 v10, v9, v97
	global_store_short v[4:5], v10, off
	v_mul_f32_e32 v4, v6, v8
	v_lshl_add_u64 v[0:1], s[34:35], 0, v[0:1]
	v_cvt_pk_bf16_f32 v4, v4, v97
	global_store_short v[0:1], v4, off
	v_mul_f32_e32 v0, v7, v9
	v_cvt_pk_bf16_f32 v4, v0, v97
	v_lshl_add_u64 v[0:1], s[34:35], 0, v[2:3]
	global_store_short v[0:1], v4, off
	v_lshlrev_b32_e32 v4, 16, v19
	v_lshlrev_b32_e32 v2, 16, v18
	v_mul_f32_e32 v3, v123, v4
	v_mul_f32_e32 v1, v121, v2
	v_mul_f32_e32 v5, v3, v3
	v_fmac_f32_e32 v5, v1, v1
	v_add_f32_e32 v0, v125, v27
	v_mul_f32_e32 v0, 0xbfb8aa3b, v0
	v_add_f32_dpp v5, v5, v5 quad_perm:[1,0,3,2] row_mask:0xf bank_mask:0xf bound_ctrl:1
	v_exp_f32_e32 v0, v0
	v_add_f32_e32 v7, v119, v11
	v_add_f32_dpp v5, v5, v5 quad_perm:[2,3,0,1] row_mask:0xf bank_mask:0xf bound_ctrl:1
	v_mul_f32_e32 v7, 0xbfb8aa3b, v7
	v_add_f32_e32 v0, 1.0, v0
	v_add_f32_dpp v5, v5, v5 row_half_mirror row_mask:0xf bank_mask:0xf bound_ctrl:1
	v_exp_f32_e32 v7, v7
	v_mov_b32_e32 v56, v48
	v_add_f32_dpp v5, v5, v5 row_mirror row_mask:0xf bank_mask:0xf bound_ctrl:1
	ds_bpermute_b32 v6, v137, v5
	v_mov_b32_e32 v57, v48
	v_mov_b32_e32 v27, v48
	s_waitcnt lgkmcnt(0)
	v_add_f32_e32 v5, v5, v6
	v_max_f32_e32 v5, 0x179abe15, v5
	v_rsq_f32_e32 v5, v5
	v_rcp_f32_e32 v6, v0
	v_add_f32_e32 v0, 1.0, v7
	v_rcp_f32_e32 v7, v0
	v_mul_f32_e32 v9, v3, v5
	v_add_f32_e32 v3, -1.0, v6
	v_mul_f32_e32 v8, v1, v5
	v_lshl_add_u64 v[0:1], v[42:43], 0, v[70:71]
	v_fma_f32 v3, v63, v3, 1.0
	v_mul_f32_e32 v2, v3, v2
	v_lshlrev_b64 v[0:1], 1, v[0:1]
	v_cvt_pk_bf16_f32 v5, v2, v97
	v_lshl_add_u64 v[2:3], s[96:97], 0, v[0:1]
	global_store_short v[2:3], v5, off
	v_add_f32_e32 v2, -1.0, v7
	v_fma_f32 v2, v62, v2, 1.0
	v_mul_f32_e32 v2, v2, v4
	v_cvt_pk_bf16_f32 v10, v2, v97
	v_or_b32_e32 v2, 64, v0
	v_mov_b32_e32 v3, v1
	v_lshl_add_u64 v[4:5], s[96:97], 0, v[2:3]
	global_store_short v[4:5], v10, off
	v_lshl_add_u64 v[4:5], s[30:31], 0, v[0:1]
	v_cvt_pk_bf16_f32 v10, v8, v97
	global_store_short v[4:5], v10, off
	v_lshl_add_u64 v[4:5], s[30:31], 0, v[2:3]
	v_cvt_pk_bf16_f32 v10, v9, v97
	global_store_short v[4:5], v10, off
	v_mul_f32_e32 v4, v6, v8
	v_lshl_add_u64 v[0:1], s[34:35], 0, v[0:1]
	v_cvt_pk_bf16_f32 v4, v4, v97
	global_store_short v[0:1], v4, off
	v_mul_f32_e32 v0, v7, v9
	v_cvt_pk_bf16_f32 v4, v0, v97
	v_lshl_add_u64 v[0:1], s[34:35], 0, v[2:3]
	global_store_short v[0:1], v4, off
	ds_read_u16 v0, v195 offset:41088
	ds_read_u16 v1, v195 offset:41152
	ds_read_u16 v6, v197 offset:41088
	ds_read_u16 v7, v197 offset:41152
	ds_read_u16 v8, v199 offset:41088
	ds_read_u16 v9, v199 offset:41152
	ds_read_u16 v10, v201 offset:41088
	ds_read_u16 v11, v201 offset:41152
	s_waitcnt lgkmcnt(6)
; __device__ __forceinline__ float bf1(bf16 h) { return __uint_as_float((unsigned)h << 16); }
; __device__ __forceinline__ bf16 f2bf(float f) { return (bf16)(pg8::cvt_pk_bf16(f, 0.f) & 0xffffu); }
; __device__ __forceinline__ float half32_sum(float v) { v = row16_sum(v); v += __shfl_xor(v, 16); return v; }
; __device__ __forceinline__ float sigmoid1(float x) { return __builtin_amdgcn_rcpf(1.0f + __expf(-x)); }
; #define RW_ZERO() do { _Pragma("unroll") for (int b_ = 0; b_ < 4; ++b_) _Pragma("unroll") for (int r_ = 0; r_ < 16; ++r_) acc[b_][r_] = 0.f; } while (0)
; __global__ void __launch_bounds__(NT, 2) mk_fwd(Args args) {
;     ...
;                     for (int hh = 0; hh < 2; ++hh) {
;                         const int colA = c0 + hh * 64 + (lane & 31), colB = colA + 32;
;                         const float a0A = a0p[colA], a0B = a0p[colB], kkA = kkw[colA], kkB = kkw[colB], kaA = kaw[colA], kaB = kaw[colB];
; #pragma unroll
;                         for (int r = 0; r < 16; ++r) { const int tl = (r & 3) + 8 * (r >> 2) + 4 * (lane >> 5); const int t = t0 + mt * 32 + tl;
;                             const float kA = bf1(Ks[tl * 1032 + colA]), kB = bf1(Ks[tl * 1032 + colB]);
;                             const float aA = sigmoid1(a0A + acc[hh * 2][r]), aB = sigmoid1(a0B + acc[hh * 2 + 1][r]);
;                             const float qA = kA * kkA, qB = kB * kkB;
;                             const float ss = half32_sum(qA * qA + qB * qB);
;                             const float inv = __builtin_amdgcn_rsqf(fmaxf(ss, 1e-24f));
;                             const float nA = qA * inv, nB = qB * inv;
;                             const size_t oA = (size_t)t * 1024 + colA, oB = oA + 32;
;                             KP[oA] = f2bf(kA * (1.0f + (aA - 1.0f) * kaA)); KP[oB] = f2bf(kB * (1.0f + (aB - 1.0f) * kaB));
;                             KKn[oA] = f2bf(nA); KKn[oB] = f2bf(nB); BB[oA] = f2bf(nA * aA); BB[oB] = f2bf(nB * aB);
;                             if ((r & 3) == 3) asm volatile("" ::: "memory"); }
;                     }
;                     RW_ZERO(); RW_MM(G2T, 160, 128, 10);
	v_lshlrev_b32_e32 v4, 16, v1
	v_lshlrev_b32_e32 v2, 16, v0
	v_mul_f32_e32 v3, v123, v4
	v_mul_f32_e32 v1, v121, v2
	v_mul_f32_e32 v5, v3, v3
	v_fmac_f32_e32 v5, v1, v1
	v_add_f32_e32 v0, v125, v28
	v_mul_f32_e32 v0, 0xbfb8aa3b, v0
	v_add_f32_dpp v5, v5, v5 quad_perm:[1,0,3,2] row_mask:0xf bank_mask:0xf bound_ctrl:1
	v_exp_f32_e32 v0, v0
	v_mov_b32_e32 v42, v48
	v_add_f32_dpp v5, v5, v5 quad_perm:[2,3,0,1] row_mask:0xf bank_mask:0xf bound_ctrl:1
	v_mov_b32_e32 v43, v48
	v_add_f32_e32 v0, 1.0, v0
	v_add_f32_dpp v5, v5, v5 row_half_mirror row_mask:0xf bank_mask:0xf bound_ctrl:1
	v_mov_b32_e32 v28, v48
	s_nop 0
	v_add_f32_dpp v5, v5, v5 row_mirror row_mask:0xf bank_mask:0xf bound_ctrl:1
	ds_bpermute_b32 v16, v137, v5
	s_waitcnt lgkmcnt(0)
	v_add_f32_e32 v5, v5, v16
	v_max_f32_e32 v5, 0x179abe15, v5
	v_rsq_f32_e32 v5, v5
	v_rcp_f32_e32 v16, v0
	v_add_f32_e32 v0, 1.0, v12
	v_rcp_f32_e32 v12, v0
	v_mul_f32_e32 v18, v3, v5
	v_add_f32_e32 v3, -1.0, v16
	v_mul_f32_e32 v17, v1, v5
	v_lshl_add_u64 v[0:1], v[58:59], 0, v[70:71]
	v_fma_f32 v3, v63, v3, 1.0
	v_mul_f32_e32 v2, v3, v2
	v_lshlrev_b64 v[0:1], 1, v[0:1]
	v_cvt_pk_bf16_f32 v5, v2, v97
	v_lshl_add_u64 v[2:3], s[96:97], 0, v[0:1]
	global_store_short v[2:3], v5, off
	v_add_f32_e32 v2, -1.0, v12
	v_fma_f32 v2, v62, v2, 1.0
	v_mul_f32_e32 v2, v2, v4
	v_cvt_pk_bf16_f32 v19, v2, v97
	v_or_b32_e32 v2, 64, v0
	v_mov_b32_e32 v3, v1
	v_lshl_add_u64 v[4:5], s[96:97], 0, v[2:3]
	global_store_short v[4:5], v19, off
	v_lshl_add_u64 v[4:5], s[30:31], 0, v[0:1]
	v_cvt_pk_bf16_f32 v19, v17, v97
	global_store_short v[4:5], v19, off
	v_lshl_add_u64 v[4:5], s[30:31], 0, v[2:3]
	v_cvt_pk_bf16_f32 v19, v18, v97
	global_store_short v[4:5], v19, off
	v_mul_f32_e32 v4, v16, v17
	v_lshl_add_u64 v[0:1], s[34:35], 0, v[0:1]
	v_cvt_pk_bf16_f32 v4, v4, v97
	global_store_short v[0:1], v4, off
	v_mul_f32_e32 v0, v12, v18
	v_cvt_pk_bf16_f32 v4, v0, v97
	v_lshl_add_u64 v[0:1], s[34:35], 0, v[2:3]
	global_store_short v[0:1], v4, off
	v_lshlrev_b32_e32 v4, 16, v7
	v_lshlrev_b32_e32 v2, 16, v6
	v_mul_f32_e32 v3, v123, v4
	v_mul_f32_e32 v1, v121, v2
	v_mul_f32_e32 v5, v3, v3
	v_fmac_f32_e32 v5, v1, v1
	v_add_f32_e32 v0, v125, v29
	v_mul_f32_e32 v0, 0xbfb8aa3b, v0
	v_add_f32_dpp v5, v5, v5 quad_perm:[1,0,3,2] row_mask:0xf bank_mask:0xf bound_ctrl:1
	v_exp_f32_e32 v0, v0
	v_add_f32_e32 v7, v119, v13
	v_add_f32_dpp v5, v5, v5 quad_perm:[2,3,0,1] row_mask:0xf bank_mask:0xf bound_ctrl:1
	v_mul_f32_e32 v7, 0xbfb8aa3b, v7
	v_add_f32_e32 v0, 1.0, v0
	v_add_f32_dpp v5, v5, v5 row_half_mirror row_mask:0xf bank_mask:0xf bound_ctrl:1
	v_exp_f32_e32 v7, v7
	v_mov_b32_e32 v58, v48
	v_add_f32_dpp v5, v5, v5 row_mirror row_mask:0xf bank_mask:0xf bound_ctrl:1
	ds_bpermute_b32 v6, v137, v5
	v_mov_b32_e32 v59, v48
	v_mov_b32_e32 v17, v48
	v_mov_b32_e32 v18, v48
	v_mov_b32_e32 v19, v48
	s_waitcnt lgkmcnt(0)
	v_add_f32_e32 v5, v5, v6
	v_max_f32_e32 v5, 0x179abe15, v5
	v_rsq_f32_e32 v5, v5
	v_rcp_f32_e32 v6, v0
	v_add_f32_e32 v0, 1.0, v7
	v_rcp_f32_e32 v7, v0
	v_mul_f32_e32 v13, v3, v5
	v_add_f32_e32 v3, -1.0, v6
	v_mul_f32_e32 v12, v1, v5
	v_lshl_add_u64 v[0:1], v[44:45], 0, v[70:71]
	v_fma_f32 v3, v63, v3, 1.0
	v_mul_f32_e32 v2, v3, v2
	v_lshlrev_b64 v[0:1], 1, v[0:1]
	v_cvt_pk_bf16_f32 v5, v2, v97
	v_lshl_add_u64 v[2:3], s[96:97], 0, v[0:1]
	global_store_short v[2:3], v5, off
	v_add_f32_e32 v2, -1.0, v7
	v_fma_f32 v2, v62, v2, 1.0
	v_mul_f32_e32 v2, v2, v4
	v_cvt_pk_bf16_f32 v16, v2, v97
	v_or_b32_e32 v2, 64, v0
	v_mov_b32_e32 v3, v1
	v_lshl_add_u64 v[4:5], s[96:97], 0, v[2:3]
	global_store_short v[4:5], v16, off
	v_lshl_add_u64 v[4:5], s[30:31], 0, v[0:1]
	v_cvt_pk_bf16_f32 v16, v12, v97
	global_store_short v[4:5], v16, off
	v_lshl_add_u64 v[4:5], s[30:31], 0, v[2:3]
	v_cvt_pk_bf16_f32 v16, v13, v97
	global_store_short v[4:5], v16, off
	v_mul_f32_e32 v4, v6, v12
	v_lshl_add_u64 v[0:1], s[34:35], 0, v[0:1]
	v_cvt_pk_bf16_f32 v4, v4, v97
	global_store_short v[0:1], v4, off
	v_mul_f32_e32 v0, v7, v13
	v_cvt_pk_bf16_f32 v4, v0, v97
	v_lshl_add_u64 v[0:1], s[34:35], 0, v[2:3]
	global_store_short v[0:1], v4, off
	v_lshlrev_b32_e32 v4, 16, v9
	v_lshlrev_b32_e32 v2, 16, v8
	v_mul_f32_e32 v3, v123, v4
	v_mul_f32_e32 v1, v121, v2
	v_mul_f32_e32 v5, v3, v3
	v_fmac_f32_e32 v5, v1, v1
	v_add_f32_e32 v0, v125, v30
	v_mul_f32_e32 v0, 0xbfb8aa3b, v0
	v_add_f32_dpp v5, v5, v5 quad_perm:[1,0,3,2] row_mask:0xf bank_mask:0xf bound_ctrl:1
	v_exp_f32_e32 v0, v0
	v_add_f32_e32 v7, v119, v14
	v_add_f32_dpp v5, v5, v5 quad_perm:[2,3,0,1] row_mask:0xf bank_mask:0xf bound_ctrl:1
	v_mul_f32_e32 v7, 0xbfb8aa3b, v7
	v_add_f32_e32 v0, 1.0, v0
	v_add_f32_dpp v5, v5, v5 row_half_mirror row_mask:0xf bank_mask:0xf bound_ctrl:1
	v_exp_f32_e32 v7, v7
	v_mov_b32_e32 v44, v48
	v_add_f32_dpp v5, v5, v5 row_mirror row_mask:0xf bank_mask:0xf bound_ctrl:1
	ds_bpermute_b32 v6, v137, v5
	v_mov_b32_e32 v45, v48
	v_mov_b32_e32 v16, v48
	v_mov_b32_e32 v29, v48
	v_mov_b32_e32 v30, v48
	s_waitcnt lgkmcnt(0)
; __device__ __forceinline__ float bf1(bf16 h) { return __uint_as_float((unsigned)h << 16); }
; __device__ __forceinline__ bf16 f2bf(float f) { return (bf16)(pg8::cvt_pk_bf16(f, 0.f) & 0xffffu); }
; __device__ __forceinline__ float half32_sum(float v) { v = row16_sum(v); v += __shfl_xor(v, 16); return v; }
; __device__ __forceinline__ float sigmoid1(float x) { return __builtin_amdgcn_rcpf(1.0f + __expf(-x)); }
; #define RW_ZERO() do { _Pragma("unroll") for (int b_ = 0; b_ < 4; ++b_) _Pragma("unroll") for (int r_ = 0; r_ < 16; ++r_) acc[b_][r_] = 0.f; } while (0)
; __global__ void __launch_bounds__(NT, 2) mk_fwd(Args args) {
;     ...
;                     for (int hh = 0; hh < 2; ++hh) {
;                         const int colA = c0 + hh * 64 + (lane & 31), colB = colA + 32;
;                         const float a0A = a0p[colA], a0B = a0p[colB], kkA = kkw[colA], kkB = kkw[colB], kaA = kaw[colA], kaB = kaw[colB];
; #pragma unroll
;                         for (int r = 0; r < 16; ++r) { const int tl = (r & 3) + 8 * (r >> 2) + 4 * (lane >> 5); const int t = t0 + mt * 32 + tl;
;                             const float kA = bf1(Ks[tl * 1032 + colA]), kB = bf1(Ks[tl * 1032 + colB]);
;                             const float aA = sigmoid1(a0A + acc[hh * 2][r]), aB = sigmoid1(a0B + acc[hh * 2 + 1][r]);
;                             const float qA = kA * kkA, qB = kB * kkB;
;                             const float ss = half32_sum(qA * qA + qB * qB);
;                             const float inv = __builtin_amdgcn_rsqf(fmaxf(ss, 1e-24f));
;                             const float nA = qA * inv, nB = qB * inv;
;                             const size_t oA = (size_t)t * 1024 + colA, oB = oA + 32;
;                             KP[oA] = f2bf(kA * (1.0f + (aA - 1.0f) * kaA)); KP[oB] = f2bf(kB * (1.0f + (aB - 1.0f) * kaB));
;                             KKn[oA] = f2bf(nA); KKn[oB] = f2bf(nB); BB[oA] = f2bf(nA * aA); BB[oB] = f2bf(nB * aB);
;                             if ((r & 3) == 3) asm volatile("" ::: "memory"); }
;                     }
;                     RW_ZERO(); RW_MM(G2T, 160, 128, 10);
	v_add_f32_e32 v5, v5, v6
	v_max_f32_e32 v5, 0x179abe15, v5
	v_rsq_f32_e32 v5, v5
	v_rcp_f32_e32 v6, v0
	v_add_f32_e32 v0, 1.0, v7
	v_rcp_f32_e32 v7, v0
	v_mul_f32_e32 v9, v3, v5
	v_add_f32_e32 v3, -1.0, v6
	v_mul_f32_e32 v8, v1, v5
	v_lshl_add_u64 v[0:1], v[60:61], 0, v[70:71]
	v_fma_f32 v3, v63, v3, 1.0
	v_mul_f32_e32 v2, v3, v2
	v_lshlrev_b64 v[0:1], 1, v[0:1]
	v_cvt_pk_bf16_f32 v5, v2, v97
	v_lshl_add_u64 v[2:3], s[96:97], 0, v[0:1]
	global_store_short v[2:3], v5, off
	v_add_f32_e32 v2, -1.0, v7
	v_fma_f32 v2, v62, v2, 1.0
	v_mul_f32_e32 v2, v2, v4
	v_cvt_pk_bf16_f32 v12, v2, v97
	v_or_b32_e32 v2, 64, v0
	v_mov_b32_e32 v3, v1
	v_lshl_add_u64 v[4:5], s[96:97], 0, v[2:3]
	global_store_short v[4:5], v12, off
	v_lshl_add_u64 v[4:5], s[30:31], 0, v[0:1]
	v_cvt_pk_bf16_f32 v12, v8, v97
	global_store_short v[4:5], v12, off
	v_lshl_add_u64 v[4:5], s[30:31], 0, v[2:3]
	v_cvt_pk_bf16_f32 v12, v9, v97
	global_store_short v[4:5], v12, off
	v_mul_f32_e32 v4, v6, v8
	v_lshl_add_u64 v[0:1], s[34:35], 0, v[0:1]
	v_cvt_pk_bf16_f32 v4, v4, v97
	global_store_short v[0:1], v4, off
	v_mul_f32_e32 v0, v7, v9
	v_cvt_pk_bf16_f32 v4, v0, v97
	v_lshl_add_u64 v[0:1], s[34:35], 0, v[2:3]
	global_store_short v[0:1], v4, off
	v_lshlrev_b32_e32 v4, 16, v11
	v_lshlrev_b32_e32 v2, 16, v10
	v_mul_f32_e32 v3, v123, v4
	v_mul_f32_e32 v1, v121, v2
	v_mul_f32_e32 v5, v3, v3
	v_fmac_f32_e32 v5, v1, v1
	v_add_f32_e32 v0, v125, v31
	v_mul_f32_e32 v0, 0xbfb8aa3b, v0
	v_add_f32_dpp v5, v5, v5 quad_perm:[1,0,3,2] row_mask:0xf bank_mask:0xf bound_ctrl:1
	v_exp_f32_e32 v0, v0
	v_add_f32_e32 v7, v119, v15
	v_add_f32_dpp v5, v5, v5 quad_perm:[2,3,0,1] row_mask:0xf bank_mask:0xf bound_ctrl:1
	v_mul_f32_e32 v7, 0xbfb8aa3b, v7
	v_add_f32_e32 v0, 1.0, v0
	v_add_f32_dpp v5, v5, v5 row_half_mirror row_mask:0xf bank_mask:0xf bound_ctrl:1
	v_exp_f32_e32 v7, v7
	v_add_u32_e32 v119, v207, v210
	v_add_f32_dpp v5, v5, v5 row_mirror row_mask:0xf bank_mask:0xf bound_ctrl:1
	ds_bpermute_b32 v6, v137, v5
	v_mov_b32_e32 v60, v48
	v_mov_b32_e32 v61, v48
	v_mov_b32_e32 v31, v48
	v_mov_b32_e32 v11, v48
	s_waitcnt lgkmcnt(0)
	v_add_f32_e32 v5, v5, v6
	v_max_f32_e32 v5, 0x179abe15, v5
	v_rsq_f32_e32 v5, v5
	v_rcp_f32_e32 v6, v0
	v_add_f32_e32 v0, 1.0, v7
	v_rcp_f32_e32 v7, v0
	v_mul_f32_e32 v9, v3, v5
	v_add_f32_e32 v3, -1.0, v6
	v_mul_f32_e32 v8, v1, v5
	v_lshl_add_u64 v[0:1], v[46:47], 0, v[70:71]
	v_fma_f32 v3, v63, v3, 1.0
	v_mul_f32_e32 v2, v3, v2
	v_lshlrev_b64 v[0:1], 1, v[0:1]
	v_cvt_pk_bf16_f32 v5, v2, v97
	v_lshl_add_u64 v[2:3], s[96:97], 0, v[0:1]
	global_store_short v[2:3], v5, off
	v_add_f32_e32 v2, -1.0, v7
	v_fma_f32 v2, v62, v2, 1.0
	v_mul_f32_e32 v2, v2, v4
	v_cvt_pk_bf16_f32 v10, v2, v97
	v_or_b32_e32 v2, 64, v0
	v_mov_b32_e32 v3, v1
	v_lshl_add_u64 v[4:5], s[96:97], 0, v[2:3]
	global_store_short v[4:5], v10, off
	v_lshl_add_u64 v[4:5], s[30:31], 0, v[0:1]
	v_cvt_pk_bf16_f32 v10, v8, v97
	global_store_short v[4:5], v10, off
	v_lshl_add_u64 v[4:5], s[30:31], 0, v[2:3]
	v_cvt_pk_bf16_f32 v10, v9, v97
	global_store_short v[4:5], v10, off
	v_mul_f32_e32 v4, v6, v8
	v_lshl_add_u64 v[0:1], s[34:35], 0, v[0:1]
	v_cvt_pk_bf16_f32 v4, v4, v97
	global_store_short v[0:1], v4, off
	v_mul_f32_e32 v0, v7, v9
	v_cvt_pk_bf16_f32 v4, v0, v97
	v_lshl_add_u64 v[0:1], s[34:35], 0, v[2:3]
	global_store_short v[0:1], v4, off
	v_mov_b32_e32 v62, v48
	v_mov_b32_e32 v63, v48
	v_mov_b32_e32 v46, v48
	v_mov_b32_e32 v47, v48
	v_mov_b32_e32 v0, v48
	v_mov_b32_e32 v1, v48
	v_mov_b32_e32 v2, v48
	v_mov_b32_e32 v3, v48
	v_mov_b32_e32 v4, v48
	v_mov_b32_e32 v5, v48
	v_mov_b32_e32 v6, v48
	v_mov_b32_e32 v7, v48
	v_mov_b32_e32 v8, v48
	v_mov_b32_e32 v9, v48
	v_mov_b32_e32 v10, v48
	v_mov_b32_e32 v12, v48
	v_mov_b32_e32 v13, v48
	v_mov_b32_e32 v14, v48
	v_mov_b32_e32 v15, v48
.LBB0_370:
	v_lshl_add_u64 v[160:161], v[114:115], 0, s[8:9]
	v_add_co_u32_e32 v218, vcc, s66, v160
	v_lshl_add_u64 v[162:163], v[112:113], 0, s[8:9]
	s_nop 0
	v_addc_co_u32_e32 v219, vcc, 0, v161, vcc
	v_add_co_u32_e32 v222, vcc, s66, v162
	v_lshl_add_u64 v[164:165], v[110:111], 0, s[8:9]
	s_nop 0
	v_addc_co_u32_e32 v223, vcc, 0, v163, vcc
	v_add_co_u32_e32 v224, vcc, s66, v164
	v_lshl_add_u64 v[166:167], v[108:109], 0, s[8:9]
	s_nop 0
	v_addc_co_u32_e32 v225, vcc, 0, v165, vcc
	v_add_co_u32_e32 v226, vcc, s66, v166
	ds_read_b128 v[152:155], v119
	ds_read_b128 v[156:159], v119 offset:32
	v_addc_co_u32_e32 v227, vcc, 0, v167, vcc
	global_load_dwordx4 v[160:163], v[218:219], off
	global_load_dwordx4 v[164:167], v[222:223], off
	global_load_dwordx4 v[210:213], v[224:225], off
	global_load_dwordx4 v[214:217], v[226:227], off
	s_nop 0
	global_load_dwordx4 v[218:221], v[218:219], off offset:1024
	s_add_u32 s8, s8, 0x800
	s_addc_u32 s9, s9, 0
	s_cmpk_eq_i32 s8, 0x2800
	v_add_u32_e32 v119, 64, v119
	s_waitcnt vmcnt(4) lgkmcnt(1)
	v_mfma_f32_32x32x16_bf16 v[48:63], v[152:155], v[160:163], v[48:63]
	global_load_dwordx4 v[160:163], v[222:223], off offset:1024
	s_waitcnt vmcnt(4)
	v_mfma_f32_32x32x16_bf16 v[32:47], v[152:155], v[164:167], v[32:47]
	global_load_dwordx4 v[164:167], v[224:225], off offset:1024
	s_waitcnt vmcnt(4)
	v_mfma_f32_32x32x16_bf16 v[16:31], v[152:155], v[210:213], v[16:31]
	global_load_dwordx4 v[210:213], v[226:227], off offset:1024
	s_waitcnt vmcnt(4)
	v_mfma_f32_32x32x16_bf16 v[0:15], v[152:155], v[214:217], v[0:15]
	s_waitcnt vmcnt(3) lgkmcnt(0)
	v_mfma_f32_32x32x16_bf16 v[48:63], v[156:159], v[218:221], v[48:63]
	s_waitcnt vmcnt(2)
	v_mfma_f32_32x32x16_bf16 v[32:47], v[156:159], v[160:163], v[32:47]
	s_waitcnt vmcnt(1)
	v_mfma_f32_32x32x16_bf16 v[16:31], v[156:159], v[164:167], v[16:31]
	s_waitcnt vmcnt(0)
	v_mfma_f32_32x32x16_bf16 v[0:15], v[156:159], v[210:213], v[0:15]
	s_cbranch_scc0 .LBB0_370
; __device__ __forceinline__ bf16 f2bf(float f) { return (bf16)(pg8::cvt_pk_bf16(f, 0.f) & 0xffffu); }
; __global__ void __launch_bounds__(NT, 2) mk_fwd(Args args) {
;     ...
; #pragma unroll
;                     for (int nt = 0; nt < 4; ++nt) { const int col = c0 + nt * 32 + (lane & 31);
; #pragma unroll
;                         for (int r = 0; r < 16; ++r) { const int t = t0 + mt * 32 + (r & 3) + 8 * (r >> 2) + 4 * (lane >> 5);
;                             GG[(size_t)t * 1024 + col] = f2bf(acc[nt][r]); }
;                         asm volatile("" ::: "memory"); }
	v_lshlrev_b32_e32 v96, 1, v96
	v_cvt_pk_bf16_f32 v48, v48, v97
	v_lshl_add_u64 v[152:153], v[66:67], 0, v[96:97]
	s_nop 2
	global_store_short v[152:153], v48, off
	v_cvt_pk_bf16_f32 v48, v49, v97
	global_store_short v[152:153], v48, off offset:2048
	v_lshlrev_b32_e32 v48, 1, v116
	v_mov_b32_e32 v49, v97
	v_cvt_pk_bf16_f32 v50, v50, v97
	v_lshl_add_u64 v[152:153], v[66:67], 0, v[48:49]
	global_store_short v[152:153], v50, off
	v_cvt_pk_bf16_f32 v116, v51, v97
	v_lshlrev_b32_e32 v50, 1, v118
	v_mov_b32_e32 v51, v97
	v_lshl_add_u64 v[118:119], v[66:67], 0, v[50:51]
	global_store_short v[118:119], v116, off
	v_lshlrev_b32_e32 v118, 1, v120
	v_mov_b32_e32 v119, v97
	v_cvt_pk_bf16_f32 v52, v52, v97
	v_lshl_add_u64 v[120:121], v[66:67], 0, v[118:119]
	global_store_short v[120:121], v52, off
	v_cvt_pk_bf16_f32 v116, v53, v97
	v_lshlrev_b32_e32 v52, 1, v122
	v_mov_b32_e32 v53, v97
	v_lshl_add_u64 v[120:121], v[66:67], 0, v[52:53]
	global_store_short v[120:121], v116, off
	v_lshlrev_b32_e32 v120, 1, v124
	v_mov_b32_e32 v121, v97
	v_cvt_pk_bf16_f32 v54, v54, v97
	v_lshl_add_u64 v[122:123], v[66:67], 0, v[120:121]
	global_store_short v[122:123], v54, off
	v_cvt_pk_bf16_f32 v116, v55, v97
	v_lshlrev_b32_e32 v54, 1, v126
	v_mov_b32_e32 v55, v97
	v_lshl_add_u64 v[122:123], v[66:67], 0, v[54:55]
	global_store_short v[122:123], v116, off
	v_lshlrev_b32_e32 v122, 1, v136
	v_mov_b32_e32 v123, v97
	v_cvt_pk_bf16_f32 v56, v56, v97
	v_lshl_add_u64 v[124:125], v[66:67], 0, v[122:123]
	global_store_short v[124:125], v56, off
	v_cvt_pk_bf16_f32 v116, v57, v97
	v_lshlrev_b32_e32 v56, 1, v138
	v_mov_b32_e32 v57, v97
	v_lshl_add_u64 v[124:125], v[66:67], 0, v[56:57]
	global_store_short v[124:125], v116, off
	v_lshlrev_b32_e32 v124, 1, v140
	v_mov_b32_e32 v125, v97
	v_cvt_pk_bf16_f32 v58, v58, v97
	v_lshl_add_u64 v[126:127], v[66:67], 0, v[124:125]
	global_store_short v[126:127], v58, off
	v_cvt_pk_bf16_f32 v116, v59, v97
	v_lshlrev_b32_e32 v58, 1, v142
	v_mov_b32_e32 v59, v97
	v_lshl_add_u64 v[126:127], v[66:67], 0, v[58:59]
	global_store_short v[126:127], v116, off
	v_lshlrev_b32_e32 v126, 1, v144
	v_mov_b32_e32 v127, v97
	v_cvt_pk_bf16_f32 v60, v60, v97
	v_lshl_add_u64 v[138:139], v[66:67], 0, v[126:127]
	global_store_short v[138:139], v60, off
	v_cvt_pk_bf16_f32 v116, v61, v97
	v_lshlrev_b32_e32 v60, 1, v146
	v_mov_b32_e32 v61, v97
	v_lshl_add_u64 v[138:139], v[66:67], 0, v[60:61]
	global_store_short v[138:139], v116, off
	v_lshlrev_b32_e32 v138, 1, v148
	v_mov_b32_e32 v139, v97
	v_cvt_pk_bf16_f32 v62, v62, v97
	v_lshl_add_u64 v[140:141], v[66:67], 0, v[138:139]
	global_store_short v[140:141], v62, off
	v_cvt_pk_bf16_f32 v116, v63, v97
	v_lshlrev_b32_e32 v62, 1, v150
	v_mov_b32_e32 v63, v97
	v_lshl_add_u64 v[140:141], v[66:67], 0, v[62:63]
	global_store_short v[140:141], v116, off
	v_lshl_add_u64 v[140:141], s[26:27], 0, v[96:97]
	v_cvt_pk_bf16_f32 v32, v32, v97
	v_lshl_add_u64 v[142:143], v[68:69], 1, v[140:141]
	global_store_short v[142:143], v32, off
	v_cvt_pk_bf16_f32 v116, v33, v97
	v_lshl_add_u64 v[32:33], v[90:91], 0, v[96:97]
	global_store_short v[32:33], v116, off offset:2048
	v_lshl_add_u64 v[32:33], v[90:91], 0, v[48:49]
	v_cvt_pk_bf16_f32 v34, v34, v97
	global_store_short v[32:33], v34, off
	v_lshl_add_u64 v[32:33], v[90:91], 0, v[50:51]
	v_cvt_pk_bf16_f32 v34, v35, v97
	global_store_short v[32:33], v34, off
	v_lshl_add_u64 v[32:33], v[90:91], 0, v[118:119]
	v_cvt_pk_bf16_f32 v34, v36, v97
	global_store_short v[32:33], v34, off
	v_lshl_add_u64 v[32:33], v[90:91], 0, v[52:53]
	v_cvt_pk_bf16_f32 v34, v37, v97
	global_store_short v[32:33], v34, off
	v_lshl_add_u64 v[32:33], v[90:91], 0, v[120:121]
	v_cvt_pk_bf16_f32 v34, v38, v97
	global_store_short v[32:33], v34, off
	v_lshl_add_u64 v[32:33], v[90:91], 0, v[54:55]
	v_cvt_pk_bf16_f32 v34, v39, v97
	global_store_short v[32:33], v34, off
	v_lshl_add_u64 v[32:33], v[90:91], 0, v[122:123]
	v_cvt_pk_bf16_f32 v34, v40, v97
	global_store_short v[32:33], v34, off
	v_lshl_add_u64 v[32:33], v[90:91], 0, v[56:57]
	v_cvt_pk_bf16_f32 v34, v41, v97
	global_store_short v[32:33], v34, off
	v_lshl_add_u64 v[32:33], v[90:91], 0, v[124:125]
	v_cvt_pk_bf16_f32 v34, v42, v97
	global_store_short v[32:33], v34, off
	v_lshl_add_u64 v[32:33], v[90:91], 0, v[58:59]
	v_cvt_pk_bf16_f32 v34, v43, v97
	global_store_short v[32:33], v34, off
	v_lshl_add_u64 v[32:33], v[90:91], 0, v[126:127]
	v_cvt_pk_bf16_f32 v34, v44, v97
	global_store_short v[32:33], v34, off
	v_lshl_add_u64 v[32:33], v[90:91], 0, v[60:61]
	v_cvt_pk_bf16_f32 v34, v45, v97
	global_store_short v[32:33], v34, off
	v_lshl_add_u64 v[32:33], v[90:91], 0, v[138:139]
	v_cvt_pk_bf16_f32 v34, v46, v97
	global_store_short v[32:33], v34, off
	v_lshl_add_u64 v[32:33], v[90:91], 0, v[62:63]
	v_cvt_pk_bf16_f32 v34, v47, v97
	global_store_short v[32:33], v34, off
	v_cvt_pk_bf16_f32 v16, v16, v97
	v_lshl_add_u64 v[32:33], v[70:71], 1, v[140:141]
	global_store_short v[32:33], v16, off
	v_cvt_pk_bf16_f32 v32, v17, v97
	v_lshl_add_u64 v[16:17], v[92:93], 0, v[96:97]
	global_store_short v[16:17], v32, off offset:2048
	v_lshl_add_u64 v[16:17], v[92:93], 0, v[48:49]
	v_cvt_pk_bf16_f32 v18, v18, v97
	global_store_short v[16:17], v18, off
	v_lshl_add_u64 v[16:17], v[92:93], 0, v[50:51]
	v_cvt_pk_bf16_f32 v18, v19, v97
	global_store_short v[16:17], v18, off
	v_lshl_add_u64 v[16:17], v[92:93], 0, v[118:119]
	v_cvt_pk_bf16_f32 v18, v20, v97
	global_store_short v[16:17], v18, off
	v_lshl_add_u64 v[16:17], v[92:93], 0, v[52:53]
	v_cvt_pk_bf16_f32 v18, v21, v97
	global_store_short v[16:17], v18, off
	v_lshl_add_u64 v[16:17], v[92:93], 0, v[120:121]
	v_cvt_pk_bf16_f32 v18, v22, v97
; __device__ __forceinline__ float bf_lo(unsigned u) { return __uint_as_float(u << 16); }
; __device__ __forceinline__ float bf_hi(unsigned u) { return __uint_as_float(u & 0xffff0000u); }
; __global__ void __launch_bounds__(NT, 2) mk_fwd(Args args) {
;     ...
; #pragma unroll
;                     for (int nt = 0; nt < 4; ++nt) { const int col = c0 + nt * 32 + (lane & 31);
; #pragma unroll
;                         for (int r = 0; r < 16; ++r) { const int t = t0 + mt * 32 + (r & 3) + 8 * (r >> 2) + 4 * (lane >> 5);
;                             GG[(size_t)t * 1024 + col] = f2bf(acc[nt][r]); }
;                         asm volatile("" ::: "memory"); }
;                 }
;     ...
;         for (int item_ = bx; item_ < 256 * RMUL(3); item_ += G) {
;             const int item = item_ & 255;
;             __syncthreads();
;             {
;                 const int T0 = (item >> 1) * 128, hg = (item & 1) * 4;
;                 bf16* VnT = (bf16*)lds;
;                 f32x2* st = (f32x2*)(lds + 36864);
;                 const float* vg = args.in[6]; const float* vb = args.in[7]; const float* wsp = args.in[8]; const float* bs = args.in[9];
; #pragma unroll 1
;                 for (int i0 = 0; i0 < 16; i0 += 4) {
;                     u32x4 a[4], b[4];
; #pragma unroll
;                     for (int i = 0; i < 4; ++i) { const bf16* row = P + (size_t)(T0 + wave * 16 + i0 + i) * NINP + 1024; a[i] = *(const u32x4*)(row + lane * 8); b[i] = *(const u32x4*)(row + 512 + lane * 8); }
; #pragma unroll
;                     for (int i = 0; i < 4; ++i) { float s = 0.f, s2 = 0.f;
; #pragma unroll
;                         for (int q = 0; q < 4; ++q) { const float v0 = bf_lo(a[i][q]), v1 = bf_hi(a[i][q]), v2 = bf_lo(b[i][q]), v3 = bf_hi(b[i][q]); s += (v0 + v1) + (v2 + v3); s2 += (v0 * v0 + v1 * v1) + (v2 * v2 + v3 * v3); }
;                         s = wave_sum(s); s2 = wave_sum(s2);
;                         const float mean = s * (1.0f / 1024.0f); const float var = fmaxf(s2 * (1.0f / 1024.0f) - mean * mean, 0.f);
;                         if (lane == 0) st[wave * 16 + i0 + i] = (f32x2){mean, rsqrtf(var + 1e-5f)}; }
;                 }
;                 for (int hh = 0; hh < 4; ++hh) {
;                     const int h = hg + hh;
;                     __syncthreads();
;                     {
;                         const int j = tid >> 2, d0 = (tid & 3) * 32; const f32x2 sj = st[j];
	global_store_short v[16:17], v18, off
	v_lshl_add_u64 v[16:17], v[92:93], 0, v[54:55]
	v_cvt_pk_bf16_f32 v18, v23, v97
	global_store_short v[16:17], v18, off
	v_lshl_add_u64 v[16:17], v[92:93], 0, v[122:123]
	v_cvt_pk_bf16_f32 v18, v24, v97
	global_store_short v[16:17], v18, off
	v_lshl_add_u64 v[16:17], v[92:93], 0, v[56:57]
	v_cvt_pk_bf16_f32 v18, v25, v97
	global_store_short v[16:17], v18, off
	v_lshl_add_u64 v[16:17], v[92:93], 0, v[124:125]
	v_cvt_pk_bf16_f32 v18, v26, v97
	global_store_short v[16:17], v18, off
	v_lshl_add_u64 v[16:17], v[92:93], 0, v[58:59]
	v_cvt_pk_bf16_f32 v18, v27, v97
	global_store_short v[16:17], v18, off
	v_lshl_add_u64 v[16:17], v[92:93], 0, v[126:127]
	v_cvt_pk_bf16_f32 v18, v28, v97
	global_store_short v[16:17], v18, off
	v_lshl_add_u64 v[16:17], v[92:93], 0, v[60:61]
	v_cvt_pk_bf16_f32 v18, v29, v97
	global_store_short v[16:17], v18, off
	v_lshl_add_u64 v[16:17], v[92:93], 0, v[138:139]
	v_cvt_pk_bf16_f32 v18, v30, v97
	global_store_short v[16:17], v18, off
	v_lshl_add_u64 v[16:17], v[92:93], 0, v[62:63]
	v_cvt_pk_bf16_f32 v18, v31, v97
	global_store_short v[16:17], v18, off
	v_cvt_pk_bf16_f32 v0, v0, v97
	v_lshl_add_u64 v[16:17], v[72:73], 1, v[140:141]
	global_store_short v[16:17], v0, off
	v_cvt_pk_bf16_f32 v16, v1, v97
	v_lshl_add_u64 v[0:1], v[94:95], 0, v[96:97]
	global_store_short v[0:1], v16, off offset:2048
	v_lshl_add_u64 v[0:1], v[94:95], 0, v[48:49]
	v_cvt_pk_bf16_f32 v2, v2, v97
	global_store_short v[0:1], v2, off
	v_lshl_add_u64 v[0:1], v[94:95], 0, v[50:51]
	v_cvt_pk_bf16_f32 v2, v3, v97
	global_store_short v[0:1], v2, off
	v_lshl_add_u64 v[0:1], v[94:95], 0, v[118:119]
	v_cvt_pk_bf16_f32 v2, v4, v97
	global_store_short v[0:1], v2, off
	v_lshl_add_u64 v[0:1], v[94:95], 0, v[52:53]
	v_cvt_pk_bf16_f32 v2, v5, v97
	global_store_short v[0:1], v2, off
	v_lshl_add_u64 v[0:1], v[94:95], 0, v[120:121]
	v_cvt_pk_bf16_f32 v2, v6, v97
	global_store_short v[0:1], v2, off
	v_lshl_add_u64 v[0:1], v[94:95], 0, v[54:55]
	v_cvt_pk_bf16_f32 v2, v7, v97
	global_store_short v[0:1], v2, off
	v_lshl_add_u64 v[0:1], v[94:95], 0, v[122:123]
	v_cvt_pk_bf16_f32 v2, v8, v97
	global_store_short v[0:1], v2, off
	v_lshl_add_u64 v[0:1], v[94:95], 0, v[56:57]
	v_cvt_pk_bf16_f32 v2, v9, v97
	global_store_short v[0:1], v2, off
	v_lshl_add_u64 v[0:1], v[94:95], 0, v[124:125]
	v_cvt_pk_bf16_f32 v2, v10, v97
	global_store_short v[0:1], v2, off
	v_lshl_add_u64 v[0:1], v[94:95], 0, v[58:59]
	v_cvt_pk_bf16_f32 v2, v11, v97
	global_store_short v[0:1], v2, off
	v_lshl_add_u64 v[0:1], v[94:95], 0, v[126:127]
	v_cvt_pk_bf16_f32 v2, v12, v97
	global_store_short v[0:1], v2, off
	v_lshl_add_u64 v[0:1], v[94:95], 0, v[60:61]
	v_cvt_pk_bf16_f32 v2, v13, v97
	global_store_short v[0:1], v2, off
	v_lshl_add_u64 v[0:1], v[94:95], 0, v[138:139]
	v_cvt_pk_bf16_f32 v2, v14, v97
	global_store_short v[0:1], v2, off
	v_lshl_add_u64 v[0:1], v[94:95], 0, v[62:63]
	v_cvt_pk_bf16_f32 v2, v15, v97
	global_store_short v[0:1], v2, off
	s_mov_b32 s69, 32
	s_mov_b64 s[8:9], 0
	s_and_b64 vcc, exec, s[0:1]
	s_cbranch_vccz .LBB0_353
	s_add_i32 s67, s67, s84
	s_cmpk_gt_i32 s67, 0xff
	s_cbranch_scc0 .LBB0_302
	v_xor_b32_e32 v0, 32, v208
	s_lshl_b32 s6, s85, 4
	v_cmp_lt_i32_e32 vcc, v0, v117
	s_ashr_i32 s8, s85, 1
	s_cmp_lt_i32 s8, 2
	v_cndmask_b32_e32 v0, v208, v0, vcc
	v_lshlrev_b32_e32 v141, 2, v0
	v_lshlrev_b32_e32 v0, 5, v168
	s_cselect_b32 s9, 4, 8
	s_lshl_b32 s8, s8, 5
	v_lshrrev_b32_e32 v2, 5, v128
	v_and_b32_e32 v145, 0x60, v0
	v_or_b32_e32 v153, s8, v131
	s_ashr_i32 s10, s8, 31
	v_or_b32_e32 v32, s8, v129
	v_lshl_or_b32 v158, v2, 2, s8
	s_lshl_b32 s8, s85, 6
	s_add_i32 s3, s3, 0
	v_mul_u32_u24_e32 v1, 0x88, v145
	v_and_or_b32 v38, s8, 64, v129
	s_add_i32 s3, s3, 0x9000
	s_mul_i32 s8, s85, 0x2c000
	v_lshl_add_u32 v149, v135, 3, 0
	v_mul_i32_i24_e32 v0, -6, v135
	v_mov_b32_e32 v33, s10
	v_mov_b32_e32 v35, 0
	v_lshlrev_b32_e32 v1, 1, v1
	s_mul_hi_i32 s6, s6, 0x2c00
	s_add_u32 s10, s92, s8
	v_and_b32_e32 v34, 32, v128
	v_add3_u32 v159, v149, v0, v1
	v_lshlrev_b32_e32 v0, 1, v135
	v_mov_b32_e32 v131, v35
	s_addc_u32 s11, s93, s6
	v_lshl_add_u64 v[36:37], s[52:53], 0, v[34:35]
	v_add3_u32 v160, 0, v1, v0
	v_lshlrev_b32_e32 v34, 1, v145
	v_lshl_add_u64 v[0:1], s[10:11], 0, v[130:131]
	s_mov_b64 s[10:11], 0xea09000
	v_mul_u32_u24_e32 v3, 0x110, v38
	v_lshl_add_u64 v[42:43], s[20:21], 0, v[34:35]
	v_lshlrev_b32_e32 v34, 1, v38
	v_lshl_add_u64 v[46:47], v[0:1], 0, s[10:11]
	v_lshlrev_b32_e32 v0, 4, v2
	v_readlane_b32 s68, v249, 31
	s_mov_b32 s7, 0
	v_cmp_eq_u32_e64 s[0:1], 0, v128
	v_add_u32_e32 v161, 0x220, v160
	v_add_u32_e32 v162, 0x440, v160
	v_add_u32_e32 v163, 0x660, v160
	v_add_u32_e32 v164, 0x880, v160
	v_add_u32_e32 v165, 0xaa0, v160
	v_add_u32_e32 v166, 0xcc0, v160
	v_add_u32_e32 v167, 0xee0, v160
	v_add_u32_e32 v170, 0x1100, v160
	v_add_u32_e32 v171, 0x1320, v160
	v_add_u32_e32 v172, 0x1540, v160
	v_add_u32_e32 v173, 0x1760, v160
	v_add_u32_e32 v174, 0x1980, v160
	v_add_u32_e32 v175, 0x1ba0, v160
	v_add_u32_e32 v176, 0x1dc0, v160
	v_add_u32_e32 v177, 0x1fe0, v159
	v_add_u32_e32 v178, 0x1fe0, v160
	v_or_b32_e32 v40, 32, v38
	v_or_b32_e32 v179, 1, v158
	v_or_b32_e32 v180, 2, v158
	v_or_b32_e32 v181, 3, v158
	v_or_b32_e32 v182, 8, v158
	v_or_b32_e32 v183, 9, v158
	v_or_b32_e32 v184, 10, v158
	v_or_b32_e32 v185, 11, v158
	v_or_b32_e32 v186, 16, v158
	v_or_b32_e32 v187, 17, v158
	v_or_b32_e32 v188, 18, v158
	v_or_b32_e32 v189, 19, v158
	v_or_b32_e32 v190, 24, v158
	v_or_b32_e32 v191, 25, v158
	v_or_b32_e32 v192, 26, v158
	v_or_b32_e32 v193, 27, v158
	v_lshl_add_u64 v[44:45], s[20:21], 0, v[34:35]
	s_movk_i32 s33, 0x2c00
	s_lshl_b32 s46, s2, 6
	s_lshl_b32 s47, s84, 6
	v_add3_u32 v194, v3, v0, 0
	s_mov_b32 s8, 0x3a800000
	s_mov_b32 s52, 0x800000
	s_mov_b64 s[42:43], 0xb000
	v_mov_b32_e32 v195, 0x160000
	s_mov_b32 s53, s2
	v_readlane_b32 s69, v249, 32

; #define SC_LOAD(tc) do { const size_t o_ = base + (size_t)(tc) * 1024 + q * 4; ld_dec = *(const f32x4*)(DEC + o_); ld_kk = *(const u32x2*)(KKn + o_); ld_bb = *(const u32x2*)(BB + o_); \
;             ld_kp = *(const u32x2*)(KP + o_); ld_rr = *(const u32x2*)(RR + o_); ld_vv = *(const unsigned*)(VV + base + (size_t)(tc) * 1024 + half * 32 + q * 2); } while (0)
; __global__ void __launch_bounds__(NT, 2) mk_fwd(Args args) {
;     ...
;         for (int task_ = bx; task_ < 256 * RMUL(4); task_ += G) {
;             const int tb_ = task_ & 255; const int task = ((tb_ >> 4) << 4) | ((tb_ & 7) << 1) | ((tb_ >> 3) & 1); const int bh = task >> 1, half = task & 1, b = bh >> 4, h = bh & 15;
;             const int stp = tid >> 4, q = tid & 15;
;             const size_t base = ((size_t)b * SEQ + stp) * 1024 + h * 64;
;             f32x4 ld_dec; u32x2 ld_kk, ld_bb, ld_kp, ld_rr; unsigned ld_vv;
;     ...
;             __syncthreads();
;             SC_LOAD(0); SC_STORE();
;             __syncthreads();
;             f32x4 S = (f32x4){0.f, 0.f, 0.f, 0.f};
;             const int row = wave * 4 + (lane >> 4), kl = lane & 15;
.Lp4_task:
	s_and_b32 s3, s48, 0xf0
	s_and_b32 s6, s48, 7
	s_lshl_b32 s6, s6, 1
	s_or_b32 s3, s3, s6
	s_bfe_u32 s6, s48, 0x10003
	s_or_b32 s3, s3, s6
	s_and_b32 s33, s3, 1
	s_lshr_b32 s6, s3, 1
	s_and_b32 s7, s6, 15
	s_lshr_b32 s6, s6, 4
	s_lshl_b32 s6, s6, 21
	s_lshl_b32 s7, s7, 6
	s_or_b32 s6, s6, s7
	s_lshl_b32 s7, s6, 1
	s_lshl_b32 s8, s6, 2
	s_add_u32 s38, s90, s8
	s_addc_u32 s39, s91, 0
	s_add_u32 s40, s30, s7
	s_addc_u32 s41, s31, 0
	s_add_u32 s42, s34, s7
	s_addc_u32 s43, s35, 0
	s_add_u32 s44, s96, s7
	s_addc_u32 s45, s97, 0
	s_add_u32 s46, s28, s7
	s_addc_u32 s47, s29, 0
	s_lshl_b32 s9, s33, 6
	s_add_u32 s9, s9, s7
	s_add_u32 s52, s24, s9
	s_addc_u32 s53, s25, 0
	s_lshl_b32 s9, s33, 7
	s_add_u32 s9, s9, s8
	s_add_u32 s54, s20, s9
	s_addc_u32 s55, s21, 0
	s_waitcnt vmcnt(0) lgkmcnt(0)
	s_barrier
	s_cmp_gt_u32 s85, 3
	s_cbranch_scc1 .Lp4_helper
	v_and_b32_e32 v54, 15, v128
	v_lshrrev_b32_e32 v55, 4, v128
	v_lshl_or_b32 v55, s85, 2, v55
	v_lshlrev_b32_e32 v80, 4, v54
	v_lshlrev_b32_e32 v81, 3, v55
	v_add_u32_e32 v81, 0x5000, v81
	v_mul_u32_u24_e32 v82, 0x90, v55
	v_lshl_add_u32 v82, v54, 3, v82
	v_add_u32_e32 v82, 0xb000, v82
	v_mov_b32_e32 v72, 0
	v_mov_b32_e32 v73, 0
	v_mov_b32_e32 v74, 0
	v_mov_b32_e32 v75, 0
	v_mov_b32_e32 v76, 0
	v_mov_b32_e32 v77, 0
	v_mov_b32_e32 v78, 0
	v_mov_b32_e32 v79, 0
	s_movk_i32 s10, 0x80
	s_barrier
	s_nop 0
	s_nop 0
	s_nop 0
	s_nop 0
